# v22: v9 + P13 conv/staging rewrite + prompt V-image LDS-DMA before softmax + sample softmax all-reduce via DPP/permlane swaps
# speedup vs baseline: 1.0000x; 1.0000x over previous
; DI void attn_sample_item(const Params& p, int item, ldsp lds, int tid_) {
;     ...
;   for (int t = 0; t < 4; ++t) { f32x4 a = {0.f, 0.f, 0.f, 0.f}; const float* pp = (const float*)(p.ws + B_PART) + (size_t)(b * 4 + t) * 1024 + h * 256 + lane * 4;
; #pragma unroll
;     for (int kp = 0; kp < 4; ++kp) a += *(const f32x4*)(pp + (size_t)kp * 512 * 1024);
;     q[t][0] = a[0] * 0.0625f; q[t][1] = a[1] * 0.0625f; q[t][2] = a[2] * 0.0625f; q[t][3] = a[3] * 0.0625f; }
;   const bool b0 = lane & 1, b1 = lane & 2;
;   f32x4 kvA[16], kvB[16];
; #pragma unroll
;   for (int j = 0; j < 16; ++j) kvA[j] = __builtin_nontemporal_load((const f32x4*)(ck + (size_t)(wid * 32 + j) * 1024 + lane * 4));
; #pragma unroll
;   for (int j = 0; j < 16; ++j) kvB[j] = __builtin_nontemporal_load((const f32x4*)(ck + (size_t)(wid * 32 + 16 + j) * 1024 + lane * 4));
.LBB0_1604:
	s_ashr_i32 s4, s40, 2
	s_ashr_i32 s5, s4, 31
	s_lshl_b64 s[4:5], s[4:5], 18
	s_and_b32 s26, s0, 0x300
	v_mov_b32_e32 v222, v212
	s_or_b32 s4, s4, s26
	s_and_b32 s28, s40, -4
	s_lshl_b32 s6, s26, 2
	s_add_u32 s6, s36, s6
	v_and_b32_e32 v223, 63, v222
	s_addc_u32 s7, s37, 0
	v_lshlrev_b32_e32 v144, 4, v223
	s_ashr_i32 s29, s28, 31
	v_lshl_add_u64 v[48:49], s[6:7], 0, v[144:145]
	s_lshl_b64 s[6:7], s[28:29], 12
	v_lshl_add_u64 v[8:9], v[48:49], 0, s[6:7]
	v_add_co_u32_e32 v4, vcc, s3, v8
	s_or_b32 s6, s28, 1
	s_nop 0
	v_addc_co_u32_e32 v5, vcc, 0, v9, vcc
	v_add_co_u32_e32 v10, vcc, s33, v8
	s_ashr_i32 s7, s6, 31
	s_nop 0
	v_addc_co_u32_e32 v11, vcc, 0, v9, vcc
	v_add_co_u32_e32 v12, vcc, s38, v8
	s_lshl_b64 s[6:7], s[6:7], 12
	s_nop 0
	v_addc_co_u32_e32 v13, vcc, 0, v9, vcc
	v_lshl_add_u64 v[24:25], v[48:49], 0, s[6:7]
	v_add_co_u32_e32 v20, vcc, s3, v24
	s_or_b32 s6, s28, 2
	s_nop 0
	v_addc_co_u32_e32 v21, vcc, 0, v25, vcc
	v_add_co_u32_e32 v26, vcc, s33, v24
	s_ashr_i32 s7, s6, 31
	s_nop 0
	v_addc_co_u32_e32 v27, vcc, 0, v25, vcc
	v_add_co_u32_e32 v28, vcc, s38, v24
	s_lshl_b64 s[6:7], s[6:7], 12
	global_load_dwordx4 v[0:3], v[8:9], off
	s_nop 0
	global_load_dwordx4 v[4:7], v[4:5], off
	v_addc_co_u32_e32 v29, vcc, 0, v25, vcc
	v_lshl_add_u64 v[44:45], v[48:49], 0, s[6:7]
	global_load_dwordx4 v[8:11], v[10:11], off
	s_nop 0
	global_load_dwordx4 v[12:15], v[12:13], off
	s_nop 0
	global_load_dwordx4 v[16:19], v[24:25], off
	s_nop 0
	global_load_dwordx4 v[20:23], v[20:21], off
	v_add_co_u32_e32 v36, vcc, s3, v44
	global_load_dwordx4 v[24:27], v[26:27], off
	s_nop 0
	global_load_dwordx4 v[28:31], v[28:29], off
	v_addc_co_u32_e32 v37, vcc, 0, v45, vcc
	v_add_co_u32_e32 v40, vcc, s33, v44
	global_load_dwordx4 v[32:35], v[44:45], off
	s_nop 0
	global_load_dwordx4 v[36:39], v[36:37], off
	v_addc_co_u32_e32 v41, vcc, 0, v45, vcc
	v_add_co_u32_e32 v44, vcc, s38, v44
	global_load_dwordx4 v[40:43], v[40:41], off
	s_nop 0
	v_addc_co_u32_e32 v45, vcc, 0, v45, vcc
	global_load_dwordx4 v[44:47], v[44:45], off
	s_or_b32 s6, s40, 3
	s_ashr_i32 s7, s6, 31
	s_lshl_b64 s[6:7], s[6:7], 12
	s_lshl_b64 s[30:31], s[4:5], 2
	s_add_u32 s4, s12, s30
	s_addc_u32 s5, s13, s31
	s_waitcnt vmcnt(11)
	v_pk_add_f32 v[2:3], v[2:3], 0 op_sel_hi:[1,0]
	v_pk_add_f32 v[0:1], v[0:1], 0 op_sel_hi:[1,0]
	s_waitcnt vmcnt(10)
	v_pk_add_f32 v[2:3], v[2:3], v[6:7]
	v_pk_add_f32 v[0:1], v[0:1], v[4:5]
	s_waitcnt vmcnt(9)
	v_pk_add_f32 v[2:3], v[2:3], v[10:11]
	s_waitcnt vmcnt(7)
	v_pk_add_f32 v[4:5], v[18:19], 0 op_sel_hi:[1,0]
	v_pk_add_f32 v[6:7], v[16:17], 0 op_sel_hi:[1,0]
	v_pk_add_f32 v[0:1], v[0:1], v[8:9]
	s_waitcnt vmcnt(6)
	v_pk_add_f32 v[4:5], v[4:5], v[22:23]
	v_pk_add_f32 v[6:7], v[6:7], v[20:21]
	v_pk_add_f32 v[2:3], v[2:3], v[14:15]
	v_pk_add_f32 v[0:1], v[0:1], v[12:13]
	s_waitcnt vmcnt(5)
	v_pk_add_f32 v[4:5], v[4:5], v[26:27]
	v_pk_add_f32 v[6:7], v[6:7], v[24:25]
	v_mul_f32_e32 v228, 0x3d800000, v0
	v_mul_f32_e32 v231, 0x3d800000, v1
	v_mul_f32_e32 v229, 0x3d800000, v2
	v_mul_f32_e32 v225, 0x3d800000, v3
	s_waitcnt vmcnt(4)
	v_pk_add_f32 v[0:1], v[4:5], v[30:31]
	v_pk_add_f32 v[2:3], v[6:7], v[28:29]
	v_mul_f32_e32 v227, 0x3d800000, v0
	v_mul_f32_e32 v226, 0x3d800000, v2
	v_mul_f32_e32 v230, 0x3d800000, v3
	v_mul_f32_e32 v224, 0x3d800000, v1
	s_waitcnt vmcnt(3)
	v_pk_add_f32 v[0:1], v[34:35], 0 op_sel_hi:[1,0]
	v_pk_add_f32 v[2:3], v[32:33], 0 op_sel_hi:[1,0]
	s_waitcnt vmcnt(2)
	v_pk_add_f32 v[0:1], v[0:1], v[38:39]
	v_pk_add_f32 v[2:3], v[2:3], v[36:37]
	s_waitcnt vmcnt(1)
	v_pk_add_f32 v[0:1], v[0:1], v[42:43]
	v_pk_add_f32 v[2:3], v[2:3], v[40:41]
	s_waitcnt vmcnt(0)
	v_pk_add_f32 v[210:211], v[0:1], v[46:47]
	v_pk_add_f32 v[0:1], v[2:3], v[44:45]
	v_mul_f32_e32 v233, 0x3d800000, v210
	v_mul_f32_e32 v232, 0x3d800000, v0
	v_mul_f32_e32 v234, 0x3d800000, v1
	v_lshl_add_u64 v[0:1], v[48:49], 0, s[6:7]
	v_add_co_u32_e32 v2, vcc, s3, v0
	v_ashrrev_i32_e32 v210, 6, v222
	s_nop 0
	v_addc_co_u32_e32 v3, vcc, 0, v1, vcc
	global_load_dwordx4 v[128:131], v[0:1], off
	global_load_dwordx4 v[132:135], v[2:3], off
	v_add_co_u32_e32 v2, vcc, s33, v0
	v_mul_f32_e32 v211, 0x3d800000, v211
	s_nop 0
	v_addc_co_u32_e32 v3, vcc, 0, v1, vcc
	v_add_co_u32_e32 v0, vcc, s38, v0
	v_cmp_lt_i32_e64 s[6:7], v218, v216
	s_nop 0
	v_addc_co_u32_e32 v1, vcc, 0, v1, vcc
	global_load_dwordx4 v[136:139], v[2:3], off
	global_load_dwordx4 v[140:143], v[0:1], off
	v_lshlrev_b32_e32 v0, 5, v210
	v_ashrrev_i32_e32 v1, 31, v0
	v_or_b32_e32 v6, 1, v0
	v_lshl_add_u64 v[2:3], s[4:5], 0, v[144:145]
	v_lshlrev_b64 v[162:163], 12, v[0:1]
	v_ashrrev_i32_e32 v7, 31, v6
	v_lshl_add_u64 v[4:5], v[2:3], 0, v[162:163]
	v_lshlrev_b64 v[166:167], 12, v[6:7]
	v_lshl_add_u64 v[6:7], v[2:3], 0, v[166:167]
	global_load_dwordx4 v[124:127], v[4:5], off nt
	global_load_dwordx4 v[120:123], v[6:7], off nt
	v_or_b32_e32 v4, 2, v0
	v_ashrrev_i32_e32 v5, 31, v4
	v_or_b32_e32 v6, 3, v0
	v_lshlrev_b64 v[168:169], 12, v[4:5]
	v_ashrrev_i32_e32 v7, 31, v6
	v_lshl_add_u64 v[4:5], v[2:3], 0, v[168:169]
	v_lshlrev_b64 v[172:173], 12, v[6:7]
	v_lshl_add_u64 v[6:7], v[2:3], 0, v[172:173]
	global_load_dwordx4 v[116:119], v[4:5], off nt
	global_load_dwordx4 v[112:115], v[6:7], off nt
	v_or_b32_e32 v4, 4, v0
	v_ashrrev_i32_e32 v5, 31, v4
	v_or_b32_e32 v6, 5, v0
	v_lshlrev_b64 v[176:177], 12, v[4:5]
	v_ashrrev_i32_e32 v7, 31, v6
	v_lshl_add_u64 v[4:5], v[2:3], 0, v[176:177]
	v_lshlrev_b64 v[180:181], 12, v[6:7]
	v_lshl_add_u64 v[6:7], v[2:3], 0, v[180:181]
	global_load_dwordx4 v[108:111], v[4:5], off nt
	global_load_dwordx4 v[104:107], v[6:7], off nt
	v_or_b32_e32 v4, 6, v0
	v_ashrrev_i32_e32 v5, 31, v4
	v_or_b32_e32 v6, 7, v0
; DI void attn_sample_item(const Params& p, int item, ldsp lds, int tid_) {
;     ...
;   for (int t = 0; t < 4; ++t) { f32x4 a = {0.f, 0.f, 0.f, 0.f}; const float* pp = (const float*)(p.ws + B_PART) + (size_t)(b * 4 + t) * 1024 + h * 256 + lane * 4;
; #pragma unroll
;     for (int kp = 0; kp < 4; ++kp) a += *(const f32x4*)(pp + (size_t)kp * 512 * 1024);
;     q[t][0] = a[0] * 0.0625f; q[t][1] = a[1] * 0.0625f; q[t][2] = a[2] * 0.0625f; q[t][3] = a[3] * 0.0625f; }
;   const bool b0 = lane & 1, b1 = lane & 2;
;   f32x4 kvA[16], kvB[16];
; #pragma unroll
;   for (int j = 0; j < 16; ++j) kvA[j] = __builtin_nontemporal_load((const f32x4*)(ck + (size_t)(wid * 32 + j) * 1024 + lane * 4));
; #pragma unroll
;   for (int j = 0; j < 16; ++j) kvB[j] = __builtin_nontemporal_load((const f32x4*)(ck + (size_t)(wid * 32 + 16 + j) * 1024 + lane * 4));
	v_lshlrev_b64 v[182:183], 12, v[4:5]
	v_ashrrev_i32_e32 v7, 31, v6
	v_lshl_add_u64 v[4:5], v[2:3], 0, v[182:183]
	v_lshlrev_b64 v[186:187], 12, v[6:7]
	v_lshl_add_u64 v[6:7], v[2:3], 0, v[186:187]
	global_load_dwordx4 v[100:103], v[4:5], off nt
	global_load_dwordx4 v[96:99], v[6:7], off nt
	v_or_b32_e32 v4, 8, v0
	v_ashrrev_i32_e32 v5, 31, v4
	v_or_b32_e32 v6, 9, v0
	v_lshlrev_b64 v[190:191], 12, v[4:5]
	v_ashrrev_i32_e32 v7, 31, v6
	v_lshl_add_u64 v[4:5], v[2:3], 0, v[190:191]
	v_lshlrev_b64 v[194:195], 12, v[6:7]
	v_lshl_add_u64 v[6:7], v[2:3], 0, v[194:195]
	global_load_dwordx4 v[92:95], v[4:5], off nt
	global_load_dwordx4 v[88:91], v[6:7], off nt
	v_or_b32_e32 v4, 10, v0
	v_ashrrev_i32_e32 v5, 31, v4
	v_or_b32_e32 v6, 11, v0
	v_lshlrev_b64 v[198:199], 12, v[4:5]
	v_ashrrev_i32_e32 v7, 31, v6
	v_lshl_add_u64 v[4:5], v[2:3], 0, v[198:199]
	v_lshlrev_b64 v[200:201], 12, v[6:7]
	v_lshl_add_u64 v[6:7], v[2:3], 0, v[200:201]
	global_load_dwordx4 v[84:87], v[4:5], off nt
	global_load_dwordx4 v[80:83], v[6:7], off nt
	v_or_b32_e32 v4, 12, v0
	v_ashrrev_i32_e32 v5, 31, v4
	v_or_b32_e32 v6, 13, v0
	v_lshlrev_b64 v[202:203], 12, v[4:5]
	v_ashrrev_i32_e32 v7, 31, v6
	v_lshl_add_u64 v[4:5], v[2:3], 0, v[202:203]
	v_lshlrev_b64 v[204:205], 12, v[6:7]
	v_lshl_add_u64 v[6:7], v[2:3], 0, v[204:205]
	global_load_dwordx4 v[76:79], v[4:5], off nt
	global_load_dwordx4 v[72:75], v[6:7], off nt
	v_or_b32_e32 v4, 14, v0
	v_ashrrev_i32_e32 v5, 31, v4
	v_or_b32_e32 v6, 15, v0
	v_lshlrev_b64 v[206:207], 12, v[4:5]
	v_ashrrev_i32_e32 v7, 31, v6
	v_lshl_add_u64 v[4:5], v[2:3], 0, v[206:207]
	v_lshlrev_b64 v[208:209], 12, v[6:7]
	v_lshl_add_u64 v[6:7], v[2:3], 0, v[208:209]
	global_load_dwordx4 v[68:71], v[4:5], off nt
	global_load_dwordx4 v[64:67], v[6:7], off nt
	v_or_b32_e32 v4, 16, v0
	v_ashrrev_i32_e32 v5, 31, v4
	v_or_b32_e32 v6, 17, v0
	v_lshlrev_b64 v[146:147], 12, v[4:5]
	v_ashrrev_i32_e32 v7, 31, v6
	v_lshl_add_u64 v[4:5], v[2:3], 0, v[146:147]
	v_lshlrev_b64 v[148:149], 12, v[6:7]
	v_lshl_add_u64 v[6:7], v[2:3], 0, v[148:149]
	global_load_dwordx4 v[60:63], v[4:5], off nt
	global_load_dwordx4 v[56:59], v[6:7], off nt
	v_or_b32_e32 v4, 18, v0
	v_ashrrev_i32_e32 v5, 31, v4
	v_or_b32_e32 v6, 19, v0
	v_lshlrev_b64 v[150:151], 12, v[4:5]
	v_ashrrev_i32_e32 v7, 31, v6
	v_lshl_add_u64 v[4:5], v[2:3], 0, v[150:151]
	v_lshlrev_b64 v[152:153], 12, v[6:7]
	v_lshl_add_u64 v[6:7], v[2:3], 0, v[152:153]
	global_load_dwordx4 v[52:55], v[4:5], off nt
	global_load_dwordx4 v[48:51], v[6:7], off nt
	v_or_b32_e32 v4, 20, v0
	v_ashrrev_i32_e32 v5, 31, v4
	v_or_b32_e32 v6, 21, v0
	v_lshlrev_b64 v[154:155], 12, v[4:5]
	v_ashrrev_i32_e32 v7, 31, v6
	v_lshl_add_u64 v[4:5], v[2:3], 0, v[154:155]
	v_lshlrev_b64 v[156:157], 12, v[6:7]
	v_lshl_add_u64 v[6:7], v[2:3], 0, v[156:157]
	global_load_dwordx4 v[44:47], v[4:5], off nt
	global_load_dwordx4 v[40:43], v[6:7], off nt
	v_or_b32_e32 v4, 22, v0
	v_ashrrev_i32_e32 v5, 31, v4
	v_or_b32_e32 v6, 23, v0
	v_lshlrev_b64 v[158:159], 12, v[4:5]
	v_ashrrev_i32_e32 v7, 31, v6
	v_lshl_add_u64 v[4:5], v[2:3], 0, v[158:159]
	v_lshlrev_b64 v[160:161], 12, v[6:7]
	v_lshl_add_u64 v[6:7], v[2:3], 0, v[160:161]
	global_load_dwordx4 v[36:39], v[4:5], off nt
	global_load_dwordx4 v[32:35], v[6:7], off nt
	v_or_b32_e32 v4, 24, v0
	v_ashrrev_i32_e32 v5, 31, v4
	v_or_b32_e32 v6, 25, v0
	v_lshlrev_b64 v[164:165], 12, v[4:5]
	v_ashrrev_i32_e32 v7, 31, v6
	v_lshl_add_u64 v[4:5], v[2:3], 0, v[164:165]
	v_lshlrev_b64 v[170:171], 12, v[6:7]
	v_lshl_add_u64 v[6:7], v[2:3], 0, v[170:171]
	global_load_dwordx4 v[28:31], v[4:5], off nt
	global_load_dwordx4 v[24:27], v[6:7], off nt
	v_or_b32_e32 v4, 26, v0
	v_ashrrev_i32_e32 v5, 31, v4
	v_or_b32_e32 v6, 27, v0
	v_lshlrev_b64 v[174:175], 12, v[4:5]
	v_ashrrev_i32_e32 v7, 31, v6
	v_lshl_add_u64 v[4:5], v[2:3], 0, v[174:175]
	v_lshlrev_b64 v[178:179], 12, v[6:7]
	v_lshl_add_u64 v[6:7], v[2:3], 0, v[178:179]
	global_load_dwordx4 v[20:23], v[4:5], off nt
	global_load_dwordx4 v[16:19], v[6:7], off nt
	v_or_b32_e32 v4, 28, v0
	v_ashrrev_i32_e32 v5, 31, v4
	v_or_b32_e32 v6, 29, v0
	v_lshlrev_b64 v[184:185], 12, v[4:5]
	v_ashrrev_i32_e32 v7, 31, v6
	v_lshl_add_u64 v[4:5], v[2:3], 0, v[184:185]
	v_lshlrev_b64 v[188:189], 12, v[6:7]
	v_lshl_add_u64 v[6:7], v[2:3], 0, v[188:189]
	global_load_dwordx4 v[12:15], v[4:5], off nt
	global_load_dwordx4 v[8:11], v[6:7], off nt
	v_or_b32_e32 v4, 30, v0
	v_or_b32_e32 v0, 31, v0
	v_ashrrev_i32_e32 v5, 31, v4
	v_ashrrev_i32_e32 v1, 31, v0
	v_lshlrev_b64 v[192:193], 12, v[4:5]
	v_lshlrev_b64 v[196:197], 12, v[0:1]
	v_lshl_add_u64 v[4:5], v[2:3], 0, v[192:193]
	v_lshl_add_u64 v[0:1], v[2:3], 0, v[196:197]
	global_load_dwordx4 v[4:7], v[4:5], off nt
	s_nop 0
	global_load_dwordx4 v[0:3], v[0:1], off nt
	s_waitcnt vmcnt(35)
	v_pk_add_f32 v[128:129], v[128:129], 0 op_sel_hi:[1,0]
	v_pk_add_f32 v[130:131], v[130:131], 0 op_sel_hi:[1,0]
	s_waitcnt vmcnt(34)
	v_pk_add_f32 v[128:129], v[128:129], v[132:133]
	v_pk_add_f32 v[130:131], v[130:131], v[134:135]
	s_waitcnt vmcnt(33)
	v_pk_add_f32 v[128:129], v[128:129], v[136:137]
	v_pk_add_f32 v[130:131], v[130:131], v[138:139]
	s_waitcnt vmcnt(32)
; DI void attn_sample_item(const Params& p, int item, ldsp lds, int tid_) {
;     ...
;   for (int t = 0; t < 4; ++t) { f32x4 a = {0.f, 0.f, 0.f, 0.f}; const float* pp = (const float*)(p.ws + B_PART) + (size_t)(b * 4 + t) * 1024 + h * 256 + lane * 4;
; #pragma unroll
;     for (int kp = 0; kp < 4; ++kp) a += *(const f32x4*)(pp + (size_t)kp * 512 * 1024);
;     q[t][0] = a[0] * 0.0625f; q[t][1] = a[1] * 0.0625f; q[t][2] = a[2] * 0.0625f; q[t][3] = a[3] * 0.0625f; }
;   const bool b0 = lane & 1, b1 = lane & 2;
;   f32x4 kvA[16], kvB[16];
; #pragma unroll
;   for (int j = 0; j < 16; ++j) kvA[j] = __builtin_nontemporal_load((const f32x4*)(ck + (size_t)(wid * 32 + j) * 1024 + lane * 4));
; #pragma unroll
;   for (int j = 0; j < 16; ++j) kvB[j] = __builtin_nontemporal_load((const f32x4*)(ck + (size_t)(wid * 32 + 16 + j) * 1024 + lane * 4));
	v_pk_add_f32 v[128:129], v[128:129], v[140:141]
	v_pk_add_f32 v[130:131], v[130:131], v[142:143]
	v_mul_f32_e32 v138, 0x3d800000, v129
	v_mul_f32_e32 v135, 0x3d800000, v128
	v_mul_f32_e32 v134, 0x3d800000, v131
	v_mul_f32_e32 v137, 0x3d800000, v130
	v_lshlrev_b32_e32 v128, 2, v215
	v_lshlrev_b32_e32 v129, 2, v217
	v_lshlrev_b32_e32 v130, 2, v218
	v_lshlrev_b32_e32 v131, 2, v219
	v_lshlrev_b32_e32 v132, 2, v220
	v_lshlrev_b32_e32 v133, 2, v221
	v_lshl_add_u32 v136, v210, 7, 16
	v_and_b32_e32 v139, 3, v223
	v_bfrev_b32_e32 v139, v139
	v_lshrrev_b32_e32 v139, 20, v139
	v_and_b32_e32 v235, -4, v223
	v_add3_u32 v235, v136, v139, v235
	v_mov_b32_e32 v236, v228
	v_mov_b32_e32 v237, v226
	v_mov_b32_e32 v238, v231
	v_mov_b32_e32 v239, v230
	v_mov_b32_e32 v240, v229
	v_mov_b32_e32 v241, v227
	v_mov_b32_e32 v242, v225
	v_mov_b32_e32 v243, v224
	v_mov_b32_e32 v244, v232
	v_mov_b32_e32 v245, v135
	v_mov_b32_e32 v246, v234
	v_mov_b32_e32 v247, v138
	v_mov_b32_e32 v248, v233
	v_mov_b32_e32 v249, v137
	v_mov_b32_e32 v250, v211
	v_mov_b32_e32 v251, v134
	s_mov_b32 vcc_lo, 0x55555555
	s_mov_b32 vcc_hi, 0x55555555
	s_mov_b32 s4, 0x33333333
	s_mov_b32 s5, 0x33333333
	s_mov_b32 s6, 0x0f0f0f0f
	s_mov_b32 s7, 0x0f0f0f0f
	s_mov_b32 s64, 0x00ff00ff
	s_mov_b32 s65, 0x00ff00ff
	s_waitcnt vmcnt(31)
	v_pk_mul_f32 v[252:253], v[236:237], v[124:125] op_sel_hi:[1,0]
	v_pk_mul_f32 v[254:255], v[244:245], v[124:125] op_sel_hi:[1,0]
	v_pk_fma_f32 v[252:253], v[238:239], v[124:125], v[252:253] op_sel:[0,1,0]
	v_pk_fma_f32 v[254:255], v[246:247], v[124:125], v[254:255] op_sel:[0,1,0]
	v_pk_fma_f32 v[252:253], v[240:241], v[126:127], v[252:253] op_sel_hi:[1,0,1]
	v_pk_fma_f32 v[254:255], v[248:249], v[126:127], v[254:255] op_sel_hi:[1,0,1]
	v_pk_fma_f32 v[252:253], v[242:243], v[126:127], v[252:253] op_sel:[0,1,0]
	v_pk_fma_f32 v[254:255], v[250:251], v[126:127], v[254:255] op_sel:[0,1,0]
	s_waitcnt vmcnt(30)
	v_pk_mul_f32 v[140:141], v[236:237], v[120:121] op_sel_hi:[1,0]
	v_pk_mul_f32 v[142:143], v[244:245], v[120:121] op_sel_hi:[1,0]
	v_pk_fma_f32 v[140:141], v[238:239], v[120:121], v[140:141] op_sel:[0,1,0]
	v_pk_fma_f32 v[142:143], v[246:247], v[120:121], v[142:143] op_sel:[0,1,0]
	v_pk_fma_f32 v[140:141], v[240:241], v[122:123], v[140:141] op_sel_hi:[1,0,1]
	v_pk_fma_f32 v[142:143], v[248:249], v[122:123], v[142:143] op_sel_hi:[1,0,1]
	v_pk_fma_f32 v[140:141], v[242:243], v[122:123], v[140:141] op_sel:[0,1,0]
	v_pk_fma_f32 v[142:143], v[250:251], v[122:123], v[142:143] op_sel:[0,1,0]
	v_add_f32_dpp v124, v252, v252 quad_perm:[1,0,3,2] row_mask:0xf bank_mask:0xf
	v_add_f32_dpp v125, v253, v253 quad_perm:[1,0,3,2] row_mask:0xf bank_mask:0xf
	v_add_f32_dpp v126, v254, v254 quad_perm:[1,0,3,2] row_mask:0xf bank_mask:0xf
	v_add_f32_dpp v127, v255, v255 quad_perm:[1,0,3,2] row_mask:0xf bank_mask:0xf
	v_cndmask_b32_e32 v124, v126, v124, vcc
	v_cndmask_b32_e32 v125, v127, v125, vcc
	s_waitcnt vmcnt(29)
	v_pk_mul_f32 v[252:253], v[236:237], v[116:117] op_sel_hi:[1,0]
	v_pk_mul_f32 v[254:255], v[244:245], v[116:117] op_sel_hi:[1,0]
	v_pk_fma_f32 v[252:253], v[238:239], v[116:117], v[252:253] op_sel:[0,1,0]
	v_pk_fma_f32 v[254:255], v[246:247], v[116:117], v[254:255] op_sel:[0,1,0]
	v_pk_fma_f32 v[252:253], v[240:241], v[118:119], v[252:253] op_sel_hi:[1,0,1]
	v_pk_fma_f32 v[254:255], v[248:249], v[118:119], v[254:255] op_sel_hi:[1,0,1]
	v_pk_fma_f32 v[252:253], v[242:243], v[118:119], v[252:253] op_sel:[0,1,0]
	v_pk_fma_f32 v[254:255], v[250:251], v[118:119], v[254:255] op_sel:[0,1,0]
	v_add_f32_dpp v120, v140, v140 quad_perm:[1,0,3,2] row_mask:0xf bank_mask:0xf
	v_add_f32_dpp v121, v141, v141 quad_perm:[1,0,3,2] row_mask:0xf bank_mask:0xf
	v_add_f32_dpp v122, v142, v142 quad_perm:[1,0,3,2] row_mask:0xf bank_mask:0xf
	v_add_f32_dpp v123, v143, v143 quad_perm:[1,0,3,2] row_mask:0xf bank_mask:0xf
	v_cndmask_b32_e32 v120, v122, v120, vcc
	v_cndmask_b32_e32 v121, v123, v121, vcc
	v_add_f32_dpp v126, v124, v124 quad_perm:[2,3,0,1] row_mask:0xf bank_mask:0xf
	v_add_f32_dpp v127, v125, v125 quad_perm:[2,3,0,1] row_mask:0xf bank_mask:0xf
	v_cndmask_b32_e64 v124, v127, v126, s[4:5]
	s_waitcnt vmcnt(28)
	v_pk_mul_f32 v[140:141], v[236:237], v[112:113] op_sel_hi:[1,0]
	v_pk_mul_f32 v[142:143], v[244:245], v[112:113] op_sel_hi:[1,0]
	v_pk_fma_f32 v[140:141], v[238:239], v[112:113], v[140:141] op_sel:[0,1,0]
	v_pk_fma_f32 v[142:143], v[246:247], v[112:113], v[142:143] op_sel:[0,1,0]
	v_pk_fma_f32 v[140:141], v[240:241], v[114:115], v[140:141] op_sel_hi:[1,0,1]
	v_pk_fma_f32 v[142:143], v[248:249], v[114:115], v[142:143] op_sel_hi:[1,0,1]
	v_pk_fma_f32 v[140:141], v[242:243], v[114:115], v[140:141] op_sel:[0,1,0]
	v_pk_fma_f32 v[142:143], v[250:251], v[114:115], v[142:143] op_sel:[0,1,0]
	v_add_f32_dpp v116, v252, v252 quad_perm:[1,0,3,2] row_mask:0xf bank_mask:0xf
	v_add_f32_dpp v117, v253, v253 quad_perm:[1,0,3,2] row_mask:0xf bank_mask:0xf
	v_add_f32_dpp v118, v254, v254 quad_perm:[1,0,3,2] row_mask:0xf bank_mask:0xf
	v_add_f32_dpp v119, v255, v255 quad_perm:[1,0,3,2] row_mask:0xf bank_mask:0xf
	v_cndmask_b32_e32 v116, v118, v116, vcc
	v_cndmask_b32_e32 v117, v119, v117, vcc
	v_add_f32_dpp v122, v120, v120 quad_perm:[2,3,0,1] row_mask:0xf bank_mask:0xf
	v_add_f32_dpp v123, v121, v121 quad_perm:[2,3,0,1] row_mask:0xf bank_mask:0xf
	v_cndmask_b32_e64 v120, v123, v122, s[4:5]
	v_cndmask_b32_e64 v125, v120, v124, s[6:7]
	v_cndmask_b32_e64 v126, v124, v120, s[6:7]
	s_waitcnt vmcnt(27)
	v_pk_mul_f32 v[252:253], v[236:237], v[108:109] op_sel_hi:[1,0]
	v_pk_mul_f32 v[254:255], v[244:245], v[108:109] op_sel_hi:[1,0]
	v_pk_fma_f32 v[252:253], v[238:239], v[108:109], v[252:253] op_sel:[0,1,0]
	v_pk_fma_f32 v[254:255], v[246:247], v[108:109], v[254:255] op_sel:[0,1,0]
	v_pk_fma_f32 v[252:253], v[240:241], v[110:111], v[252:253] op_sel_hi:[1,0,1]
	v_pk_fma_f32 v[254:255], v[248:249], v[110:111], v[254:255] op_sel_hi:[1,0,1]
	v_pk_fma_f32 v[252:253], v[242:243], v[110:111], v[252:253] op_sel:[0,1,0]
	v_pk_fma_f32 v[254:255], v[250:251], v[110:111], v[254:255] op_sel:[0,1,0]
	v_add_f32_dpp v124, v126, v125 row_ror:4 row_mask:0xf bank_mask:0xf
	v_add_f32_dpp v112, v140, v140 quad_perm:[1,0,3,2] row_mask:0xf bank_mask:0xf
	v_add_f32_dpp v113, v141, v141 quad_perm:[1,0,3,2] row_mask:0xf bank_mask:0xf
	v_add_f32_dpp v114, v142, v142 quad_perm:[1,0,3,2] row_mask:0xf bank_mask:0xf
	v_add_f32_dpp v115, v143, v143 quad_perm:[1,0,3,2] row_mask:0xf bank_mask:0xf
	v_cndmask_b32_e32 v112, v114, v112, vcc
	v_cndmask_b32_e32 v113, v115, v113, vcc
	v_add_f32_dpp v118, v116, v116 quad_perm:[2,3,0,1] row_mask:0xf bank_mask:0xf
	v_add_f32_dpp v119, v117, v117 quad_perm:[2,3,0,1] row_mask:0xf bank_mask:0xf
	v_cndmask_b32_e64 v116, v119, v118, s[4:5]
	s_waitcnt vmcnt(26)
	v_pk_mul_f32 v[140:141], v[236:237], v[104:105] op_sel_hi:[1,0]
	v_pk_mul_f32 v[142:143], v[244:245], v[104:105] op_sel_hi:[1,0]
	v_pk_fma_f32 v[140:141], v[238:239], v[104:105], v[140:141] op_sel:[0,1,0]
	v_pk_fma_f32 v[142:143], v[246:247], v[104:105], v[142:143] op_sel:[0,1,0]
	v_pk_fma_f32 v[140:141], v[240:241], v[106:107], v[140:141] op_sel_hi:[1,0,1]
	v_pk_fma_f32 v[142:143], v[248:249], v[106:107], v[142:143] op_sel_hi:[1,0,1]
	v_pk_fma_f32 v[140:141], v[242:243], v[106:107], v[140:141] op_sel:[0,1,0]
	v_pk_fma_f32 v[142:143], v[250:251], v[106:107], v[142:143] op_sel:[0,1,0]
	v_add_f32_dpp v108, v252, v252 quad_perm:[1,0,3,2] row_mask:0xf bank_mask:0xf
	v_add_f32_dpp v109, v253, v253 quad_perm:[1,0,3,2] row_mask:0xf bank_mask:0xf
	v_add_f32_dpp v110, v254, v254 quad_perm:[1,0,3,2] row_mask:0xf bank_mask:0xf
	v_add_f32_dpp v111, v255, v255 quad_perm:[1,0,3,2] row_mask:0xf bank_mask:0xf
	v_cndmask_b32_e32 v108, v110, v108, vcc
	v_cndmask_b32_e32 v109, v111, v109, vcc
	v_add_f32_dpp v114, v112, v112 quad_perm:[2,3,0,1] row_mask:0xf bank_mask:0xf
	v_add_f32_dpp v115, v113, v113 quad_perm:[2,3,0,1] row_mask:0xf bank_mask:0xf
	v_cndmask_b32_e64 v112, v115, v114, s[4:5]
	v_cndmask_b32_e64 v117, v112, v116, s[6:7]
	v_cndmask_b32_e64 v118, v116, v112, s[6:7]
	s_waitcnt vmcnt(25)
	v_pk_mul_f32 v[252:253], v[236:237], v[100:101] op_sel_hi:[1,0]
	v_pk_mul_f32 v[254:255], v[244:245], v[100:101] op_sel_hi:[1,0]
	v_pk_fma_f32 v[252:253], v[238:239], v[100:101], v[252:253] op_sel:[0,1,0]
	v_pk_fma_f32 v[254:255], v[246:247], v[100:101], v[254:255] op_sel:[0,1,0]
	v_pk_fma_f32 v[252:253], v[240:241], v[102:103], v[252:253] op_sel_hi:[1,0,1]
	v_pk_fma_f32 v[254:255], v[248:249], v[102:103], v[254:255] op_sel_hi:[1,0,1]
	v_pk_fma_f32 v[252:253], v[242:243], v[102:103], v[252:253] op_sel:[0,1,0]
	v_pk_fma_f32 v[254:255], v[250:251], v[102:103], v[254:255] op_sel:[0,1,0]
	v_add_f32_dpp v116, v118, v117 row_ror:4 row_mask:0xf bank_mask:0xf
	v_cndmask_b32_e64 v125, v116, v124, s[64:65]
	v_cndmask_b32_e64 v126, v124, v116, s[64:65]
	v_add_f32_dpp v104, v140, v140 quad_perm:[1,0,3,2] row_mask:0xf bank_mask:0xf
	v_add_f32_dpp v105, v141, v141 quad_perm:[1,0,3,2] row_mask:0xf bank_mask:0xf
	v_add_f32_dpp v106, v142, v142 quad_perm:[1,0,3,2] row_mask:0xf bank_mask:0xf
	v_add_f32_dpp v107, v143, v143 quad_perm:[1,0,3,2] row_mask:0xf bank_mask:0xf
	v_cndmask_b32_e32 v104, v106, v104, vcc
	v_cndmask_b32_e32 v105, v107, v105, vcc
	v_add_f32_dpp v110, v108, v108 quad_perm:[2,3,0,1] row_mask:0xf bank_mask:0xf
	v_add_f32_dpp v111, v109, v109 quad_perm:[2,3,0,1] row_mask:0xf bank_mask:0xf
	v_cndmask_b32_e64 v108, v111, v110, s[4:5]
	s_waitcnt vmcnt(24)
	v_pk_mul_f32 v[140:141], v[236:237], v[96:97] op_sel_hi:[1,0]
	v_pk_mul_f32 v[142:143], v[244:245], v[96:97] op_sel_hi:[1,0]
	v_pk_fma_f32 v[140:141], v[238:239], v[96:97], v[140:141] op_sel:[0,1,0]
	v_pk_fma_f32 v[142:143], v[246:247], v[96:97], v[142:143] op_sel:[0,1,0]
	v_pk_fma_f32 v[140:141], v[240:241], v[98:99], v[140:141] op_sel_hi:[1,0,1]
	v_pk_fma_f32 v[142:143], v[248:249], v[98:99], v[142:143] op_sel_hi:[1,0,1]
	v_pk_fma_f32 v[140:141], v[242:243], v[98:99], v[140:141] op_sel:[0,1,0]
	v_pk_fma_f32 v[142:143], v[250:251], v[98:99], v[142:143] op_sel:[0,1,0]
	v_add_f32_dpp v124, v126, v125 row_ror:8 row_mask:0xf bank_mask:0xf
	v_add_f32_dpp v100, v252, v252 quad_perm:[1,0,3,2] row_mask:0xf bank_mask:0xf
	v_add_f32_dpp v101, v253, v253 quad_perm:[1,0,3,2] row_mask:0xf bank_mask:0xf
	v_add_f32_dpp v102, v254, v254 quad_perm:[1,0,3,2] row_mask:0xf bank_mask:0xf
	v_add_f32_dpp v103, v255, v255 quad_perm:[1,0,3,2] row_mask:0xf bank_mask:0xf
	v_cndmask_b32_e32 v100, v102, v100, vcc
	v_cndmask_b32_e32 v101, v103, v101, vcc
	v_add_f32_dpp v106, v104, v104 quad_perm:[2,3,0,1] row_mask:0xf bank_mask:0xf
	v_add_f32_dpp v107, v105, v105 quad_perm:[2,3,0,1] row_mask:0xf bank_mask:0xf
	v_cndmask_b32_e64 v104, v107, v106, s[4:5]
	v_cndmask_b32_e64 v109, v104, v108, s[6:7]
	v_cndmask_b32_e64 v110, v108, v104, s[6:7]
	s_waitcnt vmcnt(23)
	v_pk_mul_f32 v[252:253], v[236:237], v[92:93] op_sel_hi:[1,0]
	v_pk_mul_f32 v[254:255], v[244:245], v[92:93] op_sel_hi:[1,0]
	v_pk_fma_f32 v[252:253], v[238:239], v[92:93], v[252:253] op_sel:[0,1,0]
	v_pk_fma_f32 v[254:255], v[246:247], v[92:93], v[254:255] op_sel:[0,1,0]
	v_pk_fma_f32 v[252:253], v[240:241], v[94:95], v[252:253] op_sel_hi:[1,0,1]
	v_pk_fma_f32 v[254:255], v[248:249], v[94:95], v[254:255] op_sel_hi:[1,0,1]
	v_pk_fma_f32 v[252:253], v[242:243], v[94:95], v[252:253] op_sel:[0,1,0]
	v_pk_fma_f32 v[254:255], v[250:251], v[94:95], v[254:255] op_sel:[0,1,0]
	v_add_f32_dpp v108, v110, v109 row_ror:4 row_mask:0xf bank_mask:0xf
	v_add_f32_dpp v96, v140, v140 quad_perm:[1,0,3,2] row_mask:0xf bank_mask:0xf
	v_add_f32_dpp v97, v141, v141 quad_perm:[1,0,3,2] row_mask:0xf bank_mask:0xf
	v_add_f32_dpp v98, v142, v142 quad_perm:[1,0,3,2] row_mask:0xf bank_mask:0xf
	v_add_f32_dpp v99, v143, v143 quad_perm:[1,0,3,2] row_mask:0xf bank_mask:0xf
	v_cndmask_b32_e32 v96, v98, v96, vcc
	v_cndmask_b32_e32 v97, v99, v97, vcc
	v_add_f32_dpp v102, v100, v100 quad_perm:[2,3,0,1] row_mask:0xf bank_mask:0xf
	v_add_f32_dpp v103, v101, v101 quad_perm:[2,3,0,1] row_mask:0xf bank_mask:0xf
	v_cndmask_b32_e64 v100, v103, v102, s[4:5]
	s_waitcnt vmcnt(22)
	v_pk_mul_f32 v[140:141], v[236:237], v[88:89] op_sel_hi:[1,0]
	v_pk_mul_f32 v[142:143], v[244:245], v[88:89] op_sel_hi:[1,0]
	v_pk_fma_f32 v[140:141], v[238:239], v[88:89], v[140:141] op_sel:[0,1,0]
	v_pk_fma_f32 v[142:143], v[246:247], v[88:89], v[142:143] op_sel:[0,1,0]
	v_pk_fma_f32 v[140:141], v[240:241], v[90:91], v[140:141] op_sel_hi:[1,0,1]
	v_pk_fma_f32 v[142:143], v[248:249], v[90:91], v[142:143] op_sel_hi:[1,0,1]
	v_pk_fma_f32 v[140:141], v[242:243], v[90:91], v[140:141] op_sel:[0,1,0]
	v_pk_fma_f32 v[142:143], v[250:251], v[90:91], v[142:143] op_sel:[0,1,0]
	v_add_f32_dpp v92, v252, v252 quad_perm:[1,0,3,2] row_mask:0xf bank_mask:0xf
	v_add_f32_dpp v93, v253, v253 quad_perm:[1,0,3,2] row_mask:0xf bank_mask:0xf
	v_add_f32_dpp v94, v254, v254 quad_perm:[1,0,3,2] row_mask:0xf bank_mask:0xf
	v_add_f32_dpp v95, v255, v255 quad_perm:[1,0,3,2] row_mask:0xf bank_mask:0xf
	v_cndmask_b32_e32 v92, v94, v92, vcc
	v_cndmask_b32_e32 v93, v95, v93, vcc
	v_add_f32_dpp v98, v96, v96 quad_perm:[2,3,0,1] row_mask:0xf bank_mask:0xf
	v_add_f32_dpp v99, v97, v97 quad_perm:[2,3,0,1] row_mask:0xf bank_mask:0xf
	v_cndmask_b32_e64 v96, v99, v98, s[4:5]
	v_cndmask_b32_e64 v101, v96, v100, s[6:7]
	v_cndmask_b32_e64 v102, v100, v96, s[6:7]
	s_waitcnt vmcnt(21)
	v_pk_mul_f32 v[252:253], v[236:237], v[84:85] op_sel_hi:[1,0]
	v_pk_mul_f32 v[254:255], v[244:245], v[84:85] op_sel_hi:[1,0]
	v_pk_fma_f32 v[252:253], v[238:239], v[84:85], v[252:253] op_sel:[0,1,0]
	v_pk_fma_f32 v[254:255], v[246:247], v[84:85], v[254:255] op_sel:[0,1,0]
	v_pk_fma_f32 v[252:253], v[240:241], v[86:87], v[252:253] op_sel_hi:[1,0,1]
	v_pk_fma_f32 v[254:255], v[248:249], v[86:87], v[254:255] op_sel_hi:[1,0,1]
	v_pk_fma_f32 v[252:253], v[242:243], v[86:87], v[252:253] op_sel:[0,1,0]
	v_pk_fma_f32 v[254:255], v[250:251], v[86:87], v[254:255] op_sel:[0,1,0]
	v_add_f32_dpp v100, v102, v101 row_ror:4 row_mask:0xf bank_mask:0xf
	v_cndmask_b32_e64 v109, v100, v108, s[64:65]
	v_cndmask_b32_e64 v110, v108, v100, s[64:65]
	v_add_f32_dpp v88, v140, v140 quad_perm:[1,0,3,2] row_mask:0xf bank_mask:0xf
	v_add_f32_dpp v89, v141, v141 quad_perm:[1,0,3,2] row_mask:0xf bank_mask:0xf
	v_add_f32_dpp v90, v142, v142 quad_perm:[1,0,3,2] row_mask:0xf bank_mask:0xf
	v_add_f32_dpp v91, v143, v143 quad_perm:[1,0,3,2] row_mask:0xf bank_mask:0xf
	v_cndmask_b32_e32 v88, v90, v88, vcc
	v_cndmask_b32_e32 v89, v91, v89, vcc
	v_add_f32_dpp v94, v92, v92 quad_perm:[2,3,0,1] row_mask:0xf bank_mask:0xf
	v_add_f32_dpp v95, v93, v93 quad_perm:[2,3,0,1] row_mask:0xf bank_mask:0xf
	v_cndmask_b32_e64 v92, v95, v94, s[4:5]
	s_waitcnt vmcnt(20)
	v_pk_mul_f32 v[140:141], v[236:237], v[80:81] op_sel_hi:[1,0]
	v_pk_mul_f32 v[142:143], v[244:245], v[80:81] op_sel_hi:[1,0]
	v_pk_fma_f32 v[140:141], v[238:239], v[80:81], v[140:141] op_sel:[0,1,0]
	v_pk_fma_f32 v[142:143], v[246:247], v[80:81], v[142:143] op_sel:[0,1,0]
	v_pk_fma_f32 v[140:141], v[240:241], v[82:83], v[140:141] op_sel_hi:[1,0,1]
	v_pk_fma_f32 v[142:143], v[248:249], v[82:83], v[142:143] op_sel_hi:[1,0,1]
	v_pk_fma_f32 v[140:141], v[242:243], v[82:83], v[140:141] op_sel:[0,1,0]
	v_pk_fma_f32 v[142:143], v[250:251], v[82:83], v[142:143] op_sel:[0,1,0]
	v_add_f32_dpp v108, v110, v109 row_ror:8 row_mask:0xf bank_mask:0xf
	v_add_f32_dpp v84, v252, v252 quad_perm:[1,0,3,2] row_mask:0xf bank_mask:0xf
	v_add_f32_dpp v85, v253, v253 quad_perm:[1,0,3,2] row_mask:0xf bank_mask:0xf
	v_add_f32_dpp v86, v254, v254 quad_perm:[1,0,3,2] row_mask:0xf bank_mask:0xf
	v_add_f32_dpp v87, v255, v255 quad_perm:[1,0,3,2] row_mask:0xf bank_mask:0xf
	v_cndmask_b32_e32 v84, v86, v84, vcc
	v_cndmask_b32_e32 v85, v87, v85, vcc
	v_add_f32_dpp v90, v88, v88 quad_perm:[2,3,0,1] row_mask:0xf bank_mask:0xf
	v_add_f32_dpp v91, v89, v89 quad_perm:[2,3,0,1] row_mask:0xf bank_mask:0xf
	v_cndmask_b32_e64 v88, v91, v90, s[4:5]
	v_cndmask_b32_e64 v93, v88, v92, s[6:7]
	v_cndmask_b32_e64 v94, v92, v88, s[6:7]
	s_waitcnt vmcnt(19)
	v_pk_mul_f32 v[252:253], v[236:237], v[76:77] op_sel_hi:[1,0]
	v_pk_mul_f32 v[254:255], v[244:245], v[76:77] op_sel_hi:[1,0]
	v_pk_fma_f32 v[252:253], v[238:239], v[76:77], v[252:253] op_sel:[0,1,0]
	v_pk_fma_f32 v[254:255], v[246:247], v[76:77], v[254:255] op_sel:[0,1,0]
	v_pk_fma_f32 v[252:253], v[240:241], v[78:79], v[252:253] op_sel_hi:[1,0,1]
	v_pk_fma_f32 v[254:255], v[248:249], v[78:79], v[254:255] op_sel_hi:[1,0,1]
	v_pk_fma_f32 v[252:253], v[242:243], v[78:79], v[252:253] op_sel:[0,1,0]
	v_pk_fma_f32 v[254:255], v[250:251], v[78:79], v[254:255] op_sel:[0,1,0]
	v_permlane16_swap_b32_e32 v124, v108
	v_add_f32_e32 v124, v124, v108
	v_add_f32_dpp v92, v94, v93 row_ror:4 row_mask:0xf bank_mask:0xf
	v_add_f32_dpp v80, v140, v140 quad_perm:[1,0,3,2] row_mask:0xf bank_mask:0xf
	v_add_f32_dpp v81, v141, v141 quad_perm:[1,0,3,2] row_mask:0xf bank_mask:0xf
	v_add_f32_dpp v82, v142, v142 quad_perm:[1,0,3,2] row_mask:0xf bank_mask:0xf
	v_add_f32_dpp v83, v143, v143 quad_perm:[1,0,3,2] row_mask:0xf bank_mask:0xf
	v_cndmask_b32_e32 v80, v82, v80, vcc
	v_cndmask_b32_e32 v81, v83, v81, vcc
	v_add_f32_dpp v86, v84, v84 quad_perm:[2,3,0,1] row_mask:0xf bank_mask:0xf
	v_add_f32_dpp v87, v85, v85 quad_perm:[2,3,0,1] row_mask:0xf bank_mask:0xf
	v_cndmask_b32_e64 v84, v87, v86, s[4:5]
	s_waitcnt vmcnt(18)
	v_pk_mul_f32 v[140:141], v[236:237], v[72:73] op_sel_hi:[1,0]
	v_pk_mul_f32 v[142:143], v[244:245], v[72:73] op_sel_hi:[1,0]
	v_pk_fma_f32 v[140:141], v[238:239], v[72:73], v[140:141] op_sel:[0,1,0]
	v_pk_fma_f32 v[142:143], v[246:247], v[72:73], v[142:143] op_sel:[0,1,0]
	v_pk_fma_f32 v[140:141], v[240:241], v[74:75], v[140:141] op_sel_hi:[1,0,1]
	v_pk_fma_f32 v[142:143], v[248:249], v[74:75], v[142:143] op_sel_hi:[1,0,1]
	v_pk_fma_f32 v[140:141], v[242:243], v[74:75], v[140:141] op_sel:[0,1,0]
	v_pk_fma_f32 v[142:143], v[250:251], v[74:75], v[142:143] op_sel:[0,1,0]
	v_add_f32_dpp v76, v252, v252 quad_perm:[1,0,3,2] row_mask:0xf bank_mask:0xf
	v_add_f32_dpp v77, v253, v253 quad_perm:[1,0,3,2] row_mask:0xf bank_mask:0xf
	v_add_f32_dpp v78, v254, v254 quad_perm:[1,0,3,2] row_mask:0xf bank_mask:0xf
	v_add_f32_dpp v79, v255, v255 quad_perm:[1,0,3,2] row_mask:0xf bank_mask:0xf
	v_cndmask_b32_e32 v76, v78, v76, vcc
	v_cndmask_b32_e32 v77, v79, v77, vcc
	v_add_f32_dpp v82, v80, v80 quad_perm:[2,3,0,1] row_mask:0xf bank_mask:0xf
	v_add_f32_dpp v83, v81, v81 quad_perm:[2,3,0,1] row_mask:0xf bank_mask:0xf
	v_cndmask_b32_e64 v80, v83, v82, s[4:5]
	v_cndmask_b32_e64 v85, v80, v84, s[6:7]
	v_cndmask_b32_e64 v86, v84, v80, s[6:7]
	s_waitcnt vmcnt(17)
	v_pk_mul_f32 v[252:253], v[236:237], v[68:69] op_sel_hi:[1,0]
	v_pk_mul_f32 v[254:255], v[244:245], v[68:69] op_sel_hi:[1,0]
	v_pk_fma_f32 v[252:253], v[238:239], v[68:69], v[252:253] op_sel:[0,1,0]
	v_pk_fma_f32 v[254:255], v[246:247], v[68:69], v[254:255] op_sel:[0,1,0]
	v_pk_fma_f32 v[252:253], v[240:241], v[70:71], v[252:253] op_sel_hi:[1,0,1]
	v_pk_fma_f32 v[254:255], v[248:249], v[70:71], v[254:255] op_sel_hi:[1,0,1]
	v_pk_fma_f32 v[252:253], v[242:243], v[70:71], v[252:253] op_sel:[0,1,0]
	v_pk_fma_f32 v[254:255], v[250:251], v[70:71], v[254:255] op_sel:[0,1,0]
	v_add_f32_dpp v84, v86, v85 row_ror:4 row_mask:0xf bank_mask:0xf
	v_cndmask_b32_e64 v93, v84, v92, s[64:65]
	v_cndmask_b32_e64 v94, v92, v84, s[64:65]
	v_add_f32_dpp v72, v140, v140 quad_perm:[1,0,3,2] row_mask:0xf bank_mask:0xf
	v_add_f32_dpp v73, v141, v141 quad_perm:[1,0,3,2] row_mask:0xf bank_mask:0xf
	v_add_f32_dpp v74, v142, v142 quad_perm:[1,0,3,2] row_mask:0xf bank_mask:0xf
	v_add_f32_dpp v75, v143, v143 quad_perm:[1,0,3,2] row_mask:0xf bank_mask:0xf
	v_cndmask_b32_e32 v72, v74, v72, vcc
	v_cndmask_b32_e32 v73, v75, v73, vcc
	v_add_f32_dpp v78, v76, v76 quad_perm:[2,3,0,1] row_mask:0xf bank_mask:0xf
	v_add_f32_dpp v79, v77, v77 quad_perm:[2,3,0,1] row_mask:0xf bank_mask:0xf
	v_cndmask_b32_e64 v76, v79, v78, s[4:5]
	s_waitcnt vmcnt(16)
	v_pk_mul_f32 v[140:141], v[236:237], v[64:65] op_sel_hi:[1,0]
	v_pk_mul_f32 v[142:143], v[244:245], v[64:65] op_sel_hi:[1,0]
	v_pk_fma_f32 v[140:141], v[238:239], v[64:65], v[140:141] op_sel:[0,1,0]
	v_pk_fma_f32 v[142:143], v[246:247], v[64:65], v[142:143] op_sel:[0,1,0]
	v_pk_fma_f32 v[140:141], v[240:241], v[66:67], v[140:141] op_sel_hi:[1,0,1]
	v_pk_fma_f32 v[142:143], v[248:249], v[66:67], v[142:143] op_sel_hi:[1,0,1]
	v_pk_fma_f32 v[140:141], v[242:243], v[66:67], v[140:141] op_sel:[0,1,0]
	v_pk_fma_f32 v[142:143], v[250:251], v[66:67], v[142:143] op_sel:[0,1,0]
	v_add_f32_dpp v92, v94, v93 row_ror:8 row_mask:0xf bank_mask:0xf
	v_add_f32_dpp v68, v252, v252 quad_perm:[1,0,3,2] row_mask:0xf bank_mask:0xf
	v_add_f32_dpp v69, v253, v253 quad_perm:[1,0,3,2] row_mask:0xf bank_mask:0xf
	v_add_f32_dpp v70, v254, v254 quad_perm:[1,0,3,2] row_mask:0xf bank_mask:0xf
	v_add_f32_dpp v71, v255, v255 quad_perm:[1,0,3,2] row_mask:0xf bank_mask:0xf
	v_cndmask_b32_e32 v68, v70, v68, vcc
	v_cndmask_b32_e32 v69, v71, v69, vcc
	v_add_f32_dpp v74, v72, v72 quad_perm:[2,3,0,1] row_mask:0xf bank_mask:0xf
	v_add_f32_dpp v75, v73, v73 quad_perm:[2,3,0,1] row_mask:0xf bank_mask:0xf
	v_cndmask_b32_e64 v72, v75, v74, s[4:5]
	v_cndmask_b32_e64 v77, v72, v76, s[6:7]
	v_cndmask_b32_e64 v78, v76, v72, s[6:7]
	s_waitcnt vmcnt(15)
	v_pk_mul_f32 v[252:253], v[236:237], v[60:61] op_sel_hi:[1,0]
	v_pk_mul_f32 v[254:255], v[244:245], v[60:61] op_sel_hi:[1,0]
	v_pk_fma_f32 v[252:253], v[238:239], v[60:61], v[252:253] op_sel:[0,1,0]
	v_pk_fma_f32 v[254:255], v[246:247], v[60:61], v[254:255] op_sel:[0,1,0]
	v_pk_fma_f32 v[252:253], v[240:241], v[62:63], v[252:253] op_sel_hi:[1,0,1]
	v_pk_fma_f32 v[254:255], v[248:249], v[62:63], v[254:255] op_sel_hi:[1,0,1]
	v_pk_fma_f32 v[252:253], v[242:243], v[62:63], v[252:253] op_sel:[0,1,0]
	v_pk_fma_f32 v[254:255], v[250:251], v[62:63], v[254:255] op_sel:[0,1,0]
	v_add_f32_dpp v76, v78, v77 row_ror:4 row_mask:0xf bank_mask:0xf
	v_add_f32_dpp v64, v140, v140 quad_perm:[1,0,3,2] row_mask:0xf bank_mask:0xf
	v_add_f32_dpp v65, v141, v141 quad_perm:[1,0,3,2] row_mask:0xf bank_mask:0xf
	v_add_f32_dpp v66, v142, v142 quad_perm:[1,0,3,2] row_mask:0xf bank_mask:0xf
	v_add_f32_dpp v67, v143, v143 quad_perm:[1,0,3,2] row_mask:0xf bank_mask:0xf
	v_cndmask_b32_e32 v64, v66, v64, vcc
	v_cndmask_b32_e32 v65, v67, v65, vcc
	v_add_f32_dpp v70, v68, v68 quad_perm:[2,3,0,1] row_mask:0xf bank_mask:0xf
	v_add_f32_dpp v71, v69, v69 quad_perm:[2,3,0,1] row_mask:0xf bank_mask:0xf
	v_cndmask_b32_e64 v68, v71, v70, s[4:5]
	s_waitcnt vmcnt(14)
	v_pk_mul_f32 v[140:141], v[236:237], v[56:57] op_sel_hi:[1,0]
	v_pk_mul_f32 v[142:143], v[244:245], v[56:57] op_sel_hi:[1,0]
	v_pk_fma_f32 v[140:141], v[238:239], v[56:57], v[140:141] op_sel:[0,1,0]
	v_pk_fma_f32 v[142:143], v[246:247], v[56:57], v[142:143] op_sel:[0,1,0]
	v_pk_fma_f32 v[140:141], v[240:241], v[58:59], v[140:141] op_sel_hi:[1,0,1]
	v_pk_fma_f32 v[142:143], v[248:249], v[58:59], v[142:143] op_sel_hi:[1,0,1]
	v_pk_fma_f32 v[140:141], v[242:243], v[58:59], v[140:141] op_sel:[0,1,0]
	v_pk_fma_f32 v[142:143], v[250:251], v[58:59], v[142:143] op_sel:[0,1,0]
	v_add_f32_dpp v60, v252, v252 quad_perm:[1,0,3,2] row_mask:0xf bank_mask:0xf
	v_add_f32_dpp v61, v253, v253 quad_perm:[1,0,3,2] row_mask:0xf bank_mask:0xf
	v_add_f32_dpp v62, v254, v254 quad_perm:[1,0,3,2] row_mask:0xf bank_mask:0xf
	v_add_f32_dpp v63, v255, v255 quad_perm:[1,0,3,2] row_mask:0xf bank_mask:0xf
	v_cndmask_b32_e32 v60, v62, v60, vcc
	v_cndmask_b32_e32 v61, v63, v61, vcc
	v_add_f32_dpp v66, v64, v64 quad_perm:[2,3,0,1] row_mask:0xf bank_mask:0xf
	v_add_f32_dpp v67, v65, v65 quad_perm:[2,3,0,1] row_mask:0xf bank_mask:0xf
	v_cndmask_b32_e64 v64, v67, v66, s[4:5]
	v_cndmask_b32_e64 v69, v64, v68, s[6:7]
	v_cndmask_b32_e64 v70, v68, v64, s[6:7]
	s_waitcnt vmcnt(13)
	v_pk_mul_f32 v[252:253], v[236:237], v[52:53] op_sel_hi:[1,0]
	v_pk_mul_f32 v[254:255], v[244:245], v[52:53] op_sel_hi:[1,0]
	v_pk_fma_f32 v[252:253], v[238:239], v[52:53], v[252:253] op_sel:[0,1,0]
	v_pk_fma_f32 v[254:255], v[246:247], v[52:53], v[254:255] op_sel:[0,1,0]
	v_pk_fma_f32 v[252:253], v[240:241], v[54:55], v[252:253] op_sel_hi:[1,0,1]
	v_pk_fma_f32 v[254:255], v[248:249], v[54:55], v[254:255] op_sel_hi:[1,0,1]
	v_pk_fma_f32 v[252:253], v[242:243], v[54:55], v[252:253] op_sel:[0,1,0]
	v_pk_fma_f32 v[254:255], v[250:251], v[54:55], v[254:255] op_sel:[0,1,0]
	v_add_f32_dpp v68, v70, v69 row_ror:4 row_mask:0xf bank_mask:0xf
	v_cndmask_b32_e64 v77, v68, v76, s[64:65]
	v_cndmask_b32_e64 v78, v76, v68, s[64:65]
	v_add_f32_dpp v56, v140, v140 quad_perm:[1,0,3,2] row_mask:0xf bank_mask:0xf
	v_add_f32_dpp v57, v141, v141 quad_perm:[1,0,3,2] row_mask:0xf bank_mask:0xf
	v_add_f32_dpp v58, v142, v142 quad_perm:[1,0,3,2] row_mask:0xf bank_mask:0xf
	v_add_f32_dpp v59, v143, v143 quad_perm:[1,0,3,2] row_mask:0xf bank_mask:0xf
	v_cndmask_b32_e32 v56, v58, v56, vcc
	v_cndmask_b32_e32 v57, v59, v57, vcc
	v_add_f32_dpp v62, v60, v60 quad_perm:[2,3,0,1] row_mask:0xf bank_mask:0xf
	v_add_f32_dpp v63, v61, v61 quad_perm:[2,3,0,1] row_mask:0xf bank_mask:0xf
	v_cndmask_b32_e64 v60, v63, v62, s[4:5]
	s_waitcnt vmcnt(12)
	v_pk_mul_f32 v[140:141], v[236:237], v[48:49] op_sel_hi:[1,0]
	v_pk_mul_f32 v[142:143], v[244:245], v[48:49] op_sel_hi:[1,0]
	v_pk_fma_f32 v[140:141], v[238:239], v[48:49], v[140:141] op_sel:[0,1,0]
	v_pk_fma_f32 v[142:143], v[246:247], v[48:49], v[142:143] op_sel:[0,1,0]
	v_pk_fma_f32 v[140:141], v[240:241], v[50:51], v[140:141] op_sel_hi:[1,0,1]
	v_pk_fma_f32 v[142:143], v[248:249], v[50:51], v[142:143] op_sel_hi:[1,0,1]
	v_pk_fma_f32 v[140:141], v[242:243], v[50:51], v[140:141] op_sel:[0,1,0]
	v_pk_fma_f32 v[142:143], v[250:251], v[50:51], v[142:143] op_sel:[0,1,0]
	v_add_f32_dpp v76, v78, v77 row_ror:8 row_mask:0xf bank_mask:0xf
	v_add_f32_dpp v52, v252, v252 quad_perm:[1,0,3,2] row_mask:0xf bank_mask:0xf
	v_add_f32_dpp v53, v253, v253 quad_perm:[1,0,3,2] row_mask:0xf bank_mask:0xf
	v_add_f32_dpp v54, v254, v254 quad_perm:[1,0,3,2] row_mask:0xf bank_mask:0xf
	v_add_f32_dpp v55, v255, v255 quad_perm:[1,0,3,2] row_mask:0xf bank_mask:0xf
	v_cndmask_b32_e32 v52, v54, v52, vcc
	v_cndmask_b32_e32 v53, v55, v53, vcc
	v_add_f32_dpp v58, v56, v56 quad_perm:[2,3,0,1] row_mask:0xf bank_mask:0xf
	v_add_f32_dpp v59, v57, v57 quad_perm:[2,3,0,1] row_mask:0xf bank_mask:0xf
	v_cndmask_b32_e64 v56, v59, v58, s[4:5]
	v_cndmask_b32_e64 v61, v56, v60, s[6:7]
	v_cndmask_b32_e64 v62, v60, v56, s[6:7]
	s_waitcnt vmcnt(11)
	v_pk_mul_f32 v[252:253], v[236:237], v[44:45] op_sel_hi:[1,0]
	v_pk_mul_f32 v[254:255], v[244:245], v[44:45] op_sel_hi:[1,0]
	v_pk_fma_f32 v[252:253], v[238:239], v[44:45], v[252:253] op_sel:[0,1,0]
	v_pk_fma_f32 v[254:255], v[246:247], v[44:45], v[254:255] op_sel:[0,1,0]
	v_pk_fma_f32 v[252:253], v[240:241], v[46:47], v[252:253] op_sel_hi:[1,0,1]
	v_pk_fma_f32 v[254:255], v[248:249], v[46:47], v[254:255] op_sel_hi:[1,0,1]
	v_pk_fma_f32 v[252:253], v[242:243], v[46:47], v[252:253] op_sel:[0,1,0]
	v_pk_fma_f32 v[254:255], v[250:251], v[46:47], v[254:255] op_sel:[0,1,0]
	v_permlane16_swap_b32_e32 v92, v76
	v_add_f32_e32 v92, v92, v76
	v_add_f32_dpp v60, v62, v61 row_ror:4 row_mask:0xf bank_mask:0xf
	v_add_f32_dpp v48, v140, v140 quad_perm:[1,0,3,2] row_mask:0xf bank_mask:0xf
	v_add_f32_dpp v49, v141, v141 quad_perm:[1,0,3,2] row_mask:0xf bank_mask:0xf
	v_add_f32_dpp v50, v142, v142 quad_perm:[1,0,3,2] row_mask:0xf bank_mask:0xf
	v_add_f32_dpp v51, v143, v143 quad_perm:[1,0,3,2] row_mask:0xf bank_mask:0xf
	v_cndmask_b32_e32 v48, v50, v48, vcc
	v_cndmask_b32_e32 v49, v51, v49, vcc
	v_add_f32_dpp v54, v52, v52 quad_perm:[2,3,0,1] row_mask:0xf bank_mask:0xf
	v_add_f32_dpp v55, v53, v53 quad_perm:[2,3,0,1] row_mask:0xf bank_mask:0xf
	v_cndmask_b32_e64 v52, v55, v54, s[4:5]
	s_waitcnt vmcnt(10)
	v_pk_mul_f32 v[140:141], v[236:237], v[40:41] op_sel_hi:[1,0]
	v_pk_mul_f32 v[142:143], v[244:245], v[40:41] op_sel_hi:[1,0]
	v_pk_fma_f32 v[140:141], v[238:239], v[40:41], v[140:141] op_sel:[0,1,0]
	v_pk_fma_f32 v[142:143], v[246:247], v[40:41], v[142:143] op_sel:[0,1,0]
	v_pk_fma_f32 v[140:141], v[240:241], v[42:43], v[140:141] op_sel_hi:[1,0,1]
	v_pk_fma_f32 v[142:143], v[248:249], v[42:43], v[142:143] op_sel_hi:[1,0,1]
	v_pk_fma_f32 v[140:141], v[242:243], v[42:43], v[140:141] op_sel:[0,1,0]
	v_pk_fma_f32 v[142:143], v[250:251], v[42:43], v[142:143] op_sel:[0,1,0]
	v_permlane32_swap_b32_e32 v124, v92
	v_add_f32_e32 v124, v124, v92
	ds_write_b32 v235, v124
	v_add_f32_dpp v44, v252, v252 quad_perm:[1,0,3,2] row_mask:0xf bank_mask:0xf
	v_add_f32_dpp v45, v253, v253 quad_perm:[1,0,3,2] row_mask:0xf bank_mask:0xf
	v_add_f32_dpp v46, v254, v254 quad_perm:[1,0,3,2] row_mask:0xf bank_mask:0xf
	v_add_f32_dpp v47, v255, v255 quad_perm:[1,0,3,2] row_mask:0xf bank_mask:0xf
	v_cndmask_b32_e32 v44, v46, v44, vcc
	v_cndmask_b32_e32 v45, v47, v45, vcc
	v_add_f32_dpp v50, v48, v48 quad_perm:[2,3,0,1] row_mask:0xf bank_mask:0xf
	v_add_f32_dpp v51, v49, v49 quad_perm:[2,3,0,1] row_mask:0xf bank_mask:0xf
	v_cndmask_b32_e64 v48, v51, v50, s[4:5]
	v_cndmask_b32_e64 v53, v48, v52, s[6:7]
	v_cndmask_b32_e64 v54, v52, v48, s[6:7]
	s_waitcnt vmcnt(9)
	v_pk_mul_f32 v[252:253], v[236:237], v[36:37] op_sel_hi:[1,0]
	v_pk_mul_f32 v[254:255], v[244:245], v[36:37] op_sel_hi:[1,0]
	v_pk_fma_f32 v[252:253], v[238:239], v[36:37], v[252:253] op_sel:[0,1,0]
	v_pk_fma_f32 v[254:255], v[246:247], v[36:37], v[254:255] op_sel:[0,1,0]
	v_pk_fma_f32 v[252:253], v[240:241], v[38:39], v[252:253] op_sel_hi:[1,0,1]
	v_pk_fma_f32 v[254:255], v[248:249], v[38:39], v[254:255] op_sel_hi:[1,0,1]
	v_pk_fma_f32 v[252:253], v[242:243], v[38:39], v[252:253] op_sel:[0,1,0]
	v_pk_fma_f32 v[254:255], v[250:251], v[38:39], v[254:255] op_sel:[0,1,0]
	v_add_f32_dpp v52, v54, v53 row_ror:4 row_mask:0xf bank_mask:0xf
	v_cndmask_b32_e64 v61, v52, v60, s[64:65]
	v_cndmask_b32_e64 v62, v60, v52, s[64:65]
	v_add_f32_dpp v40, v140, v140 quad_perm:[1,0,3,2] row_mask:0xf bank_mask:0xf
	v_add_f32_dpp v41, v141, v141 quad_perm:[1,0,3,2] row_mask:0xf bank_mask:0xf
	v_add_f32_dpp v42, v142, v142 quad_perm:[1,0,3,2] row_mask:0xf bank_mask:0xf
	v_add_f32_dpp v43, v143, v143 quad_perm:[1,0,3,2] row_mask:0xf bank_mask:0xf
	v_cndmask_b32_e32 v40, v42, v40, vcc
	v_cndmask_b32_e32 v41, v43, v41, vcc
	v_add_f32_dpp v46, v44, v44 quad_perm:[2,3,0,1] row_mask:0xf bank_mask:0xf
	v_add_f32_dpp v47, v45, v45 quad_perm:[2,3,0,1] row_mask:0xf bank_mask:0xf
	v_cndmask_b32_e64 v44, v47, v46, s[4:5]
	s_waitcnt vmcnt(8)
	v_pk_mul_f32 v[140:141], v[236:237], v[32:33] op_sel_hi:[1,0]
	v_pk_mul_f32 v[142:143], v[244:245], v[32:33] op_sel_hi:[1,0]
	v_pk_fma_f32 v[140:141], v[238:239], v[32:33], v[140:141] op_sel:[0,1,0]
	v_pk_fma_f32 v[142:143], v[246:247], v[32:33], v[142:143] op_sel:[0,1,0]
	v_pk_fma_f32 v[140:141], v[240:241], v[34:35], v[140:141] op_sel_hi:[1,0,1]
	v_pk_fma_f32 v[142:143], v[248:249], v[34:35], v[142:143] op_sel_hi:[1,0,1]
	v_pk_fma_f32 v[140:141], v[242:243], v[34:35], v[140:141] op_sel:[0,1,0]
	v_pk_fma_f32 v[142:143], v[250:251], v[34:35], v[142:143] op_sel:[0,1,0]
	v_add_f32_dpp v60, v62, v61 row_ror:8 row_mask:0xf bank_mask:0xf
	v_add_f32_dpp v36, v252, v252 quad_perm:[1,0,3,2] row_mask:0xf bank_mask:0xf
	v_add_f32_dpp v37, v253, v253 quad_perm:[1,0,3,2] row_mask:0xf bank_mask:0xf
	v_add_f32_dpp v38, v254, v254 quad_perm:[1,0,3,2] row_mask:0xf bank_mask:0xf
	v_add_f32_dpp v39, v255, v255 quad_perm:[1,0,3,2] row_mask:0xf bank_mask:0xf
	v_cndmask_b32_e32 v36, v38, v36, vcc
	v_cndmask_b32_e32 v37, v39, v37, vcc
	v_add_f32_dpp v42, v40, v40 quad_perm:[2,3,0,1] row_mask:0xf bank_mask:0xf
	v_add_f32_dpp v43, v41, v41 quad_perm:[2,3,0,1] row_mask:0xf bank_mask:0xf
	v_cndmask_b32_e64 v40, v43, v42, s[4:5]
	v_cndmask_b32_e64 v45, v40, v44, s[6:7]
	v_cndmask_b32_e64 v46, v44, v40, s[6:7]
	s_waitcnt vmcnt(7)
	v_pk_mul_f32 v[252:253], v[236:237], v[28:29] op_sel_hi:[1,0]
	v_pk_mul_f32 v[254:255], v[244:245], v[28:29] op_sel_hi:[1,0]
	v_pk_fma_f32 v[252:253], v[238:239], v[28:29], v[252:253] op_sel:[0,1,0]
	v_pk_fma_f32 v[254:255], v[246:247], v[28:29], v[254:255] op_sel:[0,1,0]
	v_pk_fma_f32 v[252:253], v[240:241], v[30:31], v[252:253] op_sel_hi:[1,0,1]
	v_pk_fma_f32 v[254:255], v[248:249], v[30:31], v[254:255] op_sel_hi:[1,0,1]
	v_pk_fma_f32 v[252:253], v[242:243], v[30:31], v[252:253] op_sel:[0,1,0]
	v_pk_fma_f32 v[254:255], v[250:251], v[30:31], v[254:255] op_sel:[0,1,0]
	v_add_f32_dpp v44, v46, v45 row_ror:4 row_mask:0xf bank_mask:0xf
	v_add_f32_dpp v32, v140, v140 quad_perm:[1,0,3,2] row_mask:0xf bank_mask:0xf
	v_add_f32_dpp v33, v141, v141 quad_perm:[1,0,3,2] row_mask:0xf bank_mask:0xf
	v_add_f32_dpp v34, v142, v142 quad_perm:[1,0,3,2] row_mask:0xf bank_mask:0xf
	v_add_f32_dpp v35, v143, v143 quad_perm:[1,0,3,2] row_mask:0xf bank_mask:0xf
	v_cndmask_b32_e32 v32, v34, v32, vcc
	v_cndmask_b32_e32 v33, v35, v33, vcc
	v_add_f32_dpp v38, v36, v36 quad_perm:[2,3,0,1] row_mask:0xf bank_mask:0xf
	v_add_f32_dpp v39, v37, v37 quad_perm:[2,3,0,1] row_mask:0xf bank_mask:0xf
	v_cndmask_b32_e64 v36, v39, v38, s[4:5]
	s_waitcnt vmcnt(6)
	v_pk_mul_f32 v[140:141], v[236:237], v[24:25] op_sel_hi:[1,0]
	v_pk_mul_f32 v[142:143], v[244:245], v[24:25] op_sel_hi:[1,0]
	v_pk_fma_f32 v[140:141], v[238:239], v[24:25], v[140:141] op_sel:[0,1,0]
	v_pk_fma_f32 v[142:143], v[246:247], v[24:25], v[142:143] op_sel:[0,1,0]
	v_pk_fma_f32 v[140:141], v[240:241], v[26:27], v[140:141] op_sel_hi:[1,0,1]
	v_pk_fma_f32 v[142:143], v[248:249], v[26:27], v[142:143] op_sel_hi:[1,0,1]
	v_pk_fma_f32 v[140:141], v[242:243], v[26:27], v[140:141] op_sel:[0,1,0]
	v_pk_fma_f32 v[142:143], v[250:251], v[26:27], v[142:143] op_sel:[0,1,0]
	v_add_f32_dpp v28, v252, v252 quad_perm:[1,0,3,2] row_mask:0xf bank_mask:0xf
	v_add_f32_dpp v29, v253, v253 quad_perm:[1,0,3,2] row_mask:0xf bank_mask:0xf
	v_add_f32_dpp v30, v254, v254 quad_perm:[1,0,3,2] row_mask:0xf bank_mask:0xf
	v_add_f32_dpp v31, v255, v255 quad_perm:[1,0,3,2] row_mask:0xf bank_mask:0xf
	v_cndmask_b32_e32 v28, v30, v28, vcc
	v_cndmask_b32_e32 v29, v31, v29, vcc
	v_add_f32_dpp v34, v32, v32 quad_perm:[2,3,0,1] row_mask:0xf bank_mask:0xf
	v_add_f32_dpp v35, v33, v33 quad_perm:[2,3,0,1] row_mask:0xf bank_mask:0xf
	v_cndmask_b32_e64 v32, v35, v34, s[4:5]
	v_cndmask_b32_e64 v37, v32, v36, s[6:7]
	v_cndmask_b32_e64 v38, v36, v32, s[6:7]
	s_waitcnt vmcnt(5)
	v_pk_mul_f32 v[252:253], v[236:237], v[20:21] op_sel_hi:[1,0]
	v_pk_mul_f32 v[254:255], v[244:245], v[20:21] op_sel_hi:[1,0]
	v_pk_fma_f32 v[252:253], v[238:239], v[20:21], v[252:253] op_sel:[0,1,0]
	v_pk_fma_f32 v[254:255], v[246:247], v[20:21], v[254:255] op_sel:[0,1,0]
	v_pk_fma_f32 v[252:253], v[240:241], v[22:23], v[252:253] op_sel_hi:[1,0,1]
	v_pk_fma_f32 v[254:255], v[248:249], v[22:23], v[254:255] op_sel_hi:[1,0,1]
	v_pk_fma_f32 v[252:253], v[242:243], v[22:23], v[252:253] op_sel:[0,1,0]
	v_pk_fma_f32 v[254:255], v[250:251], v[22:23], v[254:255] op_sel:[0,1,0]
	v_add_f32_dpp v36, v38, v37 row_ror:4 row_mask:0xf bank_mask:0xf
	v_cndmask_b32_e64 v45, v36, v44, s[64:65]
	v_cndmask_b32_e64 v46, v44, v36, s[64:65]
	v_add_f32_dpp v24, v140, v140 quad_perm:[1,0,3,2] row_mask:0xf bank_mask:0xf
	v_add_f32_dpp v25, v141, v141 quad_perm:[1,0,3,2] row_mask:0xf bank_mask:0xf
	v_add_f32_dpp v26, v142, v142 quad_perm:[1,0,3,2] row_mask:0xf bank_mask:0xf
	v_add_f32_dpp v27, v143, v143 quad_perm:[1,0,3,2] row_mask:0xf bank_mask:0xf
	v_cndmask_b32_e32 v24, v26, v24, vcc
	v_cndmask_b32_e32 v25, v27, v25, vcc
	v_add_f32_dpp v30, v28, v28 quad_perm:[2,3,0,1] row_mask:0xf bank_mask:0xf
	v_add_f32_dpp v31, v29, v29 quad_perm:[2,3,0,1] row_mask:0xf bank_mask:0xf
	v_cndmask_b32_e64 v28, v31, v30, s[4:5]
	s_waitcnt vmcnt(4)
	v_pk_mul_f32 v[140:141], v[236:237], v[16:17] op_sel_hi:[1,0]
	v_pk_mul_f32 v[142:143], v[244:245], v[16:17] op_sel_hi:[1,0]
	v_pk_fma_f32 v[140:141], v[238:239], v[16:17], v[140:141] op_sel:[0,1,0]
	v_pk_fma_f32 v[142:143], v[246:247], v[16:17], v[142:143] op_sel:[0,1,0]
	v_pk_fma_f32 v[140:141], v[240:241], v[18:19], v[140:141] op_sel_hi:[1,0,1]
	v_pk_fma_f32 v[142:143], v[248:249], v[18:19], v[142:143] op_sel_hi:[1,0,1]
	v_pk_fma_f32 v[140:141], v[242:243], v[18:19], v[140:141] op_sel:[0,1,0]
	v_pk_fma_f32 v[142:143], v[250:251], v[18:19], v[142:143] op_sel:[0,1,0]
	v_add_f32_dpp v44, v46, v45 row_ror:8 row_mask:0xf bank_mask:0xf
	v_add_f32_dpp v20, v252, v252 quad_perm:[1,0,3,2] row_mask:0xf bank_mask:0xf
	v_add_f32_dpp v21, v253, v253 quad_perm:[1,0,3,2] row_mask:0xf bank_mask:0xf
	v_add_f32_dpp v22, v254, v254 quad_perm:[1,0,3,2] row_mask:0xf bank_mask:0xf
	v_add_f32_dpp v23, v255, v255 quad_perm:[1,0,3,2] row_mask:0xf bank_mask:0xf
	v_cndmask_b32_e32 v20, v22, v20, vcc
	v_cndmask_b32_e32 v21, v23, v21, vcc
	v_add_f32_dpp v26, v24, v24 quad_perm:[2,3,0,1] row_mask:0xf bank_mask:0xf
	v_add_f32_dpp v27, v25, v25 quad_perm:[2,3,0,1] row_mask:0xf bank_mask:0xf
	v_cndmask_b32_e64 v24, v27, v26, s[4:5]
	v_cndmask_b32_e64 v29, v24, v28, s[6:7]
	v_cndmask_b32_e64 v30, v28, v24, s[6:7]
	s_waitcnt vmcnt(3)
; DI void attn_sample_item(const Params& p, int item, ldsp lds, int tid_) {
;     ...
;   SC_SCORE(kvA, 0)
;   SC_SCORE(kvB, 1)
;     ...
;   f32x4 vvA[16], vvB[16];
; #pragma unroll
;   for (int j = 0; j < 16; ++j) vvA[j] = __builtin_nontemporal_load((const f32x4*)(cv + (size_t)(wid * 32 + j) * 1024 + lane * 4));
	v_pk_mul_f32 v[252:253], v[236:237], v[12:13] op_sel_hi:[1,0]
	v_pk_mul_f32 v[254:255], v[244:245], v[12:13] op_sel_hi:[1,0]
	v_pk_fma_f32 v[252:253], v[238:239], v[12:13], v[252:253] op_sel:[0,1,0]
	v_pk_fma_f32 v[254:255], v[246:247], v[12:13], v[254:255] op_sel:[0,1,0]
	v_pk_fma_f32 v[252:253], v[240:241], v[14:15], v[252:253] op_sel_hi:[1,0,1]
	v_pk_fma_f32 v[254:255], v[248:249], v[14:15], v[254:255] op_sel_hi:[1,0,1]
	v_pk_fma_f32 v[252:253], v[242:243], v[14:15], v[252:253] op_sel:[0,1,0]
	v_pk_fma_f32 v[254:255], v[250:251], v[14:15], v[254:255] op_sel:[0,1,0]
	v_permlane16_swap_b32_e32 v60, v44
	v_add_f32_e32 v60, v60, v44
	v_add_f32_dpp v28, v30, v29 row_ror:4 row_mask:0xf bank_mask:0xf
	v_add_f32_dpp v16, v140, v140 quad_perm:[1,0,3,2] row_mask:0xf bank_mask:0xf
	v_add_f32_dpp v17, v141, v141 quad_perm:[1,0,3,2] row_mask:0xf bank_mask:0xf
	v_add_f32_dpp v18, v142, v142 quad_perm:[1,0,3,2] row_mask:0xf bank_mask:0xf
	v_add_f32_dpp v19, v143, v143 quad_perm:[1,0,3,2] row_mask:0xf bank_mask:0xf
	v_cndmask_b32_e32 v16, v18, v16, vcc
	v_cndmask_b32_e32 v17, v19, v17, vcc
	v_add_f32_dpp v22, v20, v20 quad_perm:[2,3,0,1] row_mask:0xf bank_mask:0xf
	v_add_f32_dpp v23, v21, v21 quad_perm:[2,3,0,1] row_mask:0xf bank_mask:0xf
	v_cndmask_b32_e64 v20, v23, v22, s[4:5]
	s_waitcnt vmcnt(2)
	v_pk_mul_f32 v[140:141], v[236:237], v[8:9] op_sel_hi:[1,0]
	v_pk_mul_f32 v[142:143], v[244:245], v[8:9] op_sel_hi:[1,0]
	v_pk_fma_f32 v[140:141], v[238:239], v[8:9], v[140:141] op_sel:[0,1,0]
	v_pk_fma_f32 v[142:143], v[246:247], v[8:9], v[142:143] op_sel:[0,1,0]
	v_pk_fma_f32 v[140:141], v[240:241], v[10:11], v[140:141] op_sel_hi:[1,0,1]
	v_pk_fma_f32 v[142:143], v[248:249], v[10:11], v[142:143] op_sel_hi:[1,0,1]
	v_pk_fma_f32 v[140:141], v[242:243], v[10:11], v[140:141] op_sel:[0,1,0]
	v_pk_fma_f32 v[142:143], v[250:251], v[10:11], v[142:143] op_sel:[0,1,0]
	v_add_f32_dpp v12, v252, v252 quad_perm:[1,0,3,2] row_mask:0xf bank_mask:0xf
	v_add_f32_dpp v13, v253, v253 quad_perm:[1,0,3,2] row_mask:0xf bank_mask:0xf
	v_add_f32_dpp v14, v254, v254 quad_perm:[1,0,3,2] row_mask:0xf bank_mask:0xf
	v_add_f32_dpp v15, v255, v255 quad_perm:[1,0,3,2] row_mask:0xf bank_mask:0xf
	v_cndmask_b32_e32 v12, v14, v12, vcc
	v_cndmask_b32_e32 v13, v15, v13, vcc
	v_add_f32_dpp v18, v16, v16 quad_perm:[2,3,0,1] row_mask:0xf bank_mask:0xf
	v_add_f32_dpp v19, v17, v17 quad_perm:[2,3,0,1] row_mask:0xf bank_mask:0xf
	v_cndmask_b32_e64 v16, v19, v18, s[4:5]
	v_cndmask_b32_e64 v21, v16, v20, s[6:7]
	v_cndmask_b32_e64 v22, v20, v16, s[6:7]
	s_waitcnt vmcnt(1)
	v_pk_mul_f32 v[252:253], v[236:237], v[4:5] op_sel_hi:[1,0]
	v_pk_mul_f32 v[254:255], v[244:245], v[4:5] op_sel_hi:[1,0]
	v_pk_fma_f32 v[252:253], v[238:239], v[4:5], v[252:253] op_sel:[0,1,0]
	v_pk_fma_f32 v[254:255], v[246:247], v[4:5], v[254:255] op_sel:[0,1,0]
	v_pk_fma_f32 v[252:253], v[240:241], v[6:7], v[252:253] op_sel_hi:[1,0,1]
	v_pk_fma_f32 v[254:255], v[248:249], v[6:7], v[254:255] op_sel_hi:[1,0,1]
	v_pk_fma_f32 v[252:253], v[242:243], v[6:7], v[252:253] op_sel:[0,1,0]
	v_pk_fma_f32 v[254:255], v[250:251], v[6:7], v[254:255] op_sel:[0,1,0]
	v_add_f32_dpp v20, v22, v21 row_ror:4 row_mask:0xf bank_mask:0xf
	v_cndmask_b32_e64 v29, v20, v28, s[64:65]
	v_cndmask_b32_e64 v30, v28, v20, s[64:65]
	v_add_f32_dpp v8, v140, v140 quad_perm:[1,0,3,2] row_mask:0xf bank_mask:0xf
	v_add_f32_dpp v9, v141, v141 quad_perm:[1,0,3,2] row_mask:0xf bank_mask:0xf
	v_add_f32_dpp v10, v142, v142 quad_perm:[1,0,3,2] row_mask:0xf bank_mask:0xf
	v_add_f32_dpp v11, v143, v143 quad_perm:[1,0,3,2] row_mask:0xf bank_mask:0xf
	v_cndmask_b32_e32 v8, v10, v8, vcc
	v_cndmask_b32_e32 v9, v11, v9, vcc
	v_add_f32_dpp v14, v12, v12 quad_perm:[2,3,0,1] row_mask:0xf bank_mask:0xf
	v_add_f32_dpp v15, v13, v13 quad_perm:[2,3,0,1] row_mask:0xf bank_mask:0xf
	v_cndmask_b32_e64 v12, v15, v14, s[4:5]
	s_waitcnt vmcnt(0)
	v_pk_mul_f32 v[140:141], v[236:237], v[0:1] op_sel_hi:[1,0]
	v_pk_mul_f32 v[142:143], v[244:245], v[0:1] op_sel_hi:[1,0]
	v_pk_fma_f32 v[140:141], v[238:239], v[0:1], v[140:141] op_sel:[0,1,0]
	v_pk_fma_f32 v[142:143], v[246:247], v[0:1], v[142:143] op_sel:[0,1,0]
	v_pk_fma_f32 v[140:141], v[240:241], v[2:3], v[140:141] op_sel_hi:[1,0,1]
	v_pk_fma_f32 v[142:143], v[248:249], v[2:3], v[142:143] op_sel_hi:[1,0,1]
	v_pk_fma_f32 v[140:141], v[242:243], v[2:3], v[140:141] op_sel:[0,1,0]
	v_pk_fma_f32 v[142:143], v[250:251], v[2:3], v[142:143] op_sel:[0,1,0]
	v_add_f32_dpp v28, v30, v29 row_ror:8 row_mask:0xf bank_mask:0xf
	v_add_f32_dpp v4, v252, v252 quad_perm:[1,0,3,2] row_mask:0xf bank_mask:0xf
	v_add_f32_dpp v5, v253, v253 quad_perm:[1,0,3,2] row_mask:0xf bank_mask:0xf
	v_add_f32_dpp v6, v254, v254 quad_perm:[1,0,3,2] row_mask:0xf bank_mask:0xf
	v_add_f32_dpp v7, v255, v255 quad_perm:[1,0,3,2] row_mask:0xf bank_mask:0xf
	v_cndmask_b32_e32 v4, v6, v4, vcc
	v_cndmask_b32_e32 v5, v7, v5, vcc
	v_add_f32_dpp v10, v8, v8 quad_perm:[2,3,0,1] row_mask:0xf bank_mask:0xf
	v_add_f32_dpp v11, v9, v9 quad_perm:[2,3,0,1] row_mask:0xf bank_mask:0xf
	v_cndmask_b32_e64 v8, v11, v10, s[4:5]
	v_cndmask_b32_e64 v13, v8, v12, s[6:7]
	v_cndmask_b32_e64 v14, v12, v8, s[6:7]
	s_nop 1
	v_add_f32_dpp v12, v14, v13 row_ror:4 row_mask:0xf bank_mask:0xf
	v_add_f32_dpp v0, v140, v140 quad_perm:[1,0,3,2] row_mask:0xf bank_mask:0xf
	v_add_f32_dpp v1, v141, v141 quad_perm:[1,0,3,2] row_mask:0xf bank_mask:0xf
	v_add_f32_dpp v2, v142, v142 quad_perm:[1,0,3,2] row_mask:0xf bank_mask:0xf
	v_add_f32_dpp v3, v143, v143 quad_perm:[1,0,3,2] row_mask:0xf bank_mask:0xf
	v_cndmask_b32_e32 v0, v2, v0, vcc
	v_cndmask_b32_e32 v1, v3, v1, vcc
	v_add_f32_dpp v6, v4, v4 quad_perm:[2,3,0,1] row_mask:0xf bank_mask:0xf
	v_add_f32_dpp v7, v5, v5 quad_perm:[2,3,0,1] row_mask:0xf bank_mask:0xf
	v_cndmask_b32_e64 v4, v7, v6, s[4:5]
	v_add_f32_dpp v2, v0, v0 quad_perm:[2,3,0,1] row_mask:0xf bank_mask:0xf
	v_add_f32_dpp v3, v1, v1 quad_perm:[2,3,0,1] row_mask:0xf bank_mask:0xf
	v_cndmask_b32_e64 v0, v3, v2, s[4:5]
	v_cndmask_b32_e64 v5, v0, v4, s[6:7]
	v_cndmask_b32_e64 v6, v4, v0, s[6:7]
	s_nop 1
	v_add_f32_dpp v4, v6, v5 row_ror:4 row_mask:0xf bank_mask:0xf
	v_cndmask_b32_e64 v13, v4, v12, s[64:65]
	v_cndmask_b32_e64 v14, v12, v4, s[64:65]
	s_nop 1
	v_add_f32_dpp v12, v14, v13 row_ror:8 row_mask:0xf bank_mask:0xf
	s_nop 1
	v_permlane16_swap_b32_e32 v28, v12
	v_add_f32_e32 v28, v28, v12
	s_nop 1
	v_permlane32_swap_b32_e32 v60, v28
	v_add_f32_e32 v60, v60, v28
	ds_write_b32 v235, v60 offset:64
	v_lshlrev_b32_e32 v2, 2, v223
	s_add_u32 s4, s14, s30
	s_addc_u32 s5, s15, s31
	v_lshlrev_b32_e32 v0, 2, v2
	s_waitcnt lgkmcnt(0)
; DI void lbar() { asm volatile("s_waitcnt lgkmcnt(0)" ::: "memory"); __builtin_amdgcn_s_barrier(); asm volatile("" ::: "memory"); }
; DI float wave_sum(float v) { for (int o = 32; o >= 1; o >>= 1) v += __shfl_xor(v, o); return v; }
; DI void attn_sample_item(const Params& p, int item, ldsp lds, int tid_) {
;     ...
;   for (int j = 0; j < 16; ++j) vvA[j] = __builtin_nontemporal_load((const f32x4*)(cv + (size_t)(wid * 32 + j) * 1024 + lane * 4));
;   lbar();
;   if (wid < 4) {
;     float v[4]; float mx = -1e30f;
; #pragma unroll
;     for (int j = 0; j < 4; ++j) { v[j] = SC[wid * 256 + j * 64 + lane]; mx = fmaxf(mx, v[j]); }
;     for (int o = 32; o >= 1; o >>= 1) mx = fmaxf(mx, __shfl_xor(mx, o));
;     float s = 0.f;
; #pragma unroll
;     for (int j = 0; j < 4; ++j) { v[j] = __expf(v[j] - mx); s += v[j]; }
;     s = wave_sum(s); const float inv = 1.f / s;
; #pragma unroll
;     for (int j = 0; j < 4; ++j) SC[wid * 256 + j * 64 + lane] = v[j] * inv;
	v_mov_b32_e32 v1, v145
	v_lshl_add_u64 v[0:1], s[4:5], 0, v[0:1]
	v_lshl_add_u64 v[4:5], v[0:1], 0, v[162:163]
	v_lshl_add_u64 v[6:7], v[0:1], 0, v[166:167]
	global_load_dwordx4 v[100:103], v[4:5], off nt
	global_load_dwordx4 v[92:95], v[6:7], off nt
	v_lshl_add_u64 v[4:5], v[0:1], 0, v[168:169]
	v_lshl_add_u64 v[6:7], v[0:1], 0, v[172:173]
	global_load_dwordx4 v[112:115], v[4:5], off nt
	global_load_dwordx4 v[108:111], v[6:7], off nt
	v_lshl_add_u64 v[4:5], v[0:1], 0, v[176:177]
	v_lshl_add_u64 v[6:7], v[0:1], 0, v[180:181]
	global_load_dwordx4 v[120:123], v[4:5], off nt
	global_load_dwordx4 v[116:119], v[6:7], off nt
	v_lshl_add_u64 v[4:5], v[0:1], 0, v[182:183]
	v_lshl_add_u64 v[6:7], v[0:1], 0, v[186:187]
	global_load_dwordx4 v[124:127], v[4:5], off nt
	global_load_dwordx4 v[104:107], v[6:7], off nt
	v_lshl_add_u64 v[4:5], v[0:1], 0, v[190:191]
	v_lshl_add_u64 v[6:7], v[0:1], 0, v[194:195]
	global_load_dwordx4 v[68:71], v[4:5], off nt
	global_load_dwordx4 v[64:67], v[6:7], off nt
	v_lshl_add_u64 v[4:5], v[0:1], 0, v[198:199]
	v_lshl_add_u64 v[6:7], v[0:1], 0, v[200:201]
	global_load_dwordx4 v[80:83], v[4:5], off nt
	global_load_dwordx4 v[76:79], v[6:7], off nt
	v_lshl_add_u64 v[4:5], v[0:1], 0, v[202:203]
	v_lshl_add_u64 v[6:7], v[0:1], 0, v[204:205]
	global_load_dwordx4 v[88:91], v[4:5], off nt
	global_load_dwordx4 v[84:87], v[6:7], off nt
	v_lshl_add_u64 v[4:5], v[0:1], 0, v[206:207]
	v_lshl_add_u64 v[6:7], v[0:1], 0, v[208:209]
	global_load_dwordx4 v[96:99], v[4:5], off nt
	global_load_dwordx4 v[72:75], v[6:7], off nt
	s_waitcnt lgkmcnt(0)
	s_barrier
	v_cmp_gt_i32_e32 vcc, 4, v210
	s_and_saveexec_b64 s[4:5], vcc
	s_cbranch_execz .LBB0_1603
	v_lshlrev_b32_e32 v3, 10, v210
	v_add3_u32 v6, 16, v3, v2
	ds_read2st64_b32 v[2:3], v6 offset1:1
	ds_read2st64_b32 v[4:5], v6 offset0:2 offset1:3
	s_waitcnt lgkmcnt(1)
	v_max3_f32 v7, v2, s39, v3
	s_waitcnt lgkmcnt(0)
	v_max3_f32 v7, v7, v4, v5
	s_nop 1
	v_max_f32_dpp v7, v7, v7 quad_perm:[1,0,3,2] row_mask:0xf bank_mask:0xf
	s_nop 1
	v_max_f32_dpp v7, v7, v7 quad_perm:[2,3,0,1] row_mask:0xf bank_mask:0xf
	s_nop 1
	v_max_f32_dpp v7, v7, v7 row_ror:4 row_mask:0xf bank_mask:0xf
	s_nop 1
	v_max_f32_dpp v7, v7, v7 row_ror:8 row_mask:0xf bank_mask:0xf
	v_mov_b32_e32 v8, v7
	s_nop 1
	v_permlane16_swap_b32_e32 v7, v8
	v_max_f32_e32 v7, v7, v8
	v_mov_b32_e32 v8, v7
	s_nop 1
	v_permlane32_swap_b32_e32 v7, v8
	v_max_f32_e32 v7, v7, v8
	v_sub_f32_e32 v2, v2, v7
	v_sub_f32_e32 v3, v3, v7
	v_mul_f32_e32 v2, 0x3fb8aa3b, v2
	v_sub_f32_e32 v4, v4, v7
	v_mul_f32_e32 v3, 0x3fb8aa3b, v3
	v_exp_f32_e32 v2, v2
	v_sub_f32_e32 v5, v5, v7
	v_mul_f32_e32 v4, 0x3fb8aa3b, v4
	v_exp_f32_e32 v3, v3
	v_mul_f32_e32 v5, 0x3fb8aa3b, v5
	v_exp_f32_e32 v4, v4
	v_exp_f32_e32 v5, v5
	v_add_f32_e32 v7, 0, v2
	v_add_f32_e32 v7, v3, v7
	v_add_f32_e32 v7, v4, v7
	v_add_f32_e32 v7, v5, v7
	s_nop 1
	v_add_f32_dpp v7, v7, v7 quad_perm:[1,0,3,2] row_mask:0xf bank_mask:0xf
	s_nop 1
	v_add_f32_dpp v7, v7, v7 quad_perm:[2,3,0,1] row_mask:0xf bank_mask:0xf
	s_nop 1
	v_add_f32_dpp v7, v7, v7 row_ror:4 row_mask:0xf bank_mask:0xf
	s_nop 1
	v_add_f32_dpp v7, v7, v7 row_ror:8 row_mask:0xf bank_mask:0xf
	v_mov_b32_e32 v8, v7
	s_nop 1
	v_permlane16_swap_b32_e32 v7, v8
	v_add_f32_e32 v7, v7, v8
	v_mov_b32_e32 v8, v7
	s_nop 1
	v_permlane32_swap_b32_e32 v7, v8
	v_add_f32_e32 v7, v7, v8
	v_div_scale_f32 v8, s[6:7], v7, v7, 1.0
	v_rcp_f32_e32 v9, v8
	v_div_scale_f32 v10, vcc, 1.0, v7, 1.0
	v_fma_f32 v11, -v8, v9, 1.0
	v_fmac_f32_e32 v9, v11, v9
	v_mul_f32_e32 v11, v10, v9
	v_fma_f32 v12, -v8, v11, v10
	v_fmac_f32_e32 v11, v12, v9
	v_fma_f32 v8, -v8, v11, v10
	v_div_fmas_f32 v8, v8, v9, v11
	v_div_fixup_f32 v7, v8, v7, 1.0
	v_mul_f32_e32 v2, v2, v7
	v_mul_f32_e32 v3, v3, v7
	v_mul_f32_e32 v4, v4, v7
	v_mul_f32_e32 v5, v5, v7
	ds_write2st64_b32 v6, v2, v3 offset1:1
	ds_write2st64_b32 v6, v4, v5 offset0:2 offset1:3
	s_branch .LBB0_1603

; DI void attn_sample_item(const Params& p, int item, ldsp lds, int tid_) {
;     ...
;   for (int t = 0; t < 4; ++t) { f32x4 a = {0.f, 0.f, 0.f, 0.f}; const float* pp = (const float*)(p.ws + B_PART) + (size_t)(b * 4 + t) * 1024 + h * 256 + lane * 4;
; #pragma unroll
;     for (int kp = 0; kp < 4; ++kp) a += *(const f32x4*)(pp + (size_t)kp * 512 * 1024);
;     q[t][0] = a[0] * 0.0625f; q[t][1] = a[1] * 0.0625f; q[t][2] = a[2] * 0.0625f; q[t][3] = a[3] * 0.0625f; }
;   const bool b0 = lane & 1, b1 = lane & 2;
;   f32x4 kvA[16], kvB[16];
; #pragma unroll
;   for (int j = 0; j < 16; ++j) kvA[j] = __builtin_nontemporal_load((const f32x4*)(ck + (size_t)(wid * 32 + j) * 1024 + lane * 4));
; #pragma unroll
;   for (int j = 0; j < 16; ++j) kvB[j] = __builtin_nontemporal_load((const f32x4*)(ck + (size_t)(wid * 32 + 16 + j) * 1024 + lane * 4));
.LBB0_1676:
	s_ashr_i32 s4, s38, 2
	s_ashr_i32 s5, s4, 31
	s_lshl_b64 s[4:5], s[4:5], 18
	s_and_b32 s24, s0, 0x300
	v_mov_b32_e32 v222, v212
	s_or_b32 s4, s4, s24
	s_and_b32 s26, s38, -4
	s_lshl_b32 s6, s24, 2
	s_add_u32 s6, s36, s6
	v_and_b32_e32 v223, 63, v222
	s_addc_u32 s7, s37, 0
	v_lshlrev_b32_e32 v144, 4, v223
	s_ashr_i32 s27, s26, 31
	v_lshl_add_u64 v[48:49], s[6:7], 0, v[144:145]
	s_lshl_b64 s[6:7], s[26:27], 12
	v_lshl_add_u64 v[8:9], v[48:49], 0, s[6:7]
	v_add_co_u32_e32 v10, vcc, s3, v8
	s_or_b32 s6, s26, 1
	s_nop 0
	v_addc_co_u32_e32 v11, vcc, 0, v9, vcc
	global_load_dwordx4 v[0:3], v[8:9], off
	global_load_dwordx4 v[4:7], v[10:11], off
	v_add_co_u32_e32 v10, vcc, s33, v8
	s_ashr_i32 s7, s6, 31
	s_nop 0
	v_addc_co_u32_e32 v11, vcc, 0, v9, vcc
	v_add_co_u32_e32 v12, vcc, s34, v8
	s_lshl_b64 s[6:7], s[6:7], 12
	s_nop 0
	v_addc_co_u32_e32 v13, vcc, 0, v9, vcc
	v_lshl_add_u64 v[24:25], v[48:49], 0, s[6:7]
	v_add_co_u32_e32 v20, vcc, s3, v24
	s_or_b32 s6, s26, 2
	s_nop 0
	v_addc_co_u32_e32 v21, vcc, 0, v25, vcc
	v_add_co_u32_e32 v26, vcc, s33, v24
	s_ashr_i32 s7, s6, 31
	s_nop 0
	v_addc_co_u32_e32 v27, vcc, 0, v25, vcc
	v_add_co_u32_e32 v28, vcc, s34, v24
	s_lshl_b64 s[6:7], s[6:7], 12
	s_nop 0
	v_addc_co_u32_e32 v29, vcc, 0, v25, vcc
	v_lshl_add_u64 v[44:45], v[48:49], 0, s[6:7]
	global_load_dwordx4 v[8:11], v[10:11], off
	s_nop 0
	global_load_dwordx4 v[12:15], v[12:13], off
	s_nop 0
	global_load_dwordx4 v[16:19], v[24:25], off
	s_nop 0
	global_load_dwordx4 v[20:23], v[20:21], off
	v_add_co_u32_e32 v36, vcc, s3, v44
	global_load_dwordx4 v[24:27], v[26:27], off
	s_nop 0
	global_load_dwordx4 v[28:31], v[28:29], off
	v_addc_co_u32_e32 v37, vcc, 0, v45, vcc
	v_add_co_u32_e32 v40, vcc, s33, v44
	global_load_dwordx4 v[32:35], v[44:45], off
	s_nop 0
	global_load_dwordx4 v[36:39], v[36:37], off
	v_addc_co_u32_e32 v41, vcc, 0, v45, vcc
	v_add_co_u32_e32 v44, vcc, s34, v44
	global_load_dwordx4 v[40:43], v[40:41], off
	s_nop 0
	v_addc_co_u32_e32 v45, vcc, 0, v45, vcc
	global_load_dwordx4 v[44:47], v[44:45], off
	s_or_b32 s6, s38, 3
	s_ashr_i32 s7, s6, 31
	s_lshl_b64 s[6:7], s[6:7], 12
	s_lshl_b64 s[28:29], s[4:5], 2
	s_add_u32 s4, s12, s28
	s_addc_u32 s5, s13, s29
	s_waitcnt vmcnt(11)
	v_pk_add_f32 v[2:3], v[2:3], 0 op_sel_hi:[1,0]
	v_pk_add_f32 v[0:1], v[0:1], 0 op_sel_hi:[1,0]
	s_waitcnt vmcnt(10)
	v_pk_add_f32 v[2:3], v[2:3], v[6:7]
	v_pk_add_f32 v[0:1], v[0:1], v[4:5]
	s_waitcnt vmcnt(9)
	v_pk_add_f32 v[2:3], v[2:3], v[10:11]
	s_waitcnt vmcnt(7)
	v_pk_add_f32 v[4:5], v[18:19], 0 op_sel_hi:[1,0]
	v_pk_add_f32 v[6:7], v[16:17], 0 op_sel_hi:[1,0]
	v_pk_add_f32 v[0:1], v[0:1], v[8:9]
	s_waitcnt vmcnt(6)
	v_pk_add_f32 v[4:5], v[4:5], v[22:23]
	v_pk_add_f32 v[6:7], v[6:7], v[20:21]
	v_pk_add_f32 v[2:3], v[2:3], v[14:15]
	v_pk_add_f32 v[0:1], v[0:1], v[12:13]
	s_waitcnt vmcnt(5)
	v_pk_add_f32 v[4:5], v[4:5], v[26:27]
	v_pk_add_f32 v[6:7], v[6:7], v[24:25]
	v_mul_f32_e32 v228, 0x3d800000, v0
	v_mul_f32_e32 v231, 0x3d800000, v1
	v_mul_f32_e32 v229, 0x3d800000, v2
	v_mul_f32_e32 v225, 0x3d800000, v3
	s_waitcnt vmcnt(4)
	v_pk_add_f32 v[0:1], v[4:5], v[30:31]
	v_pk_add_f32 v[2:3], v[6:7], v[28:29]
	v_mul_f32_e32 v227, 0x3d800000, v0
	v_mul_f32_e32 v226, 0x3d800000, v2
	v_mul_f32_e32 v230, 0x3d800000, v3
	v_mul_f32_e32 v224, 0x3d800000, v1
	s_waitcnt vmcnt(3)
	v_pk_add_f32 v[0:1], v[34:35], 0 op_sel_hi:[1,0]
	v_pk_add_f32 v[2:3], v[32:33], 0 op_sel_hi:[1,0]
	s_waitcnt vmcnt(2)
	v_pk_add_f32 v[0:1], v[0:1], v[38:39]
	v_pk_add_f32 v[2:3], v[2:3], v[36:37]
	s_waitcnt vmcnt(1)
	v_pk_add_f32 v[0:1], v[0:1], v[42:43]
	v_pk_add_f32 v[2:3], v[2:3], v[40:41]
	s_waitcnt vmcnt(0)
	v_pk_add_f32 v[210:211], v[0:1], v[46:47]
	v_pk_add_f32 v[0:1], v[2:3], v[44:45]
	v_mul_f32_e32 v233, 0x3d800000, v210
	v_mul_f32_e32 v232, 0x3d800000, v0
	v_mul_f32_e32 v234, 0x3d800000, v1
	v_lshl_add_u64 v[0:1], v[48:49], 0, s[6:7]
	v_add_co_u32_e32 v2, vcc, s3, v0
	v_ashrrev_i32_e32 v210, 6, v222
	s_nop 0
	v_addc_co_u32_e32 v3, vcc, 0, v1, vcc
	global_load_dwordx4 v[128:131], v[0:1], off
	global_load_dwordx4 v[132:135], v[2:3], off
	v_add_co_u32_e32 v2, vcc, s33, v0
	v_mul_f32_e32 v211, 0x3d800000, v211
	s_nop 0
	v_addc_co_u32_e32 v3, vcc, 0, v1, vcc
	v_add_co_u32_e32 v0, vcc, s34, v0
	v_cmp_lt_i32_e64 s[6:7], v218, v216
	s_nop 0
	v_addc_co_u32_e32 v1, vcc, 0, v1, vcc
	global_load_dwordx4 v[136:139], v[2:3], off
	global_load_dwordx4 v[140:143], v[0:1], off
	v_lshlrev_b32_e32 v0, 5, v210
	v_ashrrev_i32_e32 v1, 31, v0
	v_or_b32_e32 v6, 1, v0
	v_lshl_add_u64 v[2:3], s[4:5], 0, v[144:145]
	v_lshlrev_b64 v[158:159], 12, v[0:1]
	v_ashrrev_i32_e32 v7, 31, v6
	v_lshl_add_u64 v[4:5], v[2:3], 0, v[158:159]
	v_lshlrev_b64 v[162:163], 12, v[6:7]
	v_lshl_add_u64 v[6:7], v[2:3], 0, v[162:163]
	global_load_dwordx4 v[124:127], v[4:5], off nt
	global_load_dwordx4 v[120:123], v[6:7], off nt
	v_or_b32_e32 v4, 2, v0
	v_ashrrev_i32_e32 v5, 31, v4
	v_or_b32_e32 v6, 3, v0
	v_lshlrev_b64 v[164:165], 12, v[4:5]
	v_ashrrev_i32_e32 v7, 31, v6
	v_lshl_add_u64 v[4:5], v[2:3], 0, v[164:165]
	v_lshlrev_b64 v[168:169], 12, v[6:7]
	v_lshl_add_u64 v[6:7], v[2:3], 0, v[168:169]
	global_load_dwordx4 v[116:119], v[4:5], off nt
	global_load_dwordx4 v[112:115], v[6:7], off nt
	v_or_b32_e32 v4, 4, v0
	v_ashrrev_i32_e32 v5, 31, v4
	v_or_b32_e32 v6, 5, v0
	v_lshlrev_b64 v[172:173], 12, v[4:5]
	v_ashrrev_i32_e32 v7, 31, v6
	v_lshl_add_u64 v[4:5], v[2:3], 0, v[172:173]
	v_lshlrev_b64 v[176:177], 12, v[6:7]
	v_lshl_add_u64 v[6:7], v[2:3], 0, v[176:177]
	global_load_dwordx4 v[108:111], v[4:5], off nt
	global_load_dwordx4 v[104:107], v[6:7], off nt
	v_or_b32_e32 v4, 6, v0
	v_ashrrev_i32_e32 v5, 31, v4
	v_or_b32_e32 v6, 7, v0
; DI void attn_sample_item(const Params& p, int item, ldsp lds, int tid_) {
;     ...
;   for (int t = 0; t < 4; ++t) { f32x4 a = {0.f, 0.f, 0.f, 0.f}; const float* pp = (const float*)(p.ws + B_PART) + (size_t)(b * 4 + t) * 1024 + h * 256 + lane * 4;
; #pragma unroll
;     for (int kp = 0; kp < 4; ++kp) a += *(const f32x4*)(pp + (size_t)kp * 512 * 1024);
;     q[t][0] = a[0] * 0.0625f; q[t][1] = a[1] * 0.0625f; q[t][2] = a[2] * 0.0625f; q[t][3] = a[3] * 0.0625f; }
;   const bool b0 = lane & 1, b1 = lane & 2;
;   f32x4 kvA[16], kvB[16];
; #pragma unroll
;   for (int j = 0; j < 16; ++j) kvA[j] = __builtin_nontemporal_load((const f32x4*)(ck + (size_t)(wid * 32 + j) * 1024 + lane * 4));
; #pragma unroll
;   for (int j = 0; j < 16; ++j) kvB[j] = __builtin_nontemporal_load((const f32x4*)(ck + (size_t)(wid * 32 + 16 + j) * 1024 + lane * 4));
	v_lshlrev_b64 v[180:181], 12, v[4:5]
	v_ashrrev_i32_e32 v7, 31, v6
	v_lshl_add_u64 v[4:5], v[2:3], 0, v[180:181]
	v_lshlrev_b64 v[184:185], 12, v[6:7]
	v_lshl_add_u64 v[6:7], v[2:3], 0, v[184:185]
	global_load_dwordx4 v[100:103], v[4:5], off nt
	global_load_dwordx4 v[96:99], v[6:7], off nt
	v_or_b32_e32 v4, 8, v0
	v_ashrrev_i32_e32 v5, 31, v4
	v_or_b32_e32 v6, 9, v0
	v_lshlrev_b64 v[188:189], 12, v[4:5]
	v_ashrrev_i32_e32 v7, 31, v6
	v_lshl_add_u64 v[4:5], v[2:3], 0, v[188:189]
	v_lshlrev_b64 v[192:193], 12, v[6:7]
	v_lshl_add_u64 v[6:7], v[2:3], 0, v[192:193]
	global_load_dwordx4 v[92:95], v[4:5], off nt
	global_load_dwordx4 v[88:91], v[6:7], off nt
	v_or_b32_e32 v4, 10, v0
	v_ashrrev_i32_e32 v5, 31, v4
	v_or_b32_e32 v6, 11, v0
	v_lshlrev_b64 v[196:197], 12, v[4:5]
	v_ashrrev_i32_e32 v7, 31, v6
	v_lshl_add_u64 v[4:5], v[2:3], 0, v[196:197]
	v_lshlrev_b64 v[200:201], 12, v[6:7]
	v_lshl_add_u64 v[6:7], v[2:3], 0, v[200:201]
	global_load_dwordx4 v[84:87], v[4:5], off nt
	global_load_dwordx4 v[80:83], v[6:7], off nt
	v_or_b32_e32 v4, 12, v0
	v_ashrrev_i32_e32 v5, 31, v4
	v_or_b32_e32 v6, 13, v0
	v_lshlrev_b64 v[202:203], 12, v[4:5]
	v_ashrrev_i32_e32 v7, 31, v6
	v_lshl_add_u64 v[4:5], v[2:3], 0, v[202:203]
	v_lshlrev_b64 v[204:205], 12, v[6:7]
	v_lshl_add_u64 v[6:7], v[2:3], 0, v[204:205]
	global_load_dwordx4 v[76:79], v[4:5], off nt
	global_load_dwordx4 v[72:75], v[6:7], off nt
	v_or_b32_e32 v4, 14, v0
	v_ashrrev_i32_e32 v5, 31, v4
	v_or_b32_e32 v6, 15, v0
	v_lshlrev_b64 v[206:207], 12, v[4:5]
	v_ashrrev_i32_e32 v7, 31, v6
	v_lshl_add_u64 v[4:5], v[2:3], 0, v[206:207]
	v_lshlrev_b64 v[208:209], 12, v[6:7]
	v_lshl_add_u64 v[6:7], v[2:3], 0, v[208:209]
	global_load_dwordx4 v[68:71], v[4:5], off nt
	global_load_dwordx4 v[64:67], v[6:7], off nt
	v_or_b32_e32 v4, 16, v0
	v_ashrrev_i32_e32 v5, 31, v4
	v_or_b32_e32 v6, 17, v0
	v_lshlrev_b64 v[146:147], 12, v[4:5]
	v_ashrrev_i32_e32 v7, 31, v6
	v_lshl_add_u64 v[4:5], v[2:3], 0, v[146:147]
	v_lshlrev_b64 v[148:149], 12, v[6:7]
	v_lshl_add_u64 v[6:7], v[2:3], 0, v[148:149]
	global_load_dwordx4 v[60:63], v[4:5], off nt
	global_load_dwordx4 v[56:59], v[6:7], off nt
	v_or_b32_e32 v4, 18, v0
	v_ashrrev_i32_e32 v5, 31, v4
	v_or_b32_e32 v6, 19, v0
	v_lshlrev_b64 v[150:151], 12, v[4:5]
	v_ashrrev_i32_e32 v7, 31, v6
	v_lshl_add_u64 v[4:5], v[2:3], 0, v[150:151]
	v_lshlrev_b64 v[152:153], 12, v[6:7]
	v_lshl_add_u64 v[6:7], v[2:3], 0, v[152:153]
	global_load_dwordx4 v[52:55], v[4:5], off nt
	global_load_dwordx4 v[48:51], v[6:7], off nt
	v_or_b32_e32 v4, 20, v0
	v_ashrrev_i32_e32 v5, 31, v4
	v_or_b32_e32 v6, 21, v0
	v_lshlrev_b64 v[154:155], 12, v[4:5]
	v_ashrrev_i32_e32 v7, 31, v6
	v_lshl_add_u64 v[4:5], v[2:3], 0, v[154:155]
	v_lshlrev_b64 v[156:157], 12, v[6:7]
	v_lshl_add_u64 v[6:7], v[2:3], 0, v[156:157]
	global_load_dwordx4 v[44:47], v[4:5], off nt
	global_load_dwordx4 v[40:43], v[6:7], off nt
	v_or_b32_e32 v4, 22, v0
	v_ashrrev_i32_e32 v5, 31, v4
	v_or_b32_e32 v6, 23, v0
	v_lshlrev_b64 v[160:161], 12, v[4:5]
	v_ashrrev_i32_e32 v7, 31, v6
	v_lshl_add_u64 v[4:5], v[2:3], 0, v[160:161]
	v_lshlrev_b64 v[166:167], 12, v[6:7]
	v_lshl_add_u64 v[6:7], v[2:3], 0, v[166:167]
	global_load_dwordx4 v[36:39], v[4:5], off nt
	global_load_dwordx4 v[32:35], v[6:7], off nt
	v_or_b32_e32 v4, 24, v0
	v_ashrrev_i32_e32 v5, 31, v4
	v_or_b32_e32 v6, 25, v0
	v_lshlrev_b64 v[170:171], 12, v[4:5]
	v_ashrrev_i32_e32 v7, 31, v6
	v_lshl_add_u64 v[4:5], v[2:3], 0, v[170:171]
	v_lshlrev_b64 v[174:175], 12, v[6:7]
	v_lshl_add_u64 v[6:7], v[2:3], 0, v[174:175]
	global_load_dwordx4 v[28:31], v[4:5], off nt
	global_load_dwordx4 v[24:27], v[6:7], off nt
	v_or_b32_e32 v4, 26, v0
	v_ashrrev_i32_e32 v5, 31, v4
	v_or_b32_e32 v6, 27, v0
	v_lshlrev_b64 v[178:179], 12, v[4:5]
	v_ashrrev_i32_e32 v7, 31, v6
	v_lshl_add_u64 v[4:5], v[2:3], 0, v[178:179]
	v_lshlrev_b64 v[182:183], 12, v[6:7]
	v_lshl_add_u64 v[6:7], v[2:3], 0, v[182:183]
	global_load_dwordx4 v[20:23], v[4:5], off nt
	global_load_dwordx4 v[16:19], v[6:7], off nt
	v_or_b32_e32 v4, 28, v0
	v_ashrrev_i32_e32 v5, 31, v4
	v_or_b32_e32 v6, 29, v0
	v_lshlrev_b64 v[186:187], 12, v[4:5]
	v_ashrrev_i32_e32 v7, 31, v6
	v_lshl_add_u64 v[4:5], v[2:3], 0, v[186:187]
	v_lshlrev_b64 v[190:191], 12, v[6:7]
	v_lshl_add_u64 v[6:7], v[2:3], 0, v[190:191]
	global_load_dwordx4 v[12:15], v[4:5], off nt
	global_load_dwordx4 v[8:11], v[6:7], off nt
	v_or_b32_e32 v4, 30, v0
	v_or_b32_e32 v0, 31, v0
	v_ashrrev_i32_e32 v5, 31, v4
	v_ashrrev_i32_e32 v1, 31, v0
	v_lshlrev_b64 v[194:195], 12, v[4:5]
	v_lshlrev_b64 v[198:199], 12, v[0:1]
	v_lshl_add_u64 v[4:5], v[2:3], 0, v[194:195]
	v_lshl_add_u64 v[0:1], v[2:3], 0, v[198:199]
	global_load_dwordx4 v[4:7], v[4:5], off nt
	s_nop 0
	global_load_dwordx4 v[0:3], v[0:1], off nt
	s_waitcnt vmcnt(35)
	v_pk_add_f32 v[128:129], v[128:129], 0 op_sel_hi:[1,0]
	v_pk_add_f32 v[130:131], v[130:131], 0 op_sel_hi:[1,0]
	s_waitcnt vmcnt(34)
	v_pk_add_f32 v[128:129], v[128:129], v[132:133]
	v_pk_add_f32 v[130:131], v[130:131], v[134:135]
	s_waitcnt vmcnt(33)
	v_pk_add_f32 v[128:129], v[128:129], v[136:137]
	v_pk_add_f32 v[130:131], v[130:131], v[138:139]
	s_waitcnt vmcnt(32)
; DI void attn_sample_item(const Params& p, int item, ldsp lds, int tid_) {
;     ...
;   for (int t = 0; t < 4; ++t) { f32x4 a = {0.f, 0.f, 0.f, 0.f}; const float* pp = (const float*)(p.ws + B_PART) + (size_t)(b * 4 + t) * 1024 + h * 256 + lane * 4;
; #pragma unroll
;     for (int kp = 0; kp < 4; ++kp) a += *(const f32x4*)(pp + (size_t)kp * 512 * 1024);
;     q[t][0] = a[0] * 0.0625f; q[t][1] = a[1] * 0.0625f; q[t][2] = a[2] * 0.0625f; q[t][3] = a[3] * 0.0625f; }
;   const bool b0 = lane & 1, b1 = lane & 2;
;   f32x4 kvA[16], kvB[16];
; #pragma unroll
;   for (int j = 0; j < 16; ++j) kvA[j] = __builtin_nontemporal_load((const f32x4*)(ck + (size_t)(wid * 32 + j) * 1024 + lane * 4));
; #pragma unroll
;   for (int j = 0; j < 16; ++j) kvB[j] = __builtin_nontemporal_load((const f32x4*)(ck + (size_t)(wid * 32 + 16 + j) * 1024 + lane * 4));
;     ...
;   SC_SCORE(kvA, 0)
;   SC_SCORE(kvB, 1)
	v_pk_add_f32 v[128:129], v[128:129], v[140:141]
	v_pk_add_f32 v[130:131], v[130:131], v[142:143]
	v_mul_f32_e32 v138, 0x3d800000, v129
	v_mul_f32_e32 v135, 0x3d800000, v128
	v_mul_f32_e32 v134, 0x3d800000, v131
	v_mul_f32_e32 v137, 0x3d800000, v130
	v_lshlrev_b32_e32 v128, 2, v215
	v_lshlrev_b32_e32 v129, 2, v217
	v_lshlrev_b32_e32 v130, 2, v218
	v_lshlrev_b32_e32 v131, 2, v219
	v_lshlrev_b32_e32 v132, 2, v220
	v_lshlrev_b32_e32 v133, 2, v221
	v_lshl_add_u32 v136, v210, 7, 16
	v_and_b32_e32 v139, 3, v223
	v_bfrev_b32_e32 v139, v139
	v_lshrrev_b32_e32 v139, 20, v139
	v_and_b32_e32 v235, -4, v223
	v_add3_u32 v235, v136, v139, v235
	v_mov_b32_e32 v236, v228
	v_mov_b32_e32 v237, v226
	v_mov_b32_e32 v238, v231
	v_mov_b32_e32 v239, v230
	v_mov_b32_e32 v240, v229
	v_mov_b32_e32 v241, v227
	v_mov_b32_e32 v242, v225
	v_mov_b32_e32 v243, v224
	v_mov_b32_e32 v244, v232
	v_mov_b32_e32 v245, v135
	v_mov_b32_e32 v246, v234
	v_mov_b32_e32 v247, v138
	v_mov_b32_e32 v248, v233
	v_mov_b32_e32 v249, v137
	v_mov_b32_e32 v250, v211
	v_mov_b32_e32 v251, v134
	s_mov_b32 vcc_lo, 0x55555555
	s_mov_b32 vcc_hi, 0x55555555
	s_mov_b32 s4, 0x33333333
	s_mov_b32 s5, 0x33333333
	s_mov_b32 s6, 0x0f0f0f0f
	s_mov_b32 s7, 0x0f0f0f0f
	s_mov_b32 s64, 0x00ff00ff
	s_mov_b32 s65, 0x00ff00ff
	s_waitcnt vmcnt(31)
	v_pk_mul_f32 v[252:253], v[236:237], v[124:125] op_sel_hi:[1,0]
	v_pk_mul_f32 v[254:255], v[244:245], v[124:125] op_sel_hi:[1,0]
	v_pk_fma_f32 v[252:253], v[238:239], v[124:125], v[252:253] op_sel:[0,1,0]
	v_pk_fma_f32 v[254:255], v[246:247], v[124:125], v[254:255] op_sel:[0,1,0]
	v_pk_fma_f32 v[252:253], v[240:241], v[126:127], v[252:253] op_sel_hi:[1,0,1]
	v_pk_fma_f32 v[254:255], v[248:249], v[126:127], v[254:255] op_sel_hi:[1,0,1]
	v_pk_fma_f32 v[252:253], v[242:243], v[126:127], v[252:253] op_sel:[0,1,0]
	v_pk_fma_f32 v[254:255], v[250:251], v[126:127], v[254:255] op_sel:[0,1,0]
	s_waitcnt vmcnt(30)
	v_pk_mul_f32 v[140:141], v[236:237], v[120:121] op_sel_hi:[1,0]
	v_pk_mul_f32 v[142:143], v[244:245], v[120:121] op_sel_hi:[1,0]
	v_pk_fma_f32 v[140:141], v[238:239], v[120:121], v[140:141] op_sel:[0,1,0]
	v_pk_fma_f32 v[142:143], v[246:247], v[120:121], v[142:143] op_sel:[0,1,0]
	v_pk_fma_f32 v[140:141], v[240:241], v[122:123], v[140:141] op_sel_hi:[1,0,1]
	v_pk_fma_f32 v[142:143], v[248:249], v[122:123], v[142:143] op_sel_hi:[1,0,1]
	v_pk_fma_f32 v[140:141], v[242:243], v[122:123], v[140:141] op_sel:[0,1,0]
	v_pk_fma_f32 v[142:143], v[250:251], v[122:123], v[142:143] op_sel:[0,1,0]
	v_add_f32_dpp v124, v252, v252 quad_perm:[1,0,3,2] row_mask:0xf bank_mask:0xf
	v_add_f32_dpp v125, v253, v253 quad_perm:[1,0,3,2] row_mask:0xf bank_mask:0xf
	v_add_f32_dpp v126, v254, v254 quad_perm:[1,0,3,2] row_mask:0xf bank_mask:0xf
	v_add_f32_dpp v127, v255, v255 quad_perm:[1,0,3,2] row_mask:0xf bank_mask:0xf
	v_cndmask_b32_e32 v124, v126, v124, vcc
	v_cndmask_b32_e32 v125, v127, v125, vcc
	s_waitcnt vmcnt(29)
	v_pk_mul_f32 v[252:253], v[236:237], v[116:117] op_sel_hi:[1,0]
	v_pk_mul_f32 v[254:255], v[244:245], v[116:117] op_sel_hi:[1,0]
	v_pk_fma_f32 v[252:253], v[238:239], v[116:117], v[252:253] op_sel:[0,1,0]
	v_pk_fma_f32 v[254:255], v[246:247], v[116:117], v[254:255] op_sel:[0,1,0]
	v_pk_fma_f32 v[252:253], v[240:241], v[118:119], v[252:253] op_sel_hi:[1,0,1]
	v_pk_fma_f32 v[254:255], v[248:249], v[118:119], v[254:255] op_sel_hi:[1,0,1]
	v_pk_fma_f32 v[252:253], v[242:243], v[118:119], v[252:253] op_sel:[0,1,0]
	v_pk_fma_f32 v[254:255], v[250:251], v[118:119], v[254:255] op_sel:[0,1,0]
	v_add_f32_dpp v120, v140, v140 quad_perm:[1,0,3,2] row_mask:0xf bank_mask:0xf
	v_add_f32_dpp v121, v141, v141 quad_perm:[1,0,3,2] row_mask:0xf bank_mask:0xf
	v_add_f32_dpp v122, v142, v142 quad_perm:[1,0,3,2] row_mask:0xf bank_mask:0xf
	v_add_f32_dpp v123, v143, v143 quad_perm:[1,0,3,2] row_mask:0xf bank_mask:0xf
	v_cndmask_b32_e32 v120, v122, v120, vcc
	v_cndmask_b32_e32 v121, v123, v121, vcc
	v_add_f32_dpp v126, v124, v124 quad_perm:[2,3,0,1] row_mask:0xf bank_mask:0xf
	v_add_f32_dpp v127, v125, v125 quad_perm:[2,3,0,1] row_mask:0xf bank_mask:0xf
	v_cndmask_b32_e64 v124, v127, v126, s[4:5]
	s_waitcnt vmcnt(28)
	v_pk_mul_f32 v[140:141], v[236:237], v[112:113] op_sel_hi:[1,0]
	v_pk_mul_f32 v[142:143], v[244:245], v[112:113] op_sel_hi:[1,0]
	v_pk_fma_f32 v[140:141], v[238:239], v[112:113], v[140:141] op_sel:[0,1,0]
	v_pk_fma_f32 v[142:143], v[246:247], v[112:113], v[142:143] op_sel:[0,1,0]
	v_pk_fma_f32 v[140:141], v[240:241], v[114:115], v[140:141] op_sel_hi:[1,0,1]
	v_pk_fma_f32 v[142:143], v[248:249], v[114:115], v[142:143] op_sel_hi:[1,0,1]
	v_pk_fma_f32 v[140:141], v[242:243], v[114:115], v[140:141] op_sel:[0,1,0]
	v_pk_fma_f32 v[142:143], v[250:251], v[114:115], v[142:143] op_sel:[0,1,0]
	v_add_f32_dpp v116, v252, v252 quad_perm:[1,0,3,2] row_mask:0xf bank_mask:0xf
	v_add_f32_dpp v117, v253, v253 quad_perm:[1,0,3,2] row_mask:0xf bank_mask:0xf
	v_add_f32_dpp v118, v254, v254 quad_perm:[1,0,3,2] row_mask:0xf bank_mask:0xf
	v_add_f32_dpp v119, v255, v255 quad_perm:[1,0,3,2] row_mask:0xf bank_mask:0xf
	v_cndmask_b32_e32 v116, v118, v116, vcc
	v_cndmask_b32_e32 v117, v119, v117, vcc
	v_add_f32_dpp v122, v120, v120 quad_perm:[2,3,0,1] row_mask:0xf bank_mask:0xf
	v_add_f32_dpp v123, v121, v121 quad_perm:[2,3,0,1] row_mask:0xf bank_mask:0xf
	v_cndmask_b32_e64 v120, v123, v122, s[4:5]
	v_cndmask_b32_e64 v125, v120, v124, s[6:7]
	v_cndmask_b32_e64 v126, v124, v120, s[6:7]
	s_waitcnt vmcnt(27)
; DI void attn_sample_item(const Params& p, int item, ldsp lds, int tid_) {
;     ...
;   SC_SCORE(kvA, 0)
;   SC_SCORE(kvB, 1)
	v_pk_mul_f32 v[252:253], v[236:237], v[108:109] op_sel_hi:[1,0]
	v_pk_mul_f32 v[254:255], v[244:245], v[108:109] op_sel_hi:[1,0]
	v_pk_fma_f32 v[252:253], v[238:239], v[108:109], v[252:253] op_sel:[0,1,0]
	v_pk_fma_f32 v[254:255], v[246:247], v[108:109], v[254:255] op_sel:[0,1,0]
	v_pk_fma_f32 v[252:253], v[240:241], v[110:111], v[252:253] op_sel_hi:[1,0,1]
	v_pk_fma_f32 v[254:255], v[248:249], v[110:111], v[254:255] op_sel_hi:[1,0,1]
	v_pk_fma_f32 v[252:253], v[242:243], v[110:111], v[252:253] op_sel:[0,1,0]
	v_pk_fma_f32 v[254:255], v[250:251], v[110:111], v[254:255] op_sel:[0,1,0]
	v_add_f32_dpp v124, v126, v125 row_ror:4 row_mask:0xf bank_mask:0xf
	v_add_f32_dpp v112, v140, v140 quad_perm:[1,0,3,2] row_mask:0xf bank_mask:0xf
	v_add_f32_dpp v113, v141, v141 quad_perm:[1,0,3,2] row_mask:0xf bank_mask:0xf
	v_add_f32_dpp v114, v142, v142 quad_perm:[1,0,3,2] row_mask:0xf bank_mask:0xf
	v_add_f32_dpp v115, v143, v143 quad_perm:[1,0,3,2] row_mask:0xf bank_mask:0xf
	v_cndmask_b32_e32 v112, v114, v112, vcc
	v_cndmask_b32_e32 v113, v115, v113, vcc
	v_add_f32_dpp v118, v116, v116 quad_perm:[2,3,0,1] row_mask:0xf bank_mask:0xf
	v_add_f32_dpp v119, v117, v117 quad_perm:[2,3,0,1] row_mask:0xf bank_mask:0xf
	v_cndmask_b32_e64 v116, v119, v118, s[4:5]
	s_waitcnt vmcnt(26)
	v_pk_mul_f32 v[140:141], v[236:237], v[104:105] op_sel_hi:[1,0]
	v_pk_mul_f32 v[142:143], v[244:245], v[104:105] op_sel_hi:[1,0]
	v_pk_fma_f32 v[140:141], v[238:239], v[104:105], v[140:141] op_sel:[0,1,0]
	v_pk_fma_f32 v[142:143], v[246:247], v[104:105], v[142:143] op_sel:[0,1,0]
	v_pk_fma_f32 v[140:141], v[240:241], v[106:107], v[140:141] op_sel_hi:[1,0,1]
	v_pk_fma_f32 v[142:143], v[248:249], v[106:107], v[142:143] op_sel_hi:[1,0,1]
	v_pk_fma_f32 v[140:141], v[242:243], v[106:107], v[140:141] op_sel:[0,1,0]
	v_pk_fma_f32 v[142:143], v[250:251], v[106:107], v[142:143] op_sel:[0,1,0]
	v_add_f32_dpp v108, v252, v252 quad_perm:[1,0,3,2] row_mask:0xf bank_mask:0xf
	v_add_f32_dpp v109, v253, v253 quad_perm:[1,0,3,2] row_mask:0xf bank_mask:0xf
	v_add_f32_dpp v110, v254, v254 quad_perm:[1,0,3,2] row_mask:0xf bank_mask:0xf
	v_add_f32_dpp v111, v255, v255 quad_perm:[1,0,3,2] row_mask:0xf bank_mask:0xf
	v_cndmask_b32_e32 v108, v110, v108, vcc
	v_cndmask_b32_e32 v109, v111, v109, vcc
	v_add_f32_dpp v114, v112, v112 quad_perm:[2,3,0,1] row_mask:0xf bank_mask:0xf
	v_add_f32_dpp v115, v113, v113 quad_perm:[2,3,0,1] row_mask:0xf bank_mask:0xf
	v_cndmask_b32_e64 v112, v115, v114, s[4:5]
	v_cndmask_b32_e64 v117, v112, v116, s[6:7]
	v_cndmask_b32_e64 v118, v116, v112, s[6:7]
	s_waitcnt vmcnt(25)
	v_pk_mul_f32 v[252:253], v[236:237], v[100:101] op_sel_hi:[1,0]
	v_pk_mul_f32 v[254:255], v[244:245], v[100:101] op_sel_hi:[1,0]
	v_pk_fma_f32 v[252:253], v[238:239], v[100:101], v[252:253] op_sel:[0,1,0]
	v_pk_fma_f32 v[254:255], v[246:247], v[100:101], v[254:255] op_sel:[0,1,0]
	v_pk_fma_f32 v[252:253], v[240:241], v[102:103], v[252:253] op_sel_hi:[1,0,1]
	v_pk_fma_f32 v[254:255], v[248:249], v[102:103], v[254:255] op_sel_hi:[1,0,1]
	v_pk_fma_f32 v[252:253], v[242:243], v[102:103], v[252:253] op_sel:[0,1,0]
	v_pk_fma_f32 v[254:255], v[250:251], v[102:103], v[254:255] op_sel:[0,1,0]
	v_add_f32_dpp v116, v118, v117 row_ror:4 row_mask:0xf bank_mask:0xf
	v_cndmask_b32_e64 v125, v116, v124, s[64:65]
	v_cndmask_b32_e64 v126, v124, v116, s[64:65]
	v_add_f32_dpp v104, v140, v140 quad_perm:[1,0,3,2] row_mask:0xf bank_mask:0xf
	v_add_f32_dpp v105, v141, v141 quad_perm:[1,0,3,2] row_mask:0xf bank_mask:0xf
	v_add_f32_dpp v106, v142, v142 quad_perm:[1,0,3,2] row_mask:0xf bank_mask:0xf
	v_add_f32_dpp v107, v143, v143 quad_perm:[1,0,3,2] row_mask:0xf bank_mask:0xf
	v_cndmask_b32_e32 v104, v106, v104, vcc
	v_cndmask_b32_e32 v105, v107, v105, vcc
	v_add_f32_dpp v110, v108, v108 quad_perm:[2,3,0,1] row_mask:0xf bank_mask:0xf
	v_add_f32_dpp v111, v109, v109 quad_perm:[2,3,0,1] row_mask:0xf bank_mask:0xf
	v_cndmask_b32_e64 v108, v111, v110, s[4:5]
	s_waitcnt vmcnt(24)
	v_pk_mul_f32 v[140:141], v[236:237], v[96:97] op_sel_hi:[1,0]
	v_pk_mul_f32 v[142:143], v[244:245], v[96:97] op_sel_hi:[1,0]
	v_pk_fma_f32 v[140:141], v[238:239], v[96:97], v[140:141] op_sel:[0,1,0]
	v_pk_fma_f32 v[142:143], v[246:247], v[96:97], v[142:143] op_sel:[0,1,0]
	v_pk_fma_f32 v[140:141], v[240:241], v[98:99], v[140:141] op_sel_hi:[1,0,1]
	v_pk_fma_f32 v[142:143], v[248:249], v[98:99], v[142:143] op_sel_hi:[1,0,1]
	v_pk_fma_f32 v[140:141], v[242:243], v[98:99], v[140:141] op_sel:[0,1,0]
	v_pk_fma_f32 v[142:143], v[250:251], v[98:99], v[142:143] op_sel:[0,1,0]
	v_add_f32_dpp v124, v126, v125 row_ror:8 row_mask:0xf bank_mask:0xf
	v_add_f32_dpp v100, v252, v252 quad_perm:[1,0,3,2] row_mask:0xf bank_mask:0xf
	v_add_f32_dpp v101, v253, v253 quad_perm:[1,0,3,2] row_mask:0xf bank_mask:0xf
	v_add_f32_dpp v102, v254, v254 quad_perm:[1,0,3,2] row_mask:0xf bank_mask:0xf
	v_add_f32_dpp v103, v255, v255 quad_perm:[1,0,3,2] row_mask:0xf bank_mask:0xf
	v_cndmask_b32_e32 v100, v102, v100, vcc
	v_cndmask_b32_e32 v101, v103, v101, vcc
	v_add_f32_dpp v106, v104, v104 quad_perm:[2,3,0,1] row_mask:0xf bank_mask:0xf
	v_add_f32_dpp v107, v105, v105 quad_perm:[2,3,0,1] row_mask:0xf bank_mask:0xf
	v_cndmask_b32_e64 v104, v107, v106, s[4:5]
	v_cndmask_b32_e64 v109, v104, v108, s[6:7]
	v_cndmask_b32_e64 v110, v108, v104, s[6:7]
	s_waitcnt vmcnt(23)
; DI void attn_sample_item(const Params& p, int item, ldsp lds, int tid_) {
;     ...
;   SC_SCORE(kvA, 0)
;   SC_SCORE(kvB, 1)
	v_pk_mul_f32 v[252:253], v[236:237], v[92:93] op_sel_hi:[1,0]
	v_pk_mul_f32 v[254:255], v[244:245], v[92:93] op_sel_hi:[1,0]
	v_pk_fma_f32 v[252:253], v[238:239], v[92:93], v[252:253] op_sel:[0,1,0]
	v_pk_fma_f32 v[254:255], v[246:247], v[92:93], v[254:255] op_sel:[0,1,0]
	v_pk_fma_f32 v[252:253], v[240:241], v[94:95], v[252:253] op_sel_hi:[1,0,1]
	v_pk_fma_f32 v[254:255], v[248:249], v[94:95], v[254:255] op_sel_hi:[1,0,1]
	v_pk_fma_f32 v[252:253], v[242:243], v[94:95], v[252:253] op_sel:[0,1,0]
	v_pk_fma_f32 v[254:255], v[250:251], v[94:95], v[254:255] op_sel:[0,1,0]
	v_add_f32_dpp v108, v110, v109 row_ror:4 row_mask:0xf bank_mask:0xf
	v_add_f32_dpp v96, v140, v140 quad_perm:[1,0,3,2] row_mask:0xf bank_mask:0xf
	v_add_f32_dpp v97, v141, v141 quad_perm:[1,0,3,2] row_mask:0xf bank_mask:0xf
	v_add_f32_dpp v98, v142, v142 quad_perm:[1,0,3,2] row_mask:0xf bank_mask:0xf
	v_add_f32_dpp v99, v143, v143 quad_perm:[1,0,3,2] row_mask:0xf bank_mask:0xf
	v_cndmask_b32_e32 v96, v98, v96, vcc
	v_cndmask_b32_e32 v97, v99, v97, vcc
	v_add_f32_dpp v102, v100, v100 quad_perm:[2,3,0,1] row_mask:0xf bank_mask:0xf
	v_add_f32_dpp v103, v101, v101 quad_perm:[2,3,0,1] row_mask:0xf bank_mask:0xf
	v_cndmask_b32_e64 v100, v103, v102, s[4:5]
	s_waitcnt vmcnt(22)
	v_pk_mul_f32 v[140:141], v[236:237], v[88:89] op_sel_hi:[1,0]
	v_pk_mul_f32 v[142:143], v[244:245], v[88:89] op_sel_hi:[1,0]
	v_pk_fma_f32 v[140:141], v[238:239], v[88:89], v[140:141] op_sel:[0,1,0]
	v_pk_fma_f32 v[142:143], v[246:247], v[88:89], v[142:143] op_sel:[0,1,0]
	v_pk_fma_f32 v[140:141], v[240:241], v[90:91], v[140:141] op_sel_hi:[1,0,1]
	v_pk_fma_f32 v[142:143], v[248:249], v[90:91], v[142:143] op_sel_hi:[1,0,1]
	v_pk_fma_f32 v[140:141], v[242:243], v[90:91], v[140:141] op_sel:[0,1,0]
	v_pk_fma_f32 v[142:143], v[250:251], v[90:91], v[142:143] op_sel:[0,1,0]
	v_add_f32_dpp v92, v252, v252 quad_perm:[1,0,3,2] row_mask:0xf bank_mask:0xf
	v_add_f32_dpp v93, v253, v253 quad_perm:[1,0,3,2] row_mask:0xf bank_mask:0xf
	v_add_f32_dpp v94, v254, v254 quad_perm:[1,0,3,2] row_mask:0xf bank_mask:0xf
	v_add_f32_dpp v95, v255, v255 quad_perm:[1,0,3,2] row_mask:0xf bank_mask:0xf
	v_cndmask_b32_e32 v92, v94, v92, vcc
	v_cndmask_b32_e32 v93, v95, v93, vcc
	v_add_f32_dpp v98, v96, v96 quad_perm:[2,3,0,1] row_mask:0xf bank_mask:0xf
	v_add_f32_dpp v99, v97, v97 quad_perm:[2,3,0,1] row_mask:0xf bank_mask:0xf
	v_cndmask_b32_e64 v96, v99, v98, s[4:5]
	v_cndmask_b32_e64 v101, v96, v100, s[6:7]
	v_cndmask_b32_e64 v102, v100, v96, s[6:7]
	s_waitcnt vmcnt(21)
	v_pk_mul_f32 v[252:253], v[236:237], v[84:85] op_sel_hi:[1,0]
	v_pk_mul_f32 v[254:255], v[244:245], v[84:85] op_sel_hi:[1,0]
	v_pk_fma_f32 v[252:253], v[238:239], v[84:85], v[252:253] op_sel:[0,1,0]
	v_pk_fma_f32 v[254:255], v[246:247], v[84:85], v[254:255] op_sel:[0,1,0]
	v_pk_fma_f32 v[252:253], v[240:241], v[86:87], v[252:253] op_sel_hi:[1,0,1]
	v_pk_fma_f32 v[254:255], v[248:249], v[86:87], v[254:255] op_sel_hi:[1,0,1]
	v_pk_fma_f32 v[252:253], v[242:243], v[86:87], v[252:253] op_sel:[0,1,0]
	v_pk_fma_f32 v[254:255], v[250:251], v[86:87], v[254:255] op_sel:[0,1,0]
	v_add_f32_dpp v100, v102, v101 row_ror:4 row_mask:0xf bank_mask:0xf
	v_cndmask_b32_e64 v109, v100, v108, s[64:65]
	v_cndmask_b32_e64 v110, v108, v100, s[64:65]
	v_add_f32_dpp v88, v140, v140 quad_perm:[1,0,3,2] row_mask:0xf bank_mask:0xf
	v_add_f32_dpp v89, v141, v141 quad_perm:[1,0,3,2] row_mask:0xf bank_mask:0xf
	v_add_f32_dpp v90, v142, v142 quad_perm:[1,0,3,2] row_mask:0xf bank_mask:0xf
	v_add_f32_dpp v91, v143, v143 quad_perm:[1,0,3,2] row_mask:0xf bank_mask:0xf
	v_cndmask_b32_e32 v88, v90, v88, vcc
	v_cndmask_b32_e32 v89, v91, v89, vcc
	v_add_f32_dpp v94, v92, v92 quad_perm:[2,3,0,1] row_mask:0xf bank_mask:0xf
	v_add_f32_dpp v95, v93, v93 quad_perm:[2,3,0,1] row_mask:0xf bank_mask:0xf
	v_cndmask_b32_e64 v92, v95, v94, s[4:5]
	s_waitcnt vmcnt(20)
	v_pk_mul_f32 v[140:141], v[236:237], v[80:81] op_sel_hi:[1,0]
	v_pk_mul_f32 v[142:143], v[244:245], v[80:81] op_sel_hi:[1,0]
	v_pk_fma_f32 v[140:141], v[238:239], v[80:81], v[140:141] op_sel:[0,1,0]
	v_pk_fma_f32 v[142:143], v[246:247], v[80:81], v[142:143] op_sel:[0,1,0]
	v_pk_fma_f32 v[140:141], v[240:241], v[82:83], v[140:141] op_sel_hi:[1,0,1]
	v_pk_fma_f32 v[142:143], v[248:249], v[82:83], v[142:143] op_sel_hi:[1,0,1]
	v_pk_fma_f32 v[140:141], v[242:243], v[82:83], v[140:141] op_sel:[0,1,0]
	v_pk_fma_f32 v[142:143], v[250:251], v[82:83], v[142:143] op_sel:[0,1,0]
	v_add_f32_dpp v108, v110, v109 row_ror:8 row_mask:0xf bank_mask:0xf
	v_add_f32_dpp v84, v252, v252 quad_perm:[1,0,3,2] row_mask:0xf bank_mask:0xf
	v_add_f32_dpp v85, v253, v253 quad_perm:[1,0,3,2] row_mask:0xf bank_mask:0xf
	v_add_f32_dpp v86, v254, v254 quad_perm:[1,0,3,2] row_mask:0xf bank_mask:0xf
	v_add_f32_dpp v87, v255, v255 quad_perm:[1,0,3,2] row_mask:0xf bank_mask:0xf
	v_cndmask_b32_e32 v84, v86, v84, vcc
	v_cndmask_b32_e32 v85, v87, v85, vcc
	v_add_f32_dpp v90, v88, v88 quad_perm:[2,3,0,1] row_mask:0xf bank_mask:0xf
	v_add_f32_dpp v91, v89, v89 quad_perm:[2,3,0,1] row_mask:0xf bank_mask:0xf
	v_cndmask_b32_e64 v88, v91, v90, s[4:5]
	v_cndmask_b32_e64 v93, v88, v92, s[6:7]
	v_cndmask_b32_e64 v94, v92, v88, s[6:7]
	s_waitcnt vmcnt(19)
; DI void attn_sample_item(const Params& p, int item, ldsp lds, int tid_) {
;     ...
;   SC_SCORE(kvA, 0)
;   SC_SCORE(kvB, 1)
	v_pk_mul_f32 v[252:253], v[236:237], v[76:77] op_sel_hi:[1,0]
	v_pk_mul_f32 v[254:255], v[244:245], v[76:77] op_sel_hi:[1,0]
	v_pk_fma_f32 v[252:253], v[238:239], v[76:77], v[252:253] op_sel:[0,1,0]
	v_pk_fma_f32 v[254:255], v[246:247], v[76:77], v[254:255] op_sel:[0,1,0]
	v_pk_fma_f32 v[252:253], v[240:241], v[78:79], v[252:253] op_sel_hi:[1,0,1]
	v_pk_fma_f32 v[254:255], v[248:249], v[78:79], v[254:255] op_sel_hi:[1,0,1]
	v_pk_fma_f32 v[252:253], v[242:243], v[78:79], v[252:253] op_sel:[0,1,0]
	v_pk_fma_f32 v[254:255], v[250:251], v[78:79], v[254:255] op_sel:[0,1,0]
	v_permlane16_swap_b32_e32 v124, v108
	v_add_f32_e32 v124, v124, v108
	v_add_f32_dpp v92, v94, v93 row_ror:4 row_mask:0xf bank_mask:0xf
	v_add_f32_dpp v80, v140, v140 quad_perm:[1,0,3,2] row_mask:0xf bank_mask:0xf
	v_add_f32_dpp v81, v141, v141 quad_perm:[1,0,3,2] row_mask:0xf bank_mask:0xf
	v_add_f32_dpp v82, v142, v142 quad_perm:[1,0,3,2] row_mask:0xf bank_mask:0xf
	v_add_f32_dpp v83, v143, v143 quad_perm:[1,0,3,2] row_mask:0xf bank_mask:0xf
	v_cndmask_b32_e32 v80, v82, v80, vcc
	v_cndmask_b32_e32 v81, v83, v81, vcc
	v_add_f32_dpp v86, v84, v84 quad_perm:[2,3,0,1] row_mask:0xf bank_mask:0xf
	v_add_f32_dpp v87, v85, v85 quad_perm:[2,3,0,1] row_mask:0xf bank_mask:0xf
	v_cndmask_b32_e64 v84, v87, v86, s[4:5]
	s_waitcnt vmcnt(18)
	v_pk_mul_f32 v[140:141], v[236:237], v[72:73] op_sel_hi:[1,0]
	v_pk_mul_f32 v[142:143], v[244:245], v[72:73] op_sel_hi:[1,0]
	v_pk_fma_f32 v[140:141], v[238:239], v[72:73], v[140:141] op_sel:[0,1,0]
	v_pk_fma_f32 v[142:143], v[246:247], v[72:73], v[142:143] op_sel:[0,1,0]
	v_pk_fma_f32 v[140:141], v[240:241], v[74:75], v[140:141] op_sel_hi:[1,0,1]
	v_pk_fma_f32 v[142:143], v[248:249], v[74:75], v[142:143] op_sel_hi:[1,0,1]
	v_pk_fma_f32 v[140:141], v[242:243], v[74:75], v[140:141] op_sel:[0,1,0]
	v_pk_fma_f32 v[142:143], v[250:251], v[74:75], v[142:143] op_sel:[0,1,0]
	v_add_f32_dpp v76, v252, v252 quad_perm:[1,0,3,2] row_mask:0xf bank_mask:0xf
	v_add_f32_dpp v77, v253, v253 quad_perm:[1,0,3,2] row_mask:0xf bank_mask:0xf
	v_add_f32_dpp v78, v254, v254 quad_perm:[1,0,3,2] row_mask:0xf bank_mask:0xf
	v_add_f32_dpp v79, v255, v255 quad_perm:[1,0,3,2] row_mask:0xf bank_mask:0xf
	v_cndmask_b32_e32 v76, v78, v76, vcc
	v_cndmask_b32_e32 v77, v79, v77, vcc
	v_add_f32_dpp v82, v80, v80 quad_perm:[2,3,0,1] row_mask:0xf bank_mask:0xf
	v_add_f32_dpp v83, v81, v81 quad_perm:[2,3,0,1] row_mask:0xf bank_mask:0xf
	v_cndmask_b32_e64 v80, v83, v82, s[4:5]
	v_cndmask_b32_e64 v85, v80, v84, s[6:7]
	v_cndmask_b32_e64 v86, v84, v80, s[6:7]
	s_waitcnt vmcnt(17)
	v_pk_mul_f32 v[252:253], v[236:237], v[68:69] op_sel_hi:[1,0]
	v_pk_mul_f32 v[254:255], v[244:245], v[68:69] op_sel_hi:[1,0]
	v_pk_fma_f32 v[252:253], v[238:239], v[68:69], v[252:253] op_sel:[0,1,0]
	v_pk_fma_f32 v[254:255], v[246:247], v[68:69], v[254:255] op_sel:[0,1,0]
	v_pk_fma_f32 v[252:253], v[240:241], v[70:71], v[252:253] op_sel_hi:[1,0,1]
	v_pk_fma_f32 v[254:255], v[248:249], v[70:71], v[254:255] op_sel_hi:[1,0,1]
	v_pk_fma_f32 v[252:253], v[242:243], v[70:71], v[252:253] op_sel:[0,1,0]
	v_pk_fma_f32 v[254:255], v[250:251], v[70:71], v[254:255] op_sel:[0,1,0]
	v_add_f32_dpp v84, v86, v85 row_ror:4 row_mask:0xf bank_mask:0xf
	v_cndmask_b32_e64 v93, v84, v92, s[64:65]
	v_cndmask_b32_e64 v94, v92, v84, s[64:65]
	v_add_f32_dpp v72, v140, v140 quad_perm:[1,0,3,2] row_mask:0xf bank_mask:0xf
	v_add_f32_dpp v73, v141, v141 quad_perm:[1,0,3,2] row_mask:0xf bank_mask:0xf
	v_add_f32_dpp v74, v142, v142 quad_perm:[1,0,3,2] row_mask:0xf bank_mask:0xf
	v_add_f32_dpp v75, v143, v143 quad_perm:[1,0,3,2] row_mask:0xf bank_mask:0xf
	v_cndmask_b32_e32 v72, v74, v72, vcc
	v_cndmask_b32_e32 v73, v75, v73, vcc
	v_add_f32_dpp v78, v76, v76 quad_perm:[2,3,0,1] row_mask:0xf bank_mask:0xf
	v_add_f32_dpp v79, v77, v77 quad_perm:[2,3,0,1] row_mask:0xf bank_mask:0xf
	v_cndmask_b32_e64 v76, v79, v78, s[4:5]
	s_waitcnt vmcnt(16)
	v_pk_mul_f32 v[140:141], v[236:237], v[64:65] op_sel_hi:[1,0]
	v_pk_mul_f32 v[142:143], v[244:245], v[64:65] op_sel_hi:[1,0]
	v_pk_fma_f32 v[140:141], v[238:239], v[64:65], v[140:141] op_sel:[0,1,0]
	v_pk_fma_f32 v[142:143], v[246:247], v[64:65], v[142:143] op_sel:[0,1,0]
	v_pk_fma_f32 v[140:141], v[240:241], v[66:67], v[140:141] op_sel_hi:[1,0,1]
	v_pk_fma_f32 v[142:143], v[248:249], v[66:67], v[142:143] op_sel_hi:[1,0,1]
	v_pk_fma_f32 v[140:141], v[242:243], v[66:67], v[140:141] op_sel:[0,1,0]
	v_pk_fma_f32 v[142:143], v[250:251], v[66:67], v[142:143] op_sel:[0,1,0]
	v_add_f32_dpp v92, v94, v93 row_ror:8 row_mask:0xf bank_mask:0xf
	v_add_f32_dpp v68, v252, v252 quad_perm:[1,0,3,2] row_mask:0xf bank_mask:0xf
	v_add_f32_dpp v69, v253, v253 quad_perm:[1,0,3,2] row_mask:0xf bank_mask:0xf
	v_add_f32_dpp v70, v254, v254 quad_perm:[1,0,3,2] row_mask:0xf bank_mask:0xf
	v_add_f32_dpp v71, v255, v255 quad_perm:[1,0,3,2] row_mask:0xf bank_mask:0xf
	v_cndmask_b32_e32 v68, v70, v68, vcc
	v_cndmask_b32_e32 v69, v71, v69, vcc
	v_add_f32_dpp v74, v72, v72 quad_perm:[2,3,0,1] row_mask:0xf bank_mask:0xf
	v_add_f32_dpp v75, v73, v73 quad_perm:[2,3,0,1] row_mask:0xf bank_mask:0xf
	v_cndmask_b32_e64 v72, v75, v74, s[4:5]
	v_cndmask_b32_e64 v77, v72, v76, s[6:7]
	v_cndmask_b32_e64 v78, v76, v72, s[6:7]
	s_waitcnt vmcnt(15)
; DI void attn_sample_item(const Params& p, int item, ldsp lds, int tid_) {
;     ...
;   SC_SCORE(kvA, 0)
;   SC_SCORE(kvB, 1)
	v_pk_mul_f32 v[252:253], v[236:237], v[60:61] op_sel_hi:[1,0]
	v_pk_mul_f32 v[254:255], v[244:245], v[60:61] op_sel_hi:[1,0]
	v_pk_fma_f32 v[252:253], v[238:239], v[60:61], v[252:253] op_sel:[0,1,0]
	v_pk_fma_f32 v[254:255], v[246:247], v[60:61], v[254:255] op_sel:[0,1,0]
	v_pk_fma_f32 v[252:253], v[240:241], v[62:63], v[252:253] op_sel_hi:[1,0,1]
	v_pk_fma_f32 v[254:255], v[248:249], v[62:63], v[254:255] op_sel_hi:[1,0,1]
	v_pk_fma_f32 v[252:253], v[242:243], v[62:63], v[252:253] op_sel:[0,1,0]
	v_pk_fma_f32 v[254:255], v[250:251], v[62:63], v[254:255] op_sel:[0,1,0]
	v_add_f32_dpp v76, v78, v77 row_ror:4 row_mask:0xf bank_mask:0xf
	v_add_f32_dpp v64, v140, v140 quad_perm:[1,0,3,2] row_mask:0xf bank_mask:0xf
	v_add_f32_dpp v65, v141, v141 quad_perm:[1,0,3,2] row_mask:0xf bank_mask:0xf
	v_add_f32_dpp v66, v142, v142 quad_perm:[1,0,3,2] row_mask:0xf bank_mask:0xf
	v_add_f32_dpp v67, v143, v143 quad_perm:[1,0,3,2] row_mask:0xf bank_mask:0xf
	v_cndmask_b32_e32 v64, v66, v64, vcc
	v_cndmask_b32_e32 v65, v67, v65, vcc
	v_add_f32_dpp v70, v68, v68 quad_perm:[2,3,0,1] row_mask:0xf bank_mask:0xf
	v_add_f32_dpp v71, v69, v69 quad_perm:[2,3,0,1] row_mask:0xf bank_mask:0xf
	v_cndmask_b32_e64 v68, v71, v70, s[4:5]
	s_waitcnt vmcnt(14)
	v_pk_mul_f32 v[140:141], v[236:237], v[56:57] op_sel_hi:[1,0]
	v_pk_mul_f32 v[142:143], v[244:245], v[56:57] op_sel_hi:[1,0]
	v_pk_fma_f32 v[140:141], v[238:239], v[56:57], v[140:141] op_sel:[0,1,0]
	v_pk_fma_f32 v[142:143], v[246:247], v[56:57], v[142:143] op_sel:[0,1,0]
	v_pk_fma_f32 v[140:141], v[240:241], v[58:59], v[140:141] op_sel_hi:[1,0,1]
	v_pk_fma_f32 v[142:143], v[248:249], v[58:59], v[142:143] op_sel_hi:[1,0,1]
	v_pk_fma_f32 v[140:141], v[242:243], v[58:59], v[140:141] op_sel:[0,1,0]
	v_pk_fma_f32 v[142:143], v[250:251], v[58:59], v[142:143] op_sel:[0,1,0]
	v_add_f32_dpp v60, v252, v252 quad_perm:[1,0,3,2] row_mask:0xf bank_mask:0xf
	v_add_f32_dpp v61, v253, v253 quad_perm:[1,0,3,2] row_mask:0xf bank_mask:0xf
	v_add_f32_dpp v62, v254, v254 quad_perm:[1,0,3,2] row_mask:0xf bank_mask:0xf
	v_add_f32_dpp v63, v255, v255 quad_perm:[1,0,3,2] row_mask:0xf bank_mask:0xf
	v_cndmask_b32_e32 v60, v62, v60, vcc
	v_cndmask_b32_e32 v61, v63, v61, vcc
	v_add_f32_dpp v66, v64, v64 quad_perm:[2,3,0,1] row_mask:0xf bank_mask:0xf
	v_add_f32_dpp v67, v65, v65 quad_perm:[2,3,0,1] row_mask:0xf bank_mask:0xf
	v_cndmask_b32_e64 v64, v67, v66, s[4:5]
	v_cndmask_b32_e64 v69, v64, v68, s[6:7]
	v_cndmask_b32_e64 v70, v68, v64, s[6:7]
	s_waitcnt vmcnt(13)
	v_pk_mul_f32 v[252:253], v[236:237], v[52:53] op_sel_hi:[1,0]
	v_pk_mul_f32 v[254:255], v[244:245], v[52:53] op_sel_hi:[1,0]
	v_pk_fma_f32 v[252:253], v[238:239], v[52:53], v[252:253] op_sel:[0,1,0]
	v_pk_fma_f32 v[254:255], v[246:247], v[52:53], v[254:255] op_sel:[0,1,0]
	v_pk_fma_f32 v[252:253], v[240:241], v[54:55], v[252:253] op_sel_hi:[1,0,1]
	v_pk_fma_f32 v[254:255], v[248:249], v[54:55], v[254:255] op_sel_hi:[1,0,1]
	v_pk_fma_f32 v[252:253], v[242:243], v[54:55], v[252:253] op_sel:[0,1,0]
	v_pk_fma_f32 v[254:255], v[250:251], v[54:55], v[254:255] op_sel:[0,1,0]
	v_add_f32_dpp v68, v70, v69 row_ror:4 row_mask:0xf bank_mask:0xf
	v_cndmask_b32_e64 v77, v68, v76, s[64:65]
	v_cndmask_b32_e64 v78, v76, v68, s[64:65]
	v_add_f32_dpp v56, v140, v140 quad_perm:[1,0,3,2] row_mask:0xf bank_mask:0xf
	v_add_f32_dpp v57, v141, v141 quad_perm:[1,0,3,2] row_mask:0xf bank_mask:0xf
	v_add_f32_dpp v58, v142, v142 quad_perm:[1,0,3,2] row_mask:0xf bank_mask:0xf
	v_add_f32_dpp v59, v143, v143 quad_perm:[1,0,3,2] row_mask:0xf bank_mask:0xf
	v_cndmask_b32_e32 v56, v58, v56, vcc
	v_cndmask_b32_e32 v57, v59, v57, vcc
	v_add_f32_dpp v62, v60, v60 quad_perm:[2,3,0,1] row_mask:0xf bank_mask:0xf
	v_add_f32_dpp v63, v61, v61 quad_perm:[2,3,0,1] row_mask:0xf bank_mask:0xf
	v_cndmask_b32_e64 v60, v63, v62, s[4:5]
	s_waitcnt vmcnt(12)
	v_pk_mul_f32 v[140:141], v[236:237], v[48:49] op_sel_hi:[1,0]
	v_pk_mul_f32 v[142:143], v[244:245], v[48:49] op_sel_hi:[1,0]
	v_pk_fma_f32 v[140:141], v[238:239], v[48:49], v[140:141] op_sel:[0,1,0]
	v_pk_fma_f32 v[142:143], v[246:247], v[48:49], v[142:143] op_sel:[0,1,0]
	v_pk_fma_f32 v[140:141], v[240:241], v[50:51], v[140:141] op_sel_hi:[1,0,1]
	v_pk_fma_f32 v[142:143], v[248:249], v[50:51], v[142:143] op_sel_hi:[1,0,1]
	v_pk_fma_f32 v[140:141], v[242:243], v[50:51], v[140:141] op_sel:[0,1,0]
	v_pk_fma_f32 v[142:143], v[250:251], v[50:51], v[142:143] op_sel:[0,1,0]
	v_add_f32_dpp v76, v78, v77 row_ror:8 row_mask:0xf bank_mask:0xf
	v_add_f32_dpp v52, v252, v252 quad_perm:[1,0,3,2] row_mask:0xf bank_mask:0xf
	v_add_f32_dpp v53, v253, v253 quad_perm:[1,0,3,2] row_mask:0xf bank_mask:0xf
	v_add_f32_dpp v54, v254, v254 quad_perm:[1,0,3,2] row_mask:0xf bank_mask:0xf
	v_add_f32_dpp v55, v255, v255 quad_perm:[1,0,3,2] row_mask:0xf bank_mask:0xf
	v_cndmask_b32_e32 v52, v54, v52, vcc
	v_cndmask_b32_e32 v53, v55, v53, vcc
	v_add_f32_dpp v58, v56, v56 quad_perm:[2,3,0,1] row_mask:0xf bank_mask:0xf
	v_add_f32_dpp v59, v57, v57 quad_perm:[2,3,0,1] row_mask:0xf bank_mask:0xf
	v_cndmask_b32_e64 v56, v59, v58, s[4:5]
	v_cndmask_b32_e64 v61, v56, v60, s[6:7]
	v_cndmask_b32_e64 v62, v60, v56, s[6:7]
	s_waitcnt vmcnt(11)
; DI void attn_sample_item(const Params& p, int item, ldsp lds, int tid_) {
;     ...
;   SC_SCORE(kvA, 0)
;   SC_SCORE(kvB, 1)
	v_pk_mul_f32 v[252:253], v[236:237], v[44:45] op_sel_hi:[1,0]
	v_pk_mul_f32 v[254:255], v[244:245], v[44:45] op_sel_hi:[1,0]
	v_pk_fma_f32 v[252:253], v[238:239], v[44:45], v[252:253] op_sel:[0,1,0]
	v_pk_fma_f32 v[254:255], v[246:247], v[44:45], v[254:255] op_sel:[0,1,0]
	v_pk_fma_f32 v[252:253], v[240:241], v[46:47], v[252:253] op_sel_hi:[1,0,1]
	v_pk_fma_f32 v[254:255], v[248:249], v[46:47], v[254:255] op_sel_hi:[1,0,1]
	v_pk_fma_f32 v[252:253], v[242:243], v[46:47], v[252:253] op_sel:[0,1,0]
	v_pk_fma_f32 v[254:255], v[250:251], v[46:47], v[254:255] op_sel:[0,1,0]
	v_permlane16_swap_b32_e32 v92, v76
	v_add_f32_e32 v92, v92, v76
	v_add_f32_dpp v60, v62, v61 row_ror:4 row_mask:0xf bank_mask:0xf
	v_add_f32_dpp v48, v140, v140 quad_perm:[1,0,3,2] row_mask:0xf bank_mask:0xf
	v_add_f32_dpp v49, v141, v141 quad_perm:[1,0,3,2] row_mask:0xf bank_mask:0xf
	v_add_f32_dpp v50, v142, v142 quad_perm:[1,0,3,2] row_mask:0xf bank_mask:0xf
	v_add_f32_dpp v51, v143, v143 quad_perm:[1,0,3,2] row_mask:0xf bank_mask:0xf
	v_cndmask_b32_e32 v48, v50, v48, vcc
	v_cndmask_b32_e32 v49, v51, v49, vcc
	v_add_f32_dpp v54, v52, v52 quad_perm:[2,3,0,1] row_mask:0xf bank_mask:0xf
	v_add_f32_dpp v55, v53, v53 quad_perm:[2,3,0,1] row_mask:0xf bank_mask:0xf
	v_cndmask_b32_e64 v52, v55, v54, s[4:5]
	s_waitcnt vmcnt(10)
	v_pk_mul_f32 v[140:141], v[236:237], v[40:41] op_sel_hi:[1,0]
	v_pk_mul_f32 v[142:143], v[244:245], v[40:41] op_sel_hi:[1,0]
	v_pk_fma_f32 v[140:141], v[238:239], v[40:41], v[140:141] op_sel:[0,1,0]
	v_pk_fma_f32 v[142:143], v[246:247], v[40:41], v[142:143] op_sel:[0,1,0]
	v_pk_fma_f32 v[140:141], v[240:241], v[42:43], v[140:141] op_sel_hi:[1,0,1]
	v_pk_fma_f32 v[142:143], v[248:249], v[42:43], v[142:143] op_sel_hi:[1,0,1]
	v_pk_fma_f32 v[140:141], v[242:243], v[42:43], v[140:141] op_sel:[0,1,0]
	v_pk_fma_f32 v[142:143], v[250:251], v[42:43], v[142:143] op_sel:[0,1,0]
	v_permlane32_swap_b32_e32 v124, v92
	v_add_f32_e32 v124, v124, v92
	ds_write_b32 v235, v124
	v_add_f32_dpp v44, v252, v252 quad_perm:[1,0,3,2] row_mask:0xf bank_mask:0xf
	v_add_f32_dpp v45, v253, v253 quad_perm:[1,0,3,2] row_mask:0xf bank_mask:0xf
	v_add_f32_dpp v46, v254, v254 quad_perm:[1,0,3,2] row_mask:0xf bank_mask:0xf
	v_add_f32_dpp v47, v255, v255 quad_perm:[1,0,3,2] row_mask:0xf bank_mask:0xf
	v_cndmask_b32_e32 v44, v46, v44, vcc
	v_cndmask_b32_e32 v45, v47, v45, vcc
	v_add_f32_dpp v50, v48, v48 quad_perm:[2,3,0,1] row_mask:0xf bank_mask:0xf
	v_add_f32_dpp v51, v49, v49 quad_perm:[2,3,0,1] row_mask:0xf bank_mask:0xf
	v_cndmask_b32_e64 v48, v51, v50, s[4:5]
	v_cndmask_b32_e64 v53, v48, v52, s[6:7]
	v_cndmask_b32_e64 v54, v52, v48, s[6:7]
	s_waitcnt vmcnt(9)
	v_pk_mul_f32 v[252:253], v[236:237], v[36:37] op_sel_hi:[1,0]
	v_pk_mul_f32 v[254:255], v[244:245], v[36:37] op_sel_hi:[1,0]
	v_pk_fma_f32 v[252:253], v[238:239], v[36:37], v[252:253] op_sel:[0,1,0]
	v_pk_fma_f32 v[254:255], v[246:247], v[36:37], v[254:255] op_sel:[0,1,0]
	v_pk_fma_f32 v[252:253], v[240:241], v[38:39], v[252:253] op_sel_hi:[1,0,1]
	v_pk_fma_f32 v[254:255], v[248:249], v[38:39], v[254:255] op_sel_hi:[1,0,1]
	v_pk_fma_f32 v[252:253], v[242:243], v[38:39], v[252:253] op_sel:[0,1,0]
	v_pk_fma_f32 v[254:255], v[250:251], v[38:39], v[254:255] op_sel:[0,1,0]
	v_add_f32_dpp v52, v54, v53 row_ror:4 row_mask:0xf bank_mask:0xf
	v_cndmask_b32_e64 v61, v52, v60, s[64:65]
	v_cndmask_b32_e64 v62, v60, v52, s[64:65]
	v_add_f32_dpp v40, v140, v140 quad_perm:[1,0,3,2] row_mask:0xf bank_mask:0xf
	v_add_f32_dpp v41, v141, v141 quad_perm:[1,0,3,2] row_mask:0xf bank_mask:0xf
	v_add_f32_dpp v42, v142, v142 quad_perm:[1,0,3,2] row_mask:0xf bank_mask:0xf
	v_add_f32_dpp v43, v143, v143 quad_perm:[1,0,3,2] row_mask:0xf bank_mask:0xf
	v_cndmask_b32_e32 v40, v42, v40, vcc
	v_cndmask_b32_e32 v41, v43, v41, vcc
	v_add_f32_dpp v46, v44, v44 quad_perm:[2,3,0,1] row_mask:0xf bank_mask:0xf
	v_add_f32_dpp v47, v45, v45 quad_perm:[2,3,0,1] row_mask:0xf bank_mask:0xf
	v_cndmask_b32_e64 v44, v47, v46, s[4:5]
	s_waitcnt vmcnt(8)
	v_pk_mul_f32 v[140:141], v[236:237], v[32:33] op_sel_hi:[1,0]
	v_pk_mul_f32 v[142:143], v[244:245], v[32:33] op_sel_hi:[1,0]
	v_pk_fma_f32 v[140:141], v[238:239], v[32:33], v[140:141] op_sel:[0,1,0]
	v_pk_fma_f32 v[142:143], v[246:247], v[32:33], v[142:143] op_sel:[0,1,0]
	v_pk_fma_f32 v[140:141], v[240:241], v[34:35], v[140:141] op_sel_hi:[1,0,1]
	v_pk_fma_f32 v[142:143], v[248:249], v[34:35], v[142:143] op_sel_hi:[1,0,1]
	v_pk_fma_f32 v[140:141], v[242:243], v[34:35], v[140:141] op_sel:[0,1,0]
	v_pk_fma_f32 v[142:143], v[250:251], v[34:35], v[142:143] op_sel:[0,1,0]
	v_add_f32_dpp v60, v62, v61 row_ror:8 row_mask:0xf bank_mask:0xf
	v_add_f32_dpp v36, v252, v252 quad_perm:[1,0,3,2] row_mask:0xf bank_mask:0xf
	v_add_f32_dpp v37, v253, v253 quad_perm:[1,0,3,2] row_mask:0xf bank_mask:0xf
	v_add_f32_dpp v38, v254, v254 quad_perm:[1,0,3,2] row_mask:0xf bank_mask:0xf
	v_add_f32_dpp v39, v255, v255 quad_perm:[1,0,3,2] row_mask:0xf bank_mask:0xf
	v_cndmask_b32_e32 v36, v38, v36, vcc
	v_cndmask_b32_e32 v37, v39, v37, vcc
	v_add_f32_dpp v42, v40, v40 quad_perm:[2,3,0,1] row_mask:0xf bank_mask:0xf
	v_add_f32_dpp v43, v41, v41 quad_perm:[2,3,0,1] row_mask:0xf bank_mask:0xf
	v_cndmask_b32_e64 v40, v43, v42, s[4:5]
	v_cndmask_b32_e64 v45, v40, v44, s[6:7]
	v_cndmask_b32_e64 v46, v44, v40, s[6:7]
	s_waitcnt vmcnt(7)
; DI void attn_sample_item(const Params& p, int item, ldsp lds, int tid_) {
;     ...
;   SC_SCORE(kvA, 0)
;   SC_SCORE(kvB, 1)
	v_pk_mul_f32 v[252:253], v[236:237], v[28:29] op_sel_hi:[1,0]
	v_pk_mul_f32 v[254:255], v[244:245], v[28:29] op_sel_hi:[1,0]
	v_pk_fma_f32 v[252:253], v[238:239], v[28:29], v[252:253] op_sel:[0,1,0]
	v_pk_fma_f32 v[254:255], v[246:247], v[28:29], v[254:255] op_sel:[0,1,0]
	v_pk_fma_f32 v[252:253], v[240:241], v[30:31], v[252:253] op_sel_hi:[1,0,1]
	v_pk_fma_f32 v[254:255], v[248:249], v[30:31], v[254:255] op_sel_hi:[1,0,1]
	v_pk_fma_f32 v[252:253], v[242:243], v[30:31], v[252:253] op_sel:[0,1,0]
	v_pk_fma_f32 v[254:255], v[250:251], v[30:31], v[254:255] op_sel:[0,1,0]
	v_add_f32_dpp v44, v46, v45 row_ror:4 row_mask:0xf bank_mask:0xf
	v_add_f32_dpp v32, v140, v140 quad_perm:[1,0,3,2] row_mask:0xf bank_mask:0xf
	v_add_f32_dpp v33, v141, v141 quad_perm:[1,0,3,2] row_mask:0xf bank_mask:0xf
	v_add_f32_dpp v34, v142, v142 quad_perm:[1,0,3,2] row_mask:0xf bank_mask:0xf
	v_add_f32_dpp v35, v143, v143 quad_perm:[1,0,3,2] row_mask:0xf bank_mask:0xf
	v_cndmask_b32_e32 v32, v34, v32, vcc
	v_cndmask_b32_e32 v33, v35, v33, vcc
	v_add_f32_dpp v38, v36, v36 quad_perm:[2,3,0,1] row_mask:0xf bank_mask:0xf
	v_add_f32_dpp v39, v37, v37 quad_perm:[2,3,0,1] row_mask:0xf bank_mask:0xf
	v_cndmask_b32_e64 v36, v39, v38, s[4:5]
	s_waitcnt vmcnt(6)
	v_pk_mul_f32 v[140:141], v[236:237], v[24:25] op_sel_hi:[1,0]
	v_pk_mul_f32 v[142:143], v[244:245], v[24:25] op_sel_hi:[1,0]
	v_pk_fma_f32 v[140:141], v[238:239], v[24:25], v[140:141] op_sel:[0,1,0]
	v_pk_fma_f32 v[142:143], v[246:247], v[24:25], v[142:143] op_sel:[0,1,0]
	v_pk_fma_f32 v[140:141], v[240:241], v[26:27], v[140:141] op_sel_hi:[1,0,1]
	v_pk_fma_f32 v[142:143], v[248:249], v[26:27], v[142:143] op_sel_hi:[1,0,1]
	v_pk_fma_f32 v[140:141], v[242:243], v[26:27], v[140:141] op_sel:[0,1,0]
	v_pk_fma_f32 v[142:143], v[250:251], v[26:27], v[142:143] op_sel:[0,1,0]
	v_add_f32_dpp v28, v252, v252 quad_perm:[1,0,3,2] row_mask:0xf bank_mask:0xf
	v_add_f32_dpp v29, v253, v253 quad_perm:[1,0,3,2] row_mask:0xf bank_mask:0xf
	v_add_f32_dpp v30, v254, v254 quad_perm:[1,0,3,2] row_mask:0xf bank_mask:0xf
	v_add_f32_dpp v31, v255, v255 quad_perm:[1,0,3,2] row_mask:0xf bank_mask:0xf
	v_cndmask_b32_e32 v28, v30, v28, vcc
	v_cndmask_b32_e32 v29, v31, v29, vcc
	v_add_f32_dpp v34, v32, v32 quad_perm:[2,3,0,1] row_mask:0xf bank_mask:0xf
	v_add_f32_dpp v35, v33, v33 quad_perm:[2,3,0,1] row_mask:0xf bank_mask:0xf
	v_cndmask_b32_e64 v32, v35, v34, s[4:5]
	v_cndmask_b32_e64 v37, v32, v36, s[6:7]
	v_cndmask_b32_e64 v38, v36, v32, s[6:7]
	s_waitcnt vmcnt(5)
	v_pk_mul_f32 v[252:253], v[236:237], v[20:21] op_sel_hi:[1,0]
	v_pk_mul_f32 v[254:255], v[244:245], v[20:21] op_sel_hi:[1,0]
	v_pk_fma_f32 v[252:253], v[238:239], v[20:21], v[252:253] op_sel:[0,1,0]
	v_pk_fma_f32 v[254:255], v[246:247], v[20:21], v[254:255] op_sel:[0,1,0]
	v_pk_fma_f32 v[252:253], v[240:241], v[22:23], v[252:253] op_sel_hi:[1,0,1]
	v_pk_fma_f32 v[254:255], v[248:249], v[22:23], v[254:255] op_sel_hi:[1,0,1]
	v_pk_fma_f32 v[252:253], v[242:243], v[22:23], v[252:253] op_sel:[0,1,0]
	v_pk_fma_f32 v[254:255], v[250:251], v[22:23], v[254:255] op_sel:[0,1,0]
	v_add_f32_dpp v36, v38, v37 row_ror:4 row_mask:0xf bank_mask:0xf
	v_cndmask_b32_e64 v45, v36, v44, s[64:65]
	v_cndmask_b32_e64 v46, v44, v36, s[64:65]
	v_add_f32_dpp v24, v140, v140 quad_perm:[1,0,3,2] row_mask:0xf bank_mask:0xf
	v_add_f32_dpp v25, v141, v141 quad_perm:[1,0,3,2] row_mask:0xf bank_mask:0xf
	v_add_f32_dpp v26, v142, v142 quad_perm:[1,0,3,2] row_mask:0xf bank_mask:0xf
	v_add_f32_dpp v27, v143, v143 quad_perm:[1,0,3,2] row_mask:0xf bank_mask:0xf
	v_cndmask_b32_e32 v24, v26, v24, vcc
	v_cndmask_b32_e32 v25, v27, v25, vcc
	v_add_f32_dpp v30, v28, v28 quad_perm:[2,3,0,1] row_mask:0xf bank_mask:0xf
	v_add_f32_dpp v31, v29, v29 quad_perm:[2,3,0,1] row_mask:0xf bank_mask:0xf
	v_cndmask_b32_e64 v28, v31, v30, s[4:5]
	s_waitcnt vmcnt(4)
	v_pk_mul_f32 v[140:141], v[236:237], v[16:17] op_sel_hi:[1,0]
	v_pk_mul_f32 v[142:143], v[244:245], v[16:17] op_sel_hi:[1,0]
	v_pk_fma_f32 v[140:141], v[238:239], v[16:17], v[140:141] op_sel:[0,1,0]
	v_pk_fma_f32 v[142:143], v[246:247], v[16:17], v[142:143] op_sel:[0,1,0]
	v_pk_fma_f32 v[140:141], v[240:241], v[18:19], v[140:141] op_sel_hi:[1,0,1]
	v_pk_fma_f32 v[142:143], v[248:249], v[18:19], v[142:143] op_sel_hi:[1,0,1]
	v_pk_fma_f32 v[140:141], v[242:243], v[18:19], v[140:141] op_sel:[0,1,0]
	v_pk_fma_f32 v[142:143], v[250:251], v[18:19], v[142:143] op_sel:[0,1,0]
	v_add_f32_dpp v44, v46, v45 row_ror:8 row_mask:0xf bank_mask:0xf
	v_add_f32_dpp v20, v252, v252 quad_perm:[1,0,3,2] row_mask:0xf bank_mask:0xf
	v_add_f32_dpp v21, v253, v253 quad_perm:[1,0,3,2] row_mask:0xf bank_mask:0xf
	v_add_f32_dpp v22, v254, v254 quad_perm:[1,0,3,2] row_mask:0xf bank_mask:0xf
	v_add_f32_dpp v23, v255, v255 quad_perm:[1,0,3,2] row_mask:0xf bank_mask:0xf
	v_cndmask_b32_e32 v20, v22, v20, vcc
	v_cndmask_b32_e32 v21, v23, v21, vcc
	v_add_f32_dpp v26, v24, v24 quad_perm:[2,3,0,1] row_mask:0xf bank_mask:0xf
	v_add_f32_dpp v27, v25, v25 quad_perm:[2,3,0,1] row_mask:0xf bank_mask:0xf
	v_cndmask_b32_e64 v24, v27, v26, s[4:5]
	v_cndmask_b32_e64 v29, v24, v28, s[6:7]
	v_cndmask_b32_e64 v30, v28, v24, s[6:7]
	s_waitcnt vmcnt(3)
; DI void attn_sample_item(const Params& p, int item, ldsp lds, int tid_) {
;     ...
;   SC_SCORE(kvA, 0)
;   SC_SCORE(kvB, 1)
;     ...
;   f32x4 vvA[16], vvB[16];
; #pragma unroll
;   for (int j = 0; j < 16; ++j) vvA[j] = __builtin_nontemporal_load((const f32x4*)(cv + (size_t)(wid * 32 + j) * 1024 + lane * 4));
	v_pk_mul_f32 v[252:253], v[236:237], v[12:13] op_sel_hi:[1,0]
	v_pk_mul_f32 v[254:255], v[244:245], v[12:13] op_sel_hi:[1,0]
	v_pk_fma_f32 v[252:253], v[238:239], v[12:13], v[252:253] op_sel:[0,1,0]
	v_pk_fma_f32 v[254:255], v[246:247], v[12:13], v[254:255] op_sel:[0,1,0]
	v_pk_fma_f32 v[252:253], v[240:241], v[14:15], v[252:253] op_sel_hi:[1,0,1]
	v_pk_fma_f32 v[254:255], v[248:249], v[14:15], v[254:255] op_sel_hi:[1,0,1]
	v_pk_fma_f32 v[252:253], v[242:243], v[14:15], v[252:253] op_sel:[0,1,0]
	v_pk_fma_f32 v[254:255], v[250:251], v[14:15], v[254:255] op_sel:[0,1,0]
	v_permlane16_swap_b32_e32 v60, v44
	v_add_f32_e32 v60, v60, v44
	v_add_f32_dpp v28, v30, v29 row_ror:4 row_mask:0xf bank_mask:0xf
	v_add_f32_dpp v16, v140, v140 quad_perm:[1,0,3,2] row_mask:0xf bank_mask:0xf
	v_add_f32_dpp v17, v141, v141 quad_perm:[1,0,3,2] row_mask:0xf bank_mask:0xf
	v_add_f32_dpp v18, v142, v142 quad_perm:[1,0,3,2] row_mask:0xf bank_mask:0xf
	v_add_f32_dpp v19, v143, v143 quad_perm:[1,0,3,2] row_mask:0xf bank_mask:0xf
	v_cndmask_b32_e32 v16, v18, v16, vcc
	v_cndmask_b32_e32 v17, v19, v17, vcc
	v_add_f32_dpp v22, v20, v20 quad_perm:[2,3,0,1] row_mask:0xf bank_mask:0xf
	v_add_f32_dpp v23, v21, v21 quad_perm:[2,3,0,1] row_mask:0xf bank_mask:0xf
	v_cndmask_b32_e64 v20, v23, v22, s[4:5]
	s_waitcnt vmcnt(2)
	v_pk_mul_f32 v[140:141], v[236:237], v[8:9] op_sel_hi:[1,0]
	v_pk_mul_f32 v[142:143], v[244:245], v[8:9] op_sel_hi:[1,0]
	v_pk_fma_f32 v[140:141], v[238:239], v[8:9], v[140:141] op_sel:[0,1,0]
	v_pk_fma_f32 v[142:143], v[246:247], v[8:9], v[142:143] op_sel:[0,1,0]
	v_pk_fma_f32 v[140:141], v[240:241], v[10:11], v[140:141] op_sel_hi:[1,0,1]
	v_pk_fma_f32 v[142:143], v[248:249], v[10:11], v[142:143] op_sel_hi:[1,0,1]
	v_pk_fma_f32 v[140:141], v[242:243], v[10:11], v[140:141] op_sel:[0,1,0]
	v_pk_fma_f32 v[142:143], v[250:251], v[10:11], v[142:143] op_sel:[0,1,0]
	v_add_f32_dpp v12, v252, v252 quad_perm:[1,0,3,2] row_mask:0xf bank_mask:0xf
	v_add_f32_dpp v13, v253, v253 quad_perm:[1,0,3,2] row_mask:0xf bank_mask:0xf
	v_add_f32_dpp v14, v254, v254 quad_perm:[1,0,3,2] row_mask:0xf bank_mask:0xf
	v_add_f32_dpp v15, v255, v255 quad_perm:[1,0,3,2] row_mask:0xf bank_mask:0xf
	v_cndmask_b32_e32 v12, v14, v12, vcc
	v_cndmask_b32_e32 v13, v15, v13, vcc
	v_add_f32_dpp v18, v16, v16 quad_perm:[2,3,0,1] row_mask:0xf bank_mask:0xf
	v_add_f32_dpp v19, v17, v17 quad_perm:[2,3,0,1] row_mask:0xf bank_mask:0xf
	v_cndmask_b32_e64 v16, v19, v18, s[4:5]
	v_cndmask_b32_e64 v21, v16, v20, s[6:7]
	v_cndmask_b32_e64 v22, v20, v16, s[6:7]
	s_waitcnt vmcnt(1)
	v_pk_mul_f32 v[252:253], v[236:237], v[4:5] op_sel_hi:[1,0]
	v_pk_mul_f32 v[254:255], v[244:245], v[4:5] op_sel_hi:[1,0]
	v_pk_fma_f32 v[252:253], v[238:239], v[4:5], v[252:253] op_sel:[0,1,0]
	v_pk_fma_f32 v[254:255], v[246:247], v[4:5], v[254:255] op_sel:[0,1,0]
	v_pk_fma_f32 v[252:253], v[240:241], v[6:7], v[252:253] op_sel_hi:[1,0,1]
	v_pk_fma_f32 v[254:255], v[248:249], v[6:7], v[254:255] op_sel_hi:[1,0,1]
	v_pk_fma_f32 v[252:253], v[242:243], v[6:7], v[252:253] op_sel:[0,1,0]
	v_pk_fma_f32 v[254:255], v[250:251], v[6:7], v[254:255] op_sel:[0,1,0]
	v_add_f32_dpp v20, v22, v21 row_ror:4 row_mask:0xf bank_mask:0xf
	v_cndmask_b32_e64 v29, v20, v28, s[64:65]
	v_cndmask_b32_e64 v30, v28, v20, s[64:65]
	v_add_f32_dpp v8, v140, v140 quad_perm:[1,0,3,2] row_mask:0xf bank_mask:0xf
	v_add_f32_dpp v9, v141, v141 quad_perm:[1,0,3,2] row_mask:0xf bank_mask:0xf
	v_add_f32_dpp v10, v142, v142 quad_perm:[1,0,3,2] row_mask:0xf bank_mask:0xf
	v_add_f32_dpp v11, v143, v143 quad_perm:[1,0,3,2] row_mask:0xf bank_mask:0xf
	v_cndmask_b32_e32 v8, v10, v8, vcc
	v_cndmask_b32_e32 v9, v11, v9, vcc
	v_add_f32_dpp v14, v12, v12 quad_perm:[2,3,0,1] row_mask:0xf bank_mask:0xf
	v_add_f32_dpp v15, v13, v13 quad_perm:[2,3,0,1] row_mask:0xf bank_mask:0xf
	v_cndmask_b32_e64 v12, v15, v14, s[4:5]
	s_waitcnt vmcnt(0)
	v_pk_mul_f32 v[140:141], v[236:237], v[0:1] op_sel_hi:[1,0]
	v_pk_mul_f32 v[142:143], v[244:245], v[0:1] op_sel_hi:[1,0]
	v_pk_fma_f32 v[140:141], v[238:239], v[0:1], v[140:141] op_sel:[0,1,0]
	v_pk_fma_f32 v[142:143], v[246:247], v[0:1], v[142:143] op_sel:[0,1,0]
	v_pk_fma_f32 v[140:141], v[240:241], v[2:3], v[140:141] op_sel_hi:[1,0,1]
	v_pk_fma_f32 v[142:143], v[248:249], v[2:3], v[142:143] op_sel_hi:[1,0,1]
	v_pk_fma_f32 v[140:141], v[242:243], v[2:3], v[140:141] op_sel:[0,1,0]
	v_pk_fma_f32 v[142:143], v[250:251], v[2:3], v[142:143] op_sel:[0,1,0]
	v_add_f32_dpp v28, v30, v29 row_ror:8 row_mask:0xf bank_mask:0xf
	v_add_f32_dpp v4, v252, v252 quad_perm:[1,0,3,2] row_mask:0xf bank_mask:0xf
	v_add_f32_dpp v5, v253, v253 quad_perm:[1,0,3,2] row_mask:0xf bank_mask:0xf
	v_add_f32_dpp v6, v254, v254 quad_perm:[1,0,3,2] row_mask:0xf bank_mask:0xf
	v_add_f32_dpp v7, v255, v255 quad_perm:[1,0,3,2] row_mask:0xf bank_mask:0xf
	v_cndmask_b32_e32 v4, v6, v4, vcc
	v_cndmask_b32_e32 v5, v7, v5, vcc
	v_add_f32_dpp v10, v8, v8 quad_perm:[2,3,0,1] row_mask:0xf bank_mask:0xf
	v_add_f32_dpp v11, v9, v9 quad_perm:[2,3,0,1] row_mask:0xf bank_mask:0xf
	v_cndmask_b32_e64 v8, v11, v10, s[4:5]
	v_cndmask_b32_e64 v13, v8, v12, s[6:7]
	v_cndmask_b32_e64 v14, v12, v8, s[6:7]
	s_nop 1
	v_add_f32_dpp v12, v14, v13 row_ror:4 row_mask:0xf bank_mask:0xf
	v_add_f32_dpp v0, v140, v140 quad_perm:[1,0,3,2] row_mask:0xf bank_mask:0xf
	v_add_f32_dpp v1, v141, v141 quad_perm:[1,0,3,2] row_mask:0xf bank_mask:0xf
	v_add_f32_dpp v2, v142, v142 quad_perm:[1,0,3,2] row_mask:0xf bank_mask:0xf
	v_add_f32_dpp v3, v143, v143 quad_perm:[1,0,3,2] row_mask:0xf bank_mask:0xf
	v_cndmask_b32_e32 v0, v2, v0, vcc
	v_cndmask_b32_e32 v1, v3, v1, vcc
	v_add_f32_dpp v6, v4, v4 quad_perm:[2,3,0,1] row_mask:0xf bank_mask:0xf
	v_add_f32_dpp v7, v5, v5 quad_perm:[2,3,0,1] row_mask:0xf bank_mask:0xf
	v_cndmask_b32_e64 v4, v7, v6, s[4:5]
	v_add_f32_dpp v2, v0, v0 quad_perm:[2,3,0,1] row_mask:0xf bank_mask:0xf
	v_add_f32_dpp v3, v1, v1 quad_perm:[2,3,0,1] row_mask:0xf bank_mask:0xf
	v_cndmask_b32_e64 v0, v3, v2, s[4:5]
	v_cndmask_b32_e64 v5, v0, v4, s[6:7]
	v_cndmask_b32_e64 v6, v4, v0, s[6:7]
	s_nop 1
	v_add_f32_dpp v4, v6, v5 row_ror:4 row_mask:0xf bank_mask:0xf
	v_cndmask_b32_e64 v13, v4, v12, s[64:65]
	v_cndmask_b32_e64 v14, v12, v4, s[64:65]
	s_nop 1
	v_add_f32_dpp v12, v14, v13 row_ror:8 row_mask:0xf bank_mask:0xf
	s_nop 1
	v_permlane16_swap_b32_e32 v28, v12
	v_add_f32_e32 v28, v28, v12
	s_nop 1
	v_permlane32_swap_b32_e32 v60, v28
	v_add_f32_e32 v60, v60, v28
	ds_write_b32 v235, v60 offset:64
	v_lshlrev_b32_e32 v2, 2, v223
	s_add_u32 s4, s14, s28
	s_addc_u32 s5, s15, s29
	v_lshlrev_b32_e32 v0, 2, v2
	s_waitcnt lgkmcnt(0)
; DI void lbar() { asm volatile("s_waitcnt lgkmcnt(0)" ::: "memory"); __builtin_amdgcn_s_barrier(); asm volatile("" ::: "memory"); }
; DI float wave_sum(float v) { for (int o = 32; o >= 1; o >>= 1) v += __shfl_xor(v, o); return v; }
; DI void attn_sample_item(const Params& p, int item, ldsp lds, int tid_) {
;     ...
;   for (int j = 0; j < 16; ++j) vvA[j] = __builtin_nontemporal_load((const f32x4*)(cv + (size_t)(wid * 32 + j) * 1024 + lane * 4));
;   lbar();
;   if (wid < 4) {
;     float v[4]; float mx = -1e30f;
; #pragma unroll
;     for (int j = 0; j < 4; ++j) { v[j] = SC[wid * 256 + j * 64 + lane]; mx = fmaxf(mx, v[j]); }
;     for (int o = 32; o >= 1; o >>= 1) mx = fmaxf(mx, __shfl_xor(mx, o));
;     float s = 0.f;
; #pragma unroll
;     for (int j = 0; j < 4; ++j) { v[j] = __expf(v[j] - mx); s += v[j]; }
;     s = wave_sum(s); const float inv = 1.f / s;
; #pragma unroll
;     for (int j = 0; j < 4; ++j) SC[wid * 256 + j * 64 + lane] = v[j] * inv;
;   }
	v_mov_b32_e32 v1, v145
	v_lshl_add_u64 v[0:1], s[4:5], 0, v[0:1]
	v_lshl_add_u64 v[4:5], v[0:1], 0, v[158:159]
	v_lshl_add_u64 v[6:7], v[0:1], 0, v[162:163]
	global_load_dwordx4 v[100:103], v[4:5], off nt
	global_load_dwordx4 v[92:95], v[6:7], off nt
	v_lshl_add_u64 v[4:5], v[0:1], 0, v[164:165]
	v_lshl_add_u64 v[6:7], v[0:1], 0, v[168:169]
	global_load_dwordx4 v[112:115], v[4:5], off nt
	global_load_dwordx4 v[108:111], v[6:7], off nt
	v_lshl_add_u64 v[4:5], v[0:1], 0, v[172:173]
	v_lshl_add_u64 v[6:7], v[0:1], 0, v[176:177]
	global_load_dwordx4 v[120:123], v[4:5], off nt
	global_load_dwordx4 v[116:119], v[6:7], off nt
	v_lshl_add_u64 v[4:5], v[0:1], 0, v[180:181]
	v_lshl_add_u64 v[6:7], v[0:1], 0, v[184:185]
	global_load_dwordx4 v[124:127], v[4:5], off nt
	global_load_dwordx4 v[104:107], v[6:7], off nt
	v_lshl_add_u64 v[4:5], v[0:1], 0, v[188:189]
	v_lshl_add_u64 v[6:7], v[0:1], 0, v[192:193]
	global_load_dwordx4 v[68:71], v[4:5], off nt
	global_load_dwordx4 v[64:67], v[6:7], off nt
	v_lshl_add_u64 v[4:5], v[0:1], 0, v[196:197]
	v_lshl_add_u64 v[6:7], v[0:1], 0, v[200:201]
	global_load_dwordx4 v[80:83], v[4:5], off nt
	global_load_dwordx4 v[76:79], v[6:7], off nt
	v_lshl_add_u64 v[4:5], v[0:1], 0, v[202:203]
	v_lshl_add_u64 v[6:7], v[0:1], 0, v[204:205]
	global_load_dwordx4 v[88:91], v[4:5], off nt
	global_load_dwordx4 v[84:87], v[6:7], off nt
	v_lshl_add_u64 v[4:5], v[0:1], 0, v[206:207]
	v_lshl_add_u64 v[6:7], v[0:1], 0, v[208:209]
	global_load_dwordx4 v[96:99], v[4:5], off nt
	global_load_dwordx4 v[72:75], v[6:7], off nt
	s_waitcnt lgkmcnt(0)
	s_barrier
	v_cmp_gt_i32_e32 vcc, 4, v210
	s_and_saveexec_b64 s[4:5], vcc
	s_cbranch_execz .LBB0_1675
	v_lshlrev_b32_e32 v3, 10, v210
	v_add3_u32 v6, 16, v3, v2
	ds_read2st64_b32 v[2:3], v6 offset1:1
	ds_read2st64_b32 v[4:5], v6 offset0:2 offset1:3
	s_waitcnt lgkmcnt(1)
	v_max3_f32 v7, v2, s35, v3
	s_waitcnt lgkmcnt(0)
	v_max3_f32 v7, v7, v4, v5
	s_nop 1
	v_max_f32_dpp v7, v7, v7 quad_perm:[1,0,3,2] row_mask:0xf bank_mask:0xf
	s_nop 1
	v_max_f32_dpp v7, v7, v7 quad_perm:[2,3,0,1] row_mask:0xf bank_mask:0xf
	s_nop 1
	v_max_f32_dpp v7, v7, v7 row_ror:4 row_mask:0xf bank_mask:0xf
	s_nop 1
	v_max_f32_dpp v7, v7, v7 row_ror:8 row_mask:0xf bank_mask:0xf
	v_mov_b32_e32 v8, v7
	s_nop 1
	v_permlane16_swap_b32_e32 v7, v8
	v_max_f32_e32 v7, v7, v8
	v_mov_b32_e32 v8, v7
	s_nop 1
	v_permlane32_swap_b32_e32 v7, v8
	v_max_f32_e32 v7, v7, v8
	v_sub_f32_e32 v2, v2, v7
	v_sub_f32_e32 v3, v3, v7
	v_mul_f32_e32 v2, 0x3fb8aa3b, v2
	v_sub_f32_e32 v4, v4, v7
	v_mul_f32_e32 v3, 0x3fb8aa3b, v3
	v_exp_f32_e32 v2, v2
	v_sub_f32_e32 v5, v5, v7
	v_mul_f32_e32 v4, 0x3fb8aa3b, v4
	v_exp_f32_e32 v3, v3
	v_mul_f32_e32 v5, 0x3fb8aa3b, v5
	v_exp_f32_e32 v4, v4
	v_exp_f32_e32 v5, v5
	v_add_f32_e32 v7, 0, v2
	v_add_f32_e32 v7, v3, v7
	v_add_f32_e32 v7, v4, v7
	v_add_f32_e32 v7, v5, v7
	s_nop 1
	v_add_f32_dpp v7, v7, v7 quad_perm:[1,0,3,2] row_mask:0xf bank_mask:0xf
	s_nop 1
	v_add_f32_dpp v7, v7, v7 quad_perm:[2,3,0,1] row_mask:0xf bank_mask:0xf
	s_nop 1
	v_add_f32_dpp v7, v7, v7 row_ror:4 row_mask:0xf bank_mask:0xf
	s_nop 1
	v_add_f32_dpp v7, v7, v7 row_ror:8 row_mask:0xf bank_mask:0xf
	v_mov_b32_e32 v8, v7
	s_nop 1
	v_permlane16_swap_b32_e32 v7, v8
	v_add_f32_e32 v7, v7, v8
	v_mov_b32_e32 v8, v7
	s_nop 1
	v_permlane32_swap_b32_e32 v7, v8
	v_add_f32_e32 v7, v7, v8
	v_div_scale_f32 v8, s[6:7], v7, v7, 1.0
	v_rcp_f32_e32 v9, v8
	v_div_scale_f32 v10, vcc, 1.0, v7, 1.0
	v_fma_f32 v11, -v8, v9, 1.0
	v_fmac_f32_e32 v9, v11, v9
	v_mul_f32_e32 v11, v10, v9
	v_fma_f32 v12, -v8, v11, v10
	v_fmac_f32_e32 v11, v12, v9
	v_fma_f32 v8, -v8, v11, v10
	v_div_fmas_f32 v8, v8, v9, v11
	v_div_fixup_f32 v7, v8, v7, 1.0
	v_mul_f32_e32 v2, v2, v7
	v_mul_f32_e32 v3, v3, v7
	v_mul_f32_e32 v4, v4, v7
	v_mul_f32_e32 v5, v5, v7
	ds_write2st64_b32 v6, v2, v3 offset1:1
	ds_write2st64_b32 v6, v4, v5 offset0:2 offset1:3
	s_branch .LBB0_1675
